# out/down GEMM Y stores cached (plain) instead of nt: the norm phase that follows reads Y from cache
# baseline (speedup 1.0000x reference)
; __device__ __forceinline__ u32x4 pack8(f32x4 a, f32x4 b) { u32x4 w; w.x = cvtpk(a[0], a[1]); w.y = cvtpk(a[2], a[3]); w.z = cvtpk(b[0], b[1]); w.w = cvtpk(b[2], b[3]); return w; }
; __device__ __forceinline__ unsigned dpp_ror8(unsigned v) { return (unsigned)__builtin_amdgcn_update_dpp(0, (int)v, 0x128, 0xF, 0xF, false); }
; __device__ __forceinline__ void store_pair(bf16_t* grp  , size_t ld, int fr, int fq, u32x4 P0, u32x4 P1) {
;     const bool up = (fr & 8) != 0;
;     u32x4 snd, rcv;
;     snd.x = up ? P0.x : P1.x; snd.y = up ? P0.y : P1.y; snd.z = up ? P0.z : P1.z; snd.w = up ? P0.w : P1.w;
;     rcv.x = dpp_ror8(snd.x); rcv.y = dpp_ror8(snd.y); rcv.z = dpp_ror8(snd.z); rcv.w = dpp_ror8(snd.w);
;     u32x4 dA, dB;
;     dA.x = up ? rcv.x : P0.x; dA.y = up ? rcv.y : P0.y; dA.z = up ? rcv.z : P0.z; dA.w = up ? rcv.w : P0.w;
;     dB.x = up ? P1.x : rcv.x; dB.y = up ? P1.y : rcv.y; dB.z = up ? P1.z : rcv.z; dB.w = up ? P1.w : rcv.w;
;     bf16_t* p = grp + (size_t)(fr & 7) * ld + (up ? CBJ : 0) + 8 * fq;
;     __builtin_nontemporal_store(dA, (u32x4*)p); __builtin_nontemporal_store(dB, (u32x4*)(p + 8 * ld));
;     __device__ __forceinline__ void operator()(f32x4 (&acc)[2][2][4][2], const Unit& u, int wr, int wc, int fr, int fq) const {
;     ...
; #pragma unroll
;         for (int ai = 0; ai < 2; ++ai)
; #pragma unroll
;             for (int m = 0; m < 4; ++m) {
;                 const int row = row0 + ai * HALF + m * 16;
;                 float s = 0.f; u32x4 pk[2];
; #pragma unroll
;                 for (int bj = 0; bj < 2; ++bj) {
;                     const f32x4 v0 = acc[ai][bj][m][0], v1 = acc[ai][bj][m][1];
;                     s += (v0[0] * v0[0] + v0[1] * v0[1]) + (v0[2] * v0[2] + v0[3] * v0[3]) + (v1[0] * v1[0] + v1[1] * v1[1]) + (v1[2] * v1[2] + v1[3] * v1[3]);
;                     pk[bj] = pack8(v0, v1);
;                 }
;                 store_pair(Y + (size_t)(rowg + ai * HALF + m * 16) * DM + colw, DM, fr, fq, pk[0], pk[1]);
;                 s += __shfl_xor(s, 16); s += __shfl_xor(s, 32);
;                 if (fq == 0) ssy[(size_t)row * 32 + u.pn * 4 + wc] = s;
.LBB0_1156:
	s_mov_b32 s9, s81
	s_lshl_b32 s9, s44, 8
	s_add_i32 s58, s9, s29
	s_lshl_b32 s9, s38, 8
	s_or_b32 s40, s9, s34
	v_readlane_b32 s46, v249, 10
	s_mov_b64 s[42:43], -1
	s_cmp_gt_i32 s80, -1
	v_cvt_pk_bf16_f32 v160, v126, v127
	v_cvt_pk_bf16_f32 v161, v128, v129
	v_cvt_pk_bf16_f32 v162, v122, v123
	v_cvt_pk_bf16_f32 v163, v124, v125
	v_cvt_pk_bf16_f32 v156, v118, v119
	v_cvt_pk_bf16_f32 v157, v120, v121
	v_cvt_pk_bf16_f32 v158, v114, v115
	v_cvt_pk_bf16_f32 v159, v116, v117
	v_lshlrev_b32_e32 v130, 1, v142
	v_lshlrev_b32_e32 v152, 1, v144
	v_lshlrev_b32_e32 v150, 1, v140
	v_readlane_b32 s47, v249, 11
	v_readlane_b32 s84, v255, 29
	v_readlane_b32 s49, v255, 32
	s_cbranch_scc1 .LBB0_1175
	v_mul_f32_e32 v127, v127, v127
	v_mul_f32_e32 v119, v119, v119
	v_fmac_f32_e32 v127, v126, v126
	v_mul_f32_e32 v126, v129, v129
	v_fmac_f32_e32 v119, v118, v118
	v_mul_f32_e32 v118, v121, v121
	v_fmac_f32_e32 v126, v128, v128
	v_mul_f32_e32 v123, v123, v123
	v_fmac_f32_e32 v118, v120, v120
	v_mul_f32_e32 v115, v115, v115
	v_and_b32_e32 v153, 64, v204
	v_add_f32_e32 v126, v127, v126
	v_fmac_f32_e32 v123, v122, v122
	v_add_f32_e32 v118, v119, v118
	v_fmac_f32_e32 v115, v114, v114
	v_xor_b32_e32 v151, 16, v204
	v_add_u32_e32 v153, 64, v153
	v_add_f32_e32 v122, v126, v123
	v_mul_f32_e32 v123, v125, v125
	v_add_f32_e32 v114, v118, v115
	v_mul_f32_e32 v115, v117, v117
	s_ashr_i32 s59, s58, 31
	s_ashr_i32 s41, s40, 31
	v_cmp_lt_i32_e32 vcc, v151, v153
	v_fmac_f32_e32 v123, v124, v124
	v_fmac_f32_e32 v115, v116, v116
	s_lshl_b64 s[42:43], s[58:59], 12
	v_readlane_b32 s9, v249, 28
	v_cndmask_b32_e32 v151, v204, v151, vcc
	v_add_f32_e32 v122, v123, v122
	v_add_f32_e32 v114, v115, v114
	s_add_u32 s9, s9, s42
	v_readlane_b32 s17, v253, 5
	v_lshlrev_b32_e32 v165, 2, v151
	v_add_f32_e32 v124, v122, v114
	s_addc_u32 s17, s17, s43
	s_lshl_b64 s[62:63], s[40:41], 1
	v_xor_b32_e32 v151, 32, v204
	s_add_u32 s42, s9, s62
	ds_bpermute_b32 v125, v165, v124
	v_cmp_lt_i32_e32 vcc, v151, v153
	s_addc_u32 s43, s17, s63
	v_cndmask_b32_e64 v114, v160, v156, s[52:53]
	v_cndmask_b32_e32 v151, v204, v151, vcc
	v_cndmask_b32_e64 v115, v161, v157, s[52:53]
	v_cndmask_b32_e64 v116, v162, v158, s[52:53]
	v_cndmask_b32_e64 v117, v163, v159, s[52:53]
	v_mov_b32_e32 v118, v131
	v_mov_b32_e32 v119, v131
	v_mov_b32_e32 v120, v131
	v_mov_b32_e32 v121, v131
	v_lshl_add_u64 v[122:123], s[42:43], 0, v[130:131]
	v_mov_b32_e32 v153, v131
	v_lshlrev_b32_e32 v164, 2, v151
	v_mov_b32_dpp v118, v114 row_ror:8 row_mask:0xf bank_mask:0xf
	v_mov_b32_dpp v119, v115 row_ror:8 row_mask:0xf bank_mask:0xf
	v_mov_b32_dpp v120, v116 row_ror:8 row_mask:0xf bank_mask:0xf
	v_mov_b32_dpp v121, v117 row_ror:8 row_mask:0xf bank_mask:0xf
	v_lshl_add_u64 v[122:123], v[122:123], 0, v[152:153]
	v_mov_b32_e32 v151, v131
	v_cndmask_b32_e64 v114, v118, v160, s[52:53]
	v_cndmask_b32_e64 v115, v119, v161, s[52:53]
	v_cndmask_b32_e64 v116, v120, v162, s[52:53]
	v_cndmask_b32_e64 v117, v121, v163, s[52:53]
	v_lshl_add_u64 v[122:123], v[122:123], 0, v[150:151]
	global_store_dwordx4 v[122:123], v[114:117], off
	v_or_b32_e32 v154, s58, v141
	v_cndmask_b32_e64 v118, v156, v118, s[52:53]
	s_waitcnt lgkmcnt(0)
	v_add_f32_e32 v114, v124, v125
	ds_bpermute_b32 v115, v164, v114
	v_add_co_u32_e32 v116, vcc, 0x8000, v122
	v_cndmask_b32_e64 v119, v157, v119, s[52:53]
	v_cndmask_b32_e64 v120, v158, v120, s[52:53]
	v_cndmask_b32_e64 v121, v159, v121, s[52:53]
	v_addc_co_u32_e32 v117, vcc, 0, v123, vcc
	v_ashrrev_i32_e32 v155, 31, v154
	global_store_dwordx4 v[116:117], v[118:121], off
	s_and_saveexec_b64 s[42:43], s[54:55]
	s_cbranch_execz .LBB0_1159
	v_readlane_b32 s60, v253, 6
	s_waitcnt lgkmcnt(0)
	v_add_f32_e32 v116, v114, v115
	s_lshl_b32 s44, s38, 2
	v_lshlrev_b64 v[114:115], 7, v[154:155]
	v_readlane_b32 s61, v253, 7
	s_ashr_i32 s45, s44, 31
	s_nop 0
	v_lshl_add_u64 v[114:115], s[60:61], 0, v[114:115]
	v_lshl_add_u64 v[114:115], s[44:45], 2, v[114:115]
	s_lshl_b32 s44, s25, 2
	s_mov_b32 s45, s81
	v_lshl_add_u64 v[114:115], v[114:115], 0, s[44:45]
	global_store_dword v[114:115], v116, off
.LBB0_1159:
	s_or_b64 exec, exec, s[42:43]
	v_mul_f32_e32 v119, v103, v103
	v_mul_f32_e32 v120, v105, v105
	v_mul_f32_e32 v114, v111, v111
	s_waitcnt lgkmcnt(0)
	v_mul_f32_e32 v115, v113, v113
	v_fmac_f32_e32 v119, v102, v102
	v_fmac_f32_e32 v120, v104, v104
	v_fmac_f32_e32 v114, v110, v110
	v_fmac_f32_e32 v115, v112, v112
	v_add_f32_e32 v119, v119, v120
	v_mul_f32_e32 v120, v99, v99
	v_add_f32_e32 v114, v114, v115
	v_mul_f32_e32 v115, v107, v107
	v_fmac_f32_e32 v120, v98, v98
	v_fmac_f32_e32 v115, v106, v106
	v_add_f32_e32 v119, v119, v120
	v_mul_f32_e32 v120, v101, v101
	v_add_f32_e32 v114, v114, v115
	v_mul_f32_e32 v115, v109, v109
	v_fmac_f32_e32 v120, v100, v100
	v_fmac_f32_e32 v115, v108, v108
	v_cvt_pk_bf16_f32 v116, v112, v113
	v_add_f32_e32 v119, v120, v119
	v_cvt_pk_bf16_f32 v120, v104, v105
	s_or_b32 s42, s58, 16
	v_add_f32_e32 v114, v115, v114
	v_cvt_pk_bf16_f32 v117, v106, v107
	v_cvt_pk_bf16_f32 v121, v98, v99
	s_ashr_i32 s43, s42, 31
	v_cndmask_b32_e64 v123, v116, v120, s[52:53]
	v_mov_b32_e32 v128, v131
	v_cvt_pk_bf16_f32 v115, v110, v111
	v_cvt_pk_bf16_f32 v118, v108, v109
	v_add_f32_e32 v124, v114, v119
	v_cvt_pk_bf16_f32 v119, v102, v103
	v_cvt_pk_bf16_f32 v122, v100, v101
	s_lshl_b64 s[42:43], s[42:43], 12
	v_readlane_b32 s9, v249, 28
	v_cndmask_b32_e64 v125, v117, v121, s[52:53]
	v_mov_b32_dpp v128, v123 row_ror:8 row_mask:0xf bank_mask:0xf
	v_mov_b32_e32 v123, v131
	s_add_u32 s9, s9, s42
	v_readlane_b32 s17, v253, 5
	v_cndmask_b32_e64 v114, v115, v119, s[52:53]
	v_cndmask_b32_e64 v126, v118, v122, s[52:53]
	v_mov_b32_e32 v127, v131
	v_mov_b32_dpp v123, v125 row_ror:8 row_mask:0xf bank_mask:0xf
	v_mov_b32_e32 v125, v131
	s_addc_u32 s17, s17, s43
	v_mov_b32_dpp v127, v114 row_ror:8 row_mask:0xf bank_mask:0xf
	v_mov_b32_dpp v125, v126 row_ror:8 row_mask:0xf bank_mask:0xf
	s_add_u32 s42, s9, s62
	v_cndmask_b32_e64 v114, v127, v115, s[52:53]
	v_cndmask_b32_e64 v115, v128, v116, s[52:53]
	v_cndmask_b32_e64 v116, v123, v117, s[52:53]
	v_cndmask_b32_e64 v117, v125, v118, s[52:53]
	v_cndmask_b32_e64 v118, v119, v127, s[52:53]
	v_cndmask_b32_e64 v119, v120, v128, s[52:53]
	v_cndmask_b32_e64 v120, v121, v123, s[52:53]
	v_cndmask_b32_e64 v121, v122, v125, s[52:53]
	ds_bpermute_b32 v125, v165, v124
	s_addc_u32 s43, s17, s63
	v_lshl_add_u64 v[122:123], s[42:43], 0, v[130:131]
	v_lshl_add_u64 v[122:123], v[122:123], 0, v[152:153]
	v_lshl_add_u64 v[122:123], v[122:123], 0, v[150:151]
	global_store_dwordx4 v[122:123], v[114:117], off
	s_waitcnt lgkmcnt(0)
	s_nop 0
	v_add_f32_e32 v114, v124, v125
	ds_bpermute_b32 v115, v164, v114
	v_add_co_u32_e32 v116, vcc, 0x8000, v122
	s_nop 1
	v_addc_co_u32_e32 v117, vcc, 0, v123, vcc
	global_store_dwordx4 v[116:117], v[118:121], off
	s_and_saveexec_b64 s[42:43], s[54:55]
	s_cbranch_execz .LBB0_1161
; __device__ __forceinline__ u32x4 pack8(f32x4 a, f32x4 b) { u32x4 w; w.x = cvtpk(a[0], a[1]); w.y = cvtpk(a[2], a[3]); w.z = cvtpk(b[0], b[1]); w.w = cvtpk(b[2], b[3]); return w; }
; __device__ __forceinline__ unsigned dpp_ror8(unsigned v) { return (unsigned)__builtin_amdgcn_update_dpp(0, (int)v, 0x128, 0xF, 0xF, false); }
; __device__ __forceinline__ void store_pair(bf16_t* grp  , size_t ld, int fr, int fq, u32x4 P0, u32x4 P1) {
;     const bool up = (fr & 8) != 0;
;     u32x4 snd, rcv;
;     snd.x = up ? P0.x : P1.x; snd.y = up ? P0.y : P1.y; snd.z = up ? P0.z : P1.z; snd.w = up ? P0.w : P1.w;
;     rcv.x = dpp_ror8(snd.x); rcv.y = dpp_ror8(snd.y); rcv.z = dpp_ror8(snd.z); rcv.w = dpp_ror8(snd.w);
;     u32x4 dA, dB;
;     dA.x = up ? rcv.x : P0.x; dA.y = up ? rcv.y : P0.y; dA.z = up ? rcv.z : P0.z; dA.w = up ? rcv.w : P0.w;
;     dB.x = up ? P1.x : rcv.x; dB.y = up ? P1.y : rcv.y; dB.z = up ? P1.z : rcv.z; dB.w = up ? P1.w : rcv.w;
;     bf16_t* p = grp + (size_t)(fr & 7) * ld + (up ? CBJ : 0) + 8 * fq;
;     __builtin_nontemporal_store(dA, (u32x4*)p); __builtin_nontemporal_store(dB, (u32x4*)(p + 8 * ld));
;     __device__ __forceinline__ void operator()(f32x4 (&acc)[2][2][4][2], const Unit& u, int wr, int wc, int fr, int fq) const {
;     ...
;         for (int ai = 0; ai < 2; ++ai)
; #pragma unroll
;             for (int m = 0; m < 4; ++m) {
;                 const int row = row0 + ai * HALF + m * 16;
;                 float s = 0.f; u32x4 pk[2];
; #pragma unroll
;                 for (int bj = 0; bj < 2; ++bj) {
;                     const f32x4 v0 = acc[ai][bj][m][0], v1 = acc[ai][bj][m][1];
;                     s += (v0[0] * v0[0] + v0[1] * v0[1]) + (v0[2] * v0[2] + v0[3] * v0[3]) + (v1[0] * v1[0] + v1[1] * v1[1]) + (v1[2] * v1[2] + v1[3] * v1[3]);
;                     pk[bj] = pack8(v0, v1);
;                 }
;                 store_pair(Y + (size_t)(rowg + ai * HALF + m * 16) * DM + colw, DM, fr, fq, pk[0], pk[1]);
;                 s += __shfl_xor(s, 16); s += __shfl_xor(s, 32);
;                 if (fq == 0) ssy[(size_t)row * 32 + u.pn * 4 + wc] = s;
	v_or_b32_e32 v116, 16, v154
	v_ashrrev_i32_e32 v117, 31, v116
	v_readlane_b32 s60, v253, 6
	s_waitcnt lgkmcnt(0)
	v_add_f32_e32 v118, v114, v115
	s_lshl_b32 s44, s38, 2
	v_lshlrev_b64 v[114:115], 7, v[116:117]
	v_readlane_b32 s61, v253, 7
	s_ashr_i32 s45, s44, 31
	s_nop 0
	v_lshl_add_u64 v[114:115], s[60:61], 0, v[114:115]
	v_lshl_add_u64 v[114:115], s[44:45], 2, v[114:115]
	s_lshl_b32 s44, s25, 2
	s_mov_b32 s45, s81
	v_lshl_add_u64 v[114:115], v[114:115], 0, s[44:45]
	global_store_dword v[114:115], v118, off
.LBB0_1161:
	s_or_b64 exec, exec, s[42:43]
	v_mul_f32_e32 v119, v87, v87
	v_mul_f32_e32 v120, v89, v89
	v_mul_f32_e32 v114, v95, v95
	s_waitcnt lgkmcnt(0)
	v_mul_f32_e32 v115, v97, v97
	v_fmac_f32_e32 v119, v86, v86
	v_fmac_f32_e32 v120, v88, v88
	v_fmac_f32_e32 v114, v94, v94
	v_fmac_f32_e32 v115, v96, v96
	v_add_f32_e32 v119, v119, v120
	v_mul_f32_e32 v120, v83, v83
	v_add_f32_e32 v114, v114, v115
	v_mul_f32_e32 v115, v91, v91
	v_fmac_f32_e32 v120, v82, v82
	v_fmac_f32_e32 v115, v90, v90
	v_add_f32_e32 v119, v119, v120
	v_mul_f32_e32 v120, v85, v85
	s_or_b32 s42, s58, 32
	v_add_f32_e32 v114, v114, v115
	v_mul_f32_e32 v115, v93, v93
	v_fmac_f32_e32 v120, v84, v84
	s_ashr_i32 s43, s42, 31
	v_fmac_f32_e32 v115, v92, v92
	v_cvt_pk_bf16_f32 v116, v96, v97
	v_add_f32_e32 v119, v120, v119
	v_cvt_pk_bf16_f32 v120, v88, v89
	s_lshl_b64 s[42:43], s[42:43], 12
	v_readlane_b32 s9, v249, 28
	v_add_f32_e32 v114, v115, v114
	v_cvt_pk_bf16_f32 v117, v90, v91
	v_cvt_pk_bf16_f32 v121, v82, v83
	s_add_u32 s9, s9, s42
	v_readlane_b32 s17, v253, 5
	v_cndmask_b32_e64 v123, v116, v120, s[52:53]
	v_mov_b32_e32 v128, v131
	v_cvt_pk_bf16_f32 v115, v94, v95
	v_cvt_pk_bf16_f32 v118, v92, v93
	v_add_f32_e32 v124, v114, v119
	v_cvt_pk_bf16_f32 v119, v86, v87
	v_cvt_pk_bf16_f32 v122, v84, v85
	s_addc_u32 s17, s17, s43
	v_cndmask_b32_e64 v125, v117, v121, s[52:53]
	v_mov_b32_dpp v128, v123 row_ror:8 row_mask:0xf bank_mask:0xf
	v_mov_b32_e32 v123, v131
	s_add_u32 s42, s9, s62
	v_cndmask_b32_e64 v114, v115, v119, s[52:53]
	v_cndmask_b32_e64 v126, v118, v122, s[52:53]
	v_mov_b32_e32 v127, v131
	v_mov_b32_dpp v123, v125 row_ror:8 row_mask:0xf bank_mask:0xf
	v_mov_b32_e32 v125, v131
	s_addc_u32 s43, s17, s63
	v_mov_b32_dpp v127, v114 row_ror:8 row_mask:0xf bank_mask:0xf
	v_mov_b32_dpp v125, v126 row_ror:8 row_mask:0xf bank_mask:0xf
	v_cndmask_b32_e64 v114, v127, v115, s[52:53]
	v_cndmask_b32_e64 v115, v128, v116, s[52:53]
	v_cndmask_b32_e64 v116, v123, v117, s[52:53]
	v_cndmask_b32_e64 v117, v125, v118, s[52:53]
	v_cndmask_b32_e64 v118, v119, v127, s[52:53]
	v_cndmask_b32_e64 v119, v120, v128, s[52:53]
	v_cndmask_b32_e64 v120, v121, v123, s[52:53]
	v_cndmask_b32_e64 v121, v122, v125, s[52:53]
	v_lshl_add_u64 v[122:123], s[42:43], 0, v[130:131]
	v_mov_b32_e32 v153, v131
	v_lshl_add_u64 v[122:123], v[122:123], 0, v[152:153]
	v_mov_b32_e32 v151, v131
	v_lshl_add_u64 v[122:123], v[122:123], 0, v[150:151]
	global_store_dwordx4 v[122:123], v[114:117], off
	s_nop 1
	v_add_co_u32_e32 v114, vcc, 0x8000, v122
	s_nop 1
	v_addc_co_u32_e32 v115, vcc, 0, v123, vcc
	global_store_dwordx4 v[114:115], v[118:121], off
	ds_bpermute_b32 v114, v165, v124
	s_waitcnt lgkmcnt(0)
	v_add_f32_e32 v114, v124, v114
	ds_bpermute_b32 v115, v164, v114
	s_and_saveexec_b64 s[42:43], s[54:55]
	s_cbranch_execz .LBB0_1163
	v_or_b32_e32 v116, 32, v154
	v_ashrrev_i32_e32 v117, 31, v116
	v_readlane_b32 s60, v253, 6
	s_waitcnt lgkmcnt(0)
	v_add_f32_e32 v118, v114, v115
	s_lshl_b32 s44, s38, 2
	v_lshlrev_b64 v[114:115], 7, v[116:117]
	v_readlane_b32 s61, v253, 7
	s_ashr_i32 s45, s44, 31
	s_nop 0
	v_lshl_add_u64 v[114:115], s[60:61], 0, v[114:115]
	v_lshl_add_u64 v[114:115], s[44:45], 2, v[114:115]
	s_lshl_b32 s44, s25, 2
	s_mov_b32 s45, s81
	v_lshl_add_u64 v[114:115], v[114:115], 0, s[44:45]
	global_store_dword v[114:115], v118, off
.LBB0_1163:
	s_or_b64 exec, exec, s[42:43]
	v_mul_f32_e32 v119, v71, v71
	v_mul_f32_e32 v120, v73, v73
	v_mul_f32_e32 v114, v79, v79
	s_waitcnt lgkmcnt(0)
	v_mul_f32_e32 v115, v81, v81
	v_fmac_f32_e32 v119, v70, v70
	v_fmac_f32_e32 v120, v72, v72
	v_fmac_f32_e32 v114, v78, v78
	v_fmac_f32_e32 v115, v80, v80
	v_add_f32_e32 v119, v119, v120
	v_mul_f32_e32 v120, v67, v67
	v_add_f32_e32 v114, v114, v115
	v_mul_f32_e32 v115, v75, v75
	v_fmac_f32_e32 v120, v66, v66
	v_fmac_f32_e32 v115, v74, v74
	v_add_f32_e32 v119, v119, v120
	v_mul_f32_e32 v120, v69, v69
	v_add_f32_e32 v114, v114, v115
	v_mul_f32_e32 v115, v77, v77
	v_fmac_f32_e32 v120, v68, v68
	v_fmac_f32_e32 v115, v76, v76
	v_cvt_pk_bf16_f32 v116, v80, v81
	v_add_f32_e32 v119, v120, v119
	v_cvt_pk_bf16_f32 v120, v72, v73
	s_or_b32 s42, s58, 48
	v_add_f32_e32 v114, v115, v114
	v_cvt_pk_bf16_f32 v117, v74, v75
	v_cvt_pk_bf16_f32 v121, v66, v67
	s_ashr_i32 s43, s42, 31
	v_cndmask_b32_e64 v123, v116, v120, s[52:53]
	v_mov_b32_e32 v128, v131
	v_cvt_pk_bf16_f32 v115, v78, v79
	v_cvt_pk_bf16_f32 v118, v76, v77
	v_add_f32_e32 v124, v114, v119
	v_cvt_pk_bf16_f32 v119, v70, v71
	v_cvt_pk_bf16_f32 v122, v68, v69
	s_lshl_b64 s[42:43], s[42:43], 12
	v_readlane_b32 s9, v249, 28
	v_cndmask_b32_e64 v125, v117, v121, s[52:53]
	v_mov_b32_dpp v128, v123 row_ror:8 row_mask:0xf bank_mask:0xf
	v_mov_b32_e32 v123, v131
	s_add_u32 s9, s9, s42
	v_readlane_b32 s17, v253, 5
	v_cndmask_b32_e64 v114, v115, v119, s[52:53]
	v_cndmask_b32_e64 v126, v118, v122, s[52:53]
	v_mov_b32_e32 v127, v131
	v_mov_b32_dpp v123, v125 row_ror:8 row_mask:0xf bank_mask:0xf
	v_mov_b32_e32 v125, v131
	s_addc_u32 s17, s17, s43
	v_mov_b32_dpp v127, v114 row_ror:8 row_mask:0xf bank_mask:0xf
	v_mov_b32_dpp v125, v126 row_ror:8 row_mask:0xf bank_mask:0xf
	s_add_u32 s42, s9, s62
	v_cndmask_b32_e64 v114, v127, v115, s[52:53]
	v_cndmask_b32_e64 v115, v128, v116, s[52:53]
	v_cndmask_b32_e64 v116, v123, v117, s[52:53]
	v_cndmask_b32_e64 v117, v125, v118, s[52:53]
	v_cndmask_b32_e64 v118, v119, v127, s[52:53]
	v_cndmask_b32_e64 v119, v120, v128, s[52:53]
	v_cndmask_b32_e64 v120, v121, v123, s[52:53]
	v_cndmask_b32_e64 v121, v122, v125, s[52:53]
	ds_bpermute_b32 v125, v165, v124
	s_addc_u32 s43, s17, s63
	v_lshl_add_u64 v[122:123], s[42:43], 0, v[130:131]
	v_lshl_add_u64 v[122:123], v[122:123], 0, v[152:153]
	v_lshl_add_u64 v[122:123], v[122:123], 0, v[150:151]
	global_store_dwordx4 v[122:123], v[114:117], off
	s_waitcnt lgkmcnt(0)
	s_nop 0
	v_add_f32_e32 v114, v124, v125
	ds_bpermute_b32 v115, v164, v114
	v_add_co_u32_e32 v116, vcc, 0x8000, v122
	s_nop 1
	v_addc_co_u32_e32 v117, vcc, 0, v123, vcc
	global_store_dwordx4 v[116:117], v[118:121], off
	s_and_saveexec_b64 s[42:43], s[54:55]
	s_cbranch_execz .LBB0_1165
; __device__ __forceinline__ u32x4 pack8(f32x4 a, f32x4 b) { u32x4 w; w.x = cvtpk(a[0], a[1]); w.y = cvtpk(a[2], a[3]); w.z = cvtpk(b[0], b[1]); w.w = cvtpk(b[2], b[3]); return w; }
; __device__ __forceinline__ unsigned dpp_ror8(unsigned v) { return (unsigned)__builtin_amdgcn_update_dpp(0, (int)v, 0x128, 0xF, 0xF, false); }
; __device__ __forceinline__ void store_pair(bf16_t* grp  , size_t ld, int fr, int fq, u32x4 P0, u32x4 P1) {
;     const bool up = (fr & 8) != 0;
;     u32x4 snd, rcv;
;     snd.x = up ? P0.x : P1.x; snd.y = up ? P0.y : P1.y; snd.z = up ? P0.z : P1.z; snd.w = up ? P0.w : P1.w;
;     rcv.x = dpp_ror8(snd.x); rcv.y = dpp_ror8(snd.y); rcv.z = dpp_ror8(snd.z); rcv.w = dpp_ror8(snd.w);
;     u32x4 dA, dB;
;     dA.x = up ? rcv.x : P0.x; dA.y = up ? rcv.y : P0.y; dA.z = up ? rcv.z : P0.z; dA.w = up ? rcv.w : P0.w;
;     dB.x = up ? P1.x : rcv.x; dB.y = up ? P1.y : rcv.y; dB.z = up ? P1.z : rcv.z; dB.w = up ? P1.w : rcv.w;
;     bf16_t* p = grp + (size_t)(fr & 7) * ld + (up ? CBJ : 0) + 8 * fq;
;     __builtin_nontemporal_store(dA, (u32x4*)p); __builtin_nontemporal_store(dB, (u32x4*)(p + 8 * ld));
;     __device__ __forceinline__ void operator()(f32x4 (&acc)[2][2][4][2], const Unit& u, int wr, int wc, int fr, int fq) const {
;     ...
;         for (int ai = 0; ai < 2; ++ai)
; #pragma unroll
;             for (int m = 0; m < 4; ++m) {
;                 const int row = row0 + ai * HALF + m * 16;
;                 float s = 0.f; u32x4 pk[2];
; #pragma unroll
;                 for (int bj = 0; bj < 2; ++bj) {
;                     const f32x4 v0 = acc[ai][bj][m][0], v1 = acc[ai][bj][m][1];
;                     s += (v0[0] * v0[0] + v0[1] * v0[1]) + (v0[2] * v0[2] + v0[3] * v0[3]) + (v1[0] * v1[0] + v1[1] * v1[1]) + (v1[2] * v1[2] + v1[3] * v1[3]);
;                     pk[bj] = pack8(v0, v1);
;                 }
;                 store_pair(Y + (size_t)(rowg + ai * HALF + m * 16) * DM + colw, DM, fr, fq, pk[0], pk[1]);
;                 s += __shfl_xor(s, 16); s += __shfl_xor(s, 32);
;                 if (fq == 0) ssy[(size_t)row * 32 + u.pn * 4 + wc] = s;
	v_or_b32_e32 v116, 48, v154
	v_ashrrev_i32_e32 v117, 31, v116
	v_readlane_b32 s60, v253, 6
	s_waitcnt lgkmcnt(0)
	v_add_f32_e32 v118, v114, v115
	s_lshl_b32 s44, s38, 2
	v_lshlrev_b64 v[114:115], 7, v[116:117]
	v_readlane_b32 s61, v253, 7
	s_ashr_i32 s45, s44, 31
	s_nop 0
	v_lshl_add_u64 v[114:115], s[60:61], 0, v[114:115]
	v_lshl_add_u64 v[114:115], s[44:45], 2, v[114:115]
	s_lshl_b32 s44, s25, 2
	s_mov_b32 s45, s81
	v_lshl_add_u64 v[114:115], v[114:115], 0, s[44:45]
	global_store_dword v[114:115], v118, off
.LBB0_1165:
	s_or_b64 exec, exec, s[42:43]
	v_mul_f32_e32 v119, v55, v55
	v_mul_f32_e32 v120, v57, v57
	v_mul_f32_e32 v114, v63, v63
	s_waitcnt lgkmcnt(0)
	v_mul_f32_e32 v115, v65, v65
	v_fmac_f32_e32 v119, v54, v54
	v_fmac_f32_e32 v120, v56, v56
	v_fmac_f32_e32 v114, v62, v62
	v_fmac_f32_e32 v115, v64, v64
	v_add_f32_e32 v119, v119, v120
	v_mul_f32_e32 v120, v51, v51
	v_add_f32_e32 v114, v114, v115
	v_mul_f32_e32 v115, v59, v59
	v_fmac_f32_e32 v120, v50, v50
	v_fmac_f32_e32 v115, v58, v58
	v_add_f32_e32 v119, v119, v120
	v_mul_f32_e32 v120, v53, v53
	v_add_f32_e32 v114, v114, v115
	v_mul_f32_e32 v115, v61, v61
	v_fmac_f32_e32 v120, v52, v52
	v_fmac_f32_e32 v115, v60, v60
	v_cvt_pk_bf16_f32 v116, v64, v65
	v_add_f32_e32 v119, v120, v119
	v_cvt_pk_bf16_f32 v120, v56, v57
	s_lshl_b64 s[42:43], s[58:59], 12
	v_readlane_b32 s9, v249, 28
	v_add_f32_e32 v114, v115, v114
	v_cvt_pk_bf16_f32 v117, v58, v59
	v_cvt_pk_bf16_f32 v121, v50, v51
	s_add_u32 s9, s9, s42
	v_readlane_b32 s17, v253, 5
	v_cndmask_b32_e64 v123, v116, v120, s[52:53]
	v_mov_b32_e32 v128, v131
	v_cvt_pk_bf16_f32 v115, v62, v63
	v_cvt_pk_bf16_f32 v118, v60, v61
	v_add_f32_e32 v126, v114, v119
	v_cvt_pk_bf16_f32 v119, v54, v55
	v_cvt_pk_bf16_f32 v122, v52, v53
	s_addc_u32 s17, s17, s43
	v_cndmask_b32_e64 v124, v117, v121, s[52:53]
	v_mov_b32_dpp v128, v123 row_ror:8 row_mask:0xf bank_mask:0xf
	v_mov_b32_e32 v123, v131
	s_add_u32 s44, s9, s62
	v_cndmask_b32_e64 v114, v115, v119, s[52:53]
	v_cndmask_b32_e64 v125, v118, v122, s[52:53]
	v_mov_b32_e32 v127, v131
	v_mov_b32_dpp v123, v124 row_ror:8 row_mask:0xf bank_mask:0xf
	v_mov_b32_e32 v124, v131
	s_addc_u32 s45, s17, s63
	v_mov_b32_dpp v127, v114 row_ror:8 row_mask:0xf bank_mask:0xf
	v_mov_b32_dpp v124, v125 row_ror:8 row_mask:0xf bank_mask:0xf
	v_cndmask_b32_e64 v114, v127, v115, s[52:53]
	v_cndmask_b32_e64 v115, v128, v116, s[52:53]
	v_cndmask_b32_e64 v116, v123, v117, s[52:53]
	v_cndmask_b32_e64 v117, v124, v118, s[52:53]
	v_cndmask_b32_e64 v118, v119, v127, s[52:53]
	v_cndmask_b32_e64 v119, v120, v128, s[52:53]
	v_cndmask_b32_e64 v120, v121, v123, s[52:53]
	v_cndmask_b32_e64 v121, v122, v124, s[52:53]
	v_lshl_add_u64 v[122:123], s[44:45], 0, v[130:131]
	v_mov_b32_e32 v153, v131
	v_lshl_add_u64 v[122:123], v[122:123], 0, v[152:153]
	v_mov_b32_e32 v151, v131
	v_lshl_add_u64 v[122:123], v[122:123], 0, v[150:151]
	s_mov_b32 s9, 0x80000
	v_add_co_u32_e32 v124, vcc, s9, v122
	s_nop 1
	v_addc_co_u32_e32 v125, vcc, 0, v123, vcc
	global_store_dwordx4 v[124:125], v[114:117], off
	s_nop 1
	v_add_co_u32_e32 v114, vcc, 0x88000, v122
	s_nop 1
	v_addc_co_u32_e32 v115, vcc, 0, v123, vcc
	global_store_dwordx4 v[114:115], v[118:121], off
	ds_bpermute_b32 v114, v165, v126
	s_waitcnt lgkmcnt(0)
	v_add_f32_e32 v114, v126, v114
	ds_bpermute_b32 v115, v164, v114
	s_and_saveexec_b64 s[82:83], s[54:55]
	s_cbranch_execz .LBB0_1167
	v_readlane_b32 s60, v253, 6
	s_waitcnt lgkmcnt(0)
	v_add_f32_e32 v116, v114, v115
	v_lshlrev_b64 v[114:115], 7, v[154:155]
	s_lshl_b32 s44, s38, 2
	v_readlane_b32 s61, v253, 7
	s_ashr_i32 s45, s44, 31
	s_nop 0
	v_lshl_add_u64 v[114:115], s[60:61], 0, v[114:115]
	v_lshl_add_u64 v[114:115], s[44:45], 2, v[114:115]
	s_lshl_b32 s44, s25, 2
	s_mov_b32 s45, s81
	v_lshl_add_u64 v[114:115], v[114:115], 0, s[44:45]
	v_add_co_u32_e32 v114, vcc, 0x4000, v114
	s_nop 1
	v_addc_co_u32_e32 v115, vcc, 0, v115, vcc
	global_store_dword v[114:115], v116, off
.LBB0_1167:
	s_or_b64 exec, exec, s[82:83]
	v_mul_f32_e32 v119, v39, v39
	v_mul_f32_e32 v120, v41, v41
	v_mul_f32_e32 v114, v47, v47
	s_waitcnt lgkmcnt(0)
	v_mul_f32_e32 v115, v49, v49
	v_fmac_f32_e32 v119, v38, v38
	v_fmac_f32_e32 v120, v40, v40
	v_fmac_f32_e32 v114, v46, v46
	v_fmac_f32_e32 v115, v48, v48
	v_add_f32_e32 v119, v119, v120
	v_mul_f32_e32 v120, v35, v35
	v_add_f32_e32 v114, v114, v115
	v_mul_f32_e32 v115, v43, v43
	v_fmac_f32_e32 v120, v34, v34
	v_fmac_f32_e32 v115, v42, v42
	v_add_f32_e32 v119, v119, v120
	v_mul_f32_e32 v120, v37, v37
	v_add_f32_e32 v114, v114, v115
	v_mul_f32_e32 v115, v45, v45
	v_fmac_f32_e32 v120, v36, v36
	v_fmac_f32_e32 v115, v44, v44
	v_cvt_pk_bf16_f32 v116, v48, v49
	v_add_f32_e32 v119, v120, v119
	v_cvt_pk_bf16_f32 v120, v40, v41
	v_readlane_b32 s9, v249, 28
	v_add_f32_e32 v114, v115, v114
	v_cvt_pk_bf16_f32 v117, v42, v43
	v_cvt_pk_bf16_f32 v121, v34, v35
	s_add_u32 s9, s9, s42
	v_readlane_b32 s17, v253, 5
	v_cndmask_b32_e64 v123, v116, v120, s[52:53]
	v_mov_b32_e32 v128, v131
	v_cvt_pk_bf16_f32 v115, v46, v47
	v_cvt_pk_bf16_f32 v118, v44, v45
	v_add_f32_e32 v126, v114, v119
	v_cvt_pk_bf16_f32 v119, v38, v39
	v_cvt_pk_bf16_f32 v122, v36, v37
	s_addc_u32 s17, s17, s43
	v_cndmask_b32_e64 v124, v117, v121, s[52:53]
	v_mov_b32_dpp v128, v123 row_ror:8 row_mask:0xf bank_mask:0xf
	v_mov_b32_e32 v123, v131
	s_add_u32 s42, s9, s62
	v_cndmask_b32_e64 v114, v115, v119, s[52:53]
	v_cndmask_b32_e64 v125, v118, v122, s[52:53]
	v_mov_b32_e32 v127, v131
	v_mov_b32_dpp v123, v124 row_ror:8 row_mask:0xf bank_mask:0xf
	v_mov_b32_e32 v124, v131
	s_addc_u32 s43, s17, s63
	v_mov_b32_dpp v127, v114 row_ror:8 row_mask:0xf bank_mask:0xf
	v_mov_b32_dpp v124, v125 row_ror:8 row_mask:0xf bank_mask:0xf
	v_cndmask_b32_e64 v114, v127, v115, s[52:53]
	v_cndmask_b32_e64 v115, v128, v116, s[52:53]
	v_cndmask_b32_e64 v116, v123, v117, s[52:53]
	v_cndmask_b32_e64 v117, v124, v118, s[52:53]
	v_cndmask_b32_e64 v118, v119, v127, s[52:53]
	v_cndmask_b32_e64 v119, v120, v128, s[52:53]
	v_cndmask_b32_e64 v120, v121, v123, s[52:53]
	v_cndmask_b32_e64 v121, v122, v124, s[52:53]
	v_lshl_add_u64 v[122:123], s[42:43], 0, v[130:131]
	ds_bpermute_b32 v127, v165, v126
	v_lshl_add_u64 v[122:123], v[122:123], 0, v[152:153]
	v_lshl_add_u64 v[122:123], v[122:123], 0, v[150:151]
	s_mov_b32 s9, 0x90000
	v_add_co_u32_e32 v124, vcc, s9, v122
	s_nop 1
	v_addc_co_u32_e32 v125, vcc, 0, v123, vcc
	global_store_dwordx4 v[124:125], v[114:117], off
	s_waitcnt lgkmcnt(0)
	s_nop 0
	v_add_f32_e32 v114, v126, v127
	ds_bpermute_b32 v115, v164, v114
	v_add_co_u32_e32 v116, vcc, 0x98000, v122
	s_nop 1
	v_addc_co_u32_e32 v117, vcc, 0, v123, vcc
	global_store_dwordx4 v[116:117], v[118:121], off
	s_and_saveexec_b64 s[42:43], s[54:55]
	s_cbranch_execz .LBB0_1169
; __device__ __forceinline__ u32x4 pack8(f32x4 a, f32x4 b) { u32x4 w; w.x = cvtpk(a[0], a[1]); w.y = cvtpk(a[2], a[3]); w.z = cvtpk(b[0], b[1]); w.w = cvtpk(b[2], b[3]); return w; }
; __device__ __forceinline__ unsigned dpp_ror8(unsigned v) { return (unsigned)__builtin_amdgcn_update_dpp(0, (int)v, 0x128, 0xF, 0xF, false); }
; __device__ __forceinline__ void store_pair(bf16_t* grp  , size_t ld, int fr, int fq, u32x4 P0, u32x4 P1) {
;     const bool up = (fr & 8) != 0;
;     u32x4 snd, rcv;
;     snd.x = up ? P0.x : P1.x; snd.y = up ? P0.y : P1.y; snd.z = up ? P0.z : P1.z; snd.w = up ? P0.w : P1.w;
;     rcv.x = dpp_ror8(snd.x); rcv.y = dpp_ror8(snd.y); rcv.z = dpp_ror8(snd.z); rcv.w = dpp_ror8(snd.w);
;     u32x4 dA, dB;
;     dA.x = up ? rcv.x : P0.x; dA.y = up ? rcv.y : P0.y; dA.z = up ? rcv.z : P0.z; dA.w = up ? rcv.w : P0.w;
;     dB.x = up ? P1.x : rcv.x; dB.y = up ? P1.y : rcv.y; dB.z = up ? P1.z : rcv.z; dB.w = up ? P1.w : rcv.w;
;     bf16_t* p = grp + (size_t)(fr & 7) * ld + (up ? CBJ : 0) + 8 * fq;
;     __builtin_nontemporal_store(dA, (u32x4*)p); __builtin_nontemporal_store(dB, (u32x4*)(p + 8 * ld));
;     __device__ __forceinline__ void operator()(f32x4 (&acc)[2][2][4][2], const Unit& u, int wr, int wc, int fr, int fq) const {
;     ...
;         for (int ai = 0; ai < 2; ++ai)
; #pragma unroll
;             for (int m = 0; m < 4; ++m) {
;                 const int row = row0 + ai * HALF + m * 16;
;                 float s = 0.f; u32x4 pk[2];
; #pragma unroll
;                 for (int bj = 0; bj < 2; ++bj) {
;                     const f32x4 v0 = acc[ai][bj][m][0], v1 = acc[ai][bj][m][1];
;                     s += (v0[0] * v0[0] + v0[1] * v0[1]) + (v0[2] * v0[2] + v0[3] * v0[3]) + (v1[0] * v1[0] + v1[1] * v1[1]) + (v1[2] * v1[2] + v1[3] * v1[3]);
;                     pk[bj] = pack8(v0, v1);
;                 }
;                 store_pair(Y + (size_t)(rowg + ai * HALF + m * 16) * DM + colw, DM, fr, fq, pk[0], pk[1]);
;                 s += __shfl_xor(s, 16); s += __shfl_xor(s, 32);
;                 if (fq == 0) ssy[(size_t)row * 32 + u.pn * 4 + wc] = s;
	v_readlane_b32 s60, v253, 6
	s_waitcnt lgkmcnt(0)
	v_add_f32_e32 v116, v114, v115
	v_lshlrev_b64 v[114:115], 7, v[154:155]
	s_lshl_b32 s44, s38, 2
	v_readlane_b32 s61, v253, 7
	s_ashr_i32 s45, s44, 31
	s_nop 0
	v_lshl_add_u64 v[114:115], s[60:61], 0, v[114:115]
	v_lshl_add_u64 v[114:115], s[44:45], 2, v[114:115]
	s_lshl_b32 s44, s25, 2
	s_mov_b32 s45, s81
	v_lshl_add_u64 v[114:115], v[114:115], 0, s[44:45]
	v_add_co_u32_e32 v114, vcc, 0x4000, v114
	s_nop 1
	v_addc_co_u32_e32 v115, vcc, 0, v115, vcc
	global_store_dword v[114:115], v116, off offset:2048
.LBB0_1169:
	s_or_b64 exec, exec, s[42:43]
	v_mul_f32_e32 v119, v23, v23
	v_mul_f32_e32 v120, v25, v25
	v_mul_f32_e32 v114, v31, v31
	s_waitcnt lgkmcnt(0)
	v_mul_f32_e32 v115, v33, v33
	v_fmac_f32_e32 v119, v22, v22
	v_fmac_f32_e32 v120, v24, v24
	v_fmac_f32_e32 v114, v30, v30
	v_fmac_f32_e32 v115, v32, v32
	v_add_f32_e32 v119, v119, v120
	v_mul_f32_e32 v120, v19, v19
	v_add_f32_e32 v114, v114, v115
	v_mul_f32_e32 v115, v27, v27
	v_fmac_f32_e32 v120, v18, v18
	v_fmac_f32_e32 v115, v26, v26
	v_add_f32_e32 v119, v119, v120
	v_mul_f32_e32 v120, v21, v21
	v_add_f32_e32 v114, v114, v115
	v_mul_f32_e32 v115, v29, v29
	v_fmac_f32_e32 v120, v20, v20
	v_fmac_f32_e32 v115, v28, v28
	v_cvt_pk_bf16_f32 v116, v32, v33
	v_add_f32_e32 v119, v120, v119
	v_cvt_pk_bf16_f32 v120, v24, v25
	s_lshl_b64 s[42:43], s[58:59], 12
	v_readlane_b32 s9, v249, 28
	v_add_f32_e32 v114, v115, v114
	v_cvt_pk_bf16_f32 v117, v26, v27
	v_cvt_pk_bf16_f32 v121, v18, v19
	s_add_u32 s9, s9, s42
	v_readlane_b32 s17, v253, 5
	v_cndmask_b32_e64 v123, v116, v120, s[52:53]
	v_mov_b32_e32 v128, v131
	v_cvt_pk_bf16_f32 v115, v30, v31
	v_cvt_pk_bf16_f32 v118, v28, v29
	v_add_f32_e32 v126, v114, v119
	v_cvt_pk_bf16_f32 v119, v22, v23
	v_cvt_pk_bf16_f32 v122, v20, v21
	s_addc_u32 s17, s17, s43
	v_cndmask_b32_e64 v124, v117, v121, s[52:53]
	v_mov_b32_dpp v128, v123 row_ror:8 row_mask:0xf bank_mask:0xf
	v_mov_b32_e32 v123, v131
	s_add_u32 s44, s9, s62
	v_cndmask_b32_e64 v114, v115, v119, s[52:53]
	v_cndmask_b32_e64 v125, v118, v122, s[52:53]
	v_mov_b32_e32 v127, v131
	v_mov_b32_dpp v123, v124 row_ror:8 row_mask:0xf bank_mask:0xf
	v_mov_b32_e32 v124, v131
	s_addc_u32 s45, s17, s63
	v_mov_b32_dpp v127, v114 row_ror:8 row_mask:0xf bank_mask:0xf
	v_mov_b32_dpp v124, v125 row_ror:8 row_mask:0xf bank_mask:0xf
	v_cndmask_b32_e64 v114, v127, v115, s[52:53]
	v_cndmask_b32_e64 v115, v128, v116, s[52:53]
	v_cndmask_b32_e64 v116, v123, v117, s[52:53]
	v_cndmask_b32_e64 v117, v124, v118, s[52:53]
	v_cndmask_b32_e64 v118, v119, v127, s[52:53]
	v_cndmask_b32_e64 v119, v120, v128, s[52:53]
	v_cndmask_b32_e64 v120, v121, v123, s[52:53]
	v_cndmask_b32_e64 v121, v122, v124, s[52:53]
	v_lshl_add_u64 v[122:123], s[44:45], 0, v[130:131]
	v_mov_b32_e32 v153, v131
	v_lshl_add_u64 v[122:123], v[122:123], 0, v[152:153]
	v_mov_b32_e32 v151, v131
	v_lshl_add_u64 v[122:123], v[122:123], 0, v[150:151]
	s_mov_b32 s9, 0xa0000
	v_add_co_u32_e32 v124, vcc, s9, v122
	s_nop 1
	v_addc_co_u32_e32 v125, vcc, 0, v123, vcc
	global_store_dwordx4 v[124:125], v[114:117], off
	s_nop 1
	v_add_co_u32_e32 v114, vcc, 0xa8000, v122
	s_nop 1
	v_addc_co_u32_e32 v115, vcc, 0, v123, vcc
	global_store_dwordx4 v[114:115], v[118:121], off
	ds_bpermute_b32 v114, v165, v126
	s_waitcnt lgkmcnt(0)
	v_add_f32_e32 v114, v126, v114
	ds_bpermute_b32 v115, v164, v114
	s_and_saveexec_b64 s[82:83], s[54:55]
	s_cbranch_execz .LBB0_1171
	v_readlane_b32 s60, v253, 6
	s_waitcnt lgkmcnt(0)
	v_add_f32_e32 v116, v114, v115
	v_lshlrev_b64 v[114:115], 7, v[154:155]
	s_lshl_b32 s44, s38, 2
	v_readlane_b32 s61, v253, 7
	s_ashr_i32 s45, s44, 31
	s_nop 0
	v_lshl_add_u64 v[114:115], s[60:61], 0, v[114:115]
	v_lshl_add_u64 v[114:115], s[44:45], 2, v[114:115]
	s_lshl_b32 s44, s25, 2
	s_mov_b32 s45, s81
	v_lshl_add_u64 v[114:115], v[114:115], 0, s[44:45]
	v_add_co_u32_e32 v114, vcc, 0x5000, v114
	s_nop 1
	v_addc_co_u32_e32 v115, vcc, 0, v115, vcc
	global_store_dword v[114:115], v116, off
; __device__ __forceinline__ u32x4 pack8(f32x4 a, f32x4 b) { u32x4 w; w.x = cvtpk(a[0], a[1]); w.y = cvtpk(a[2], a[3]); w.z = cvtpk(b[0], b[1]); w.w = cvtpk(b[2], b[3]); return w; }
; __device__ __forceinline__ unsigned dpp_ror8(unsigned v) { return (unsigned)__builtin_amdgcn_update_dpp(0, (int)v, 0x128, 0xF, 0xF, false); }
; __device__ __forceinline__ void store_pair(bf16_t* grp  , size_t ld, int fr, int fq, u32x4 P0, u32x4 P1) {
;     const bool up = (fr & 8) != 0;
;     u32x4 snd, rcv;
;     snd.x = up ? P0.x : P1.x; snd.y = up ? P0.y : P1.y; snd.z = up ? P0.z : P1.z; snd.w = up ? P0.w : P1.w;
;     rcv.x = dpp_ror8(snd.x); rcv.y = dpp_ror8(snd.y); rcv.z = dpp_ror8(snd.z); rcv.w = dpp_ror8(snd.w);
;     u32x4 dA, dB;
;     dA.x = up ? rcv.x : P0.x; dA.y = up ? rcv.y : P0.y; dA.z = up ? rcv.z : P0.z; dA.w = up ? rcv.w : P0.w;
;     dB.x = up ? P1.x : rcv.x; dB.y = up ? P1.y : rcv.y; dB.z = up ? P1.z : rcv.z; dB.w = up ? P1.w : rcv.w;
;     bf16_t* p = grp + (size_t)(fr & 7) * ld + (up ? CBJ : 0) + 8 * fq;
;     __builtin_nontemporal_store(dA, (u32x4*)p); __builtin_nontemporal_store(dB, (u32x4*)(p + 8 * ld));
;     __device__ __forceinline__ void operator()(f32x4 (&acc)[2][2][4][2], const Unit& u, int wr, int wc, int fr, int fq) const {
;     ...
;         for (int ai = 0; ai < 2; ++ai)
; #pragma unroll
;             for (int m = 0; m < 4; ++m) {
;                 const int row = row0 + ai * HALF + m * 16;
;                 float s = 0.f; u32x4 pk[2];
; #pragma unroll
;                 for (int bj = 0; bj < 2; ++bj) {
;                     const f32x4 v0 = acc[ai][bj][m][0], v1 = acc[ai][bj][m][1];
;                     s += (v0[0] * v0[0] + v0[1] * v0[1]) + (v0[2] * v0[2] + v0[3] * v0[3]) + (v1[0] * v1[0] + v1[1] * v1[1]) + (v1[2] * v1[2] + v1[3] * v1[3]);
;                     pk[bj] = pack8(v0, v1);
;                 }
;                 store_pair(Y + (size_t)(rowg + ai * HALF + m * 16) * DM + colw, DM, fr, fq, pk[0], pk[1]);
;                 s += __shfl_xor(s, 16); s += __shfl_xor(s, 32);
;                 if (fq == 0) ssy[(size_t)row * 32 + u.pn * 4 + wc] = s;
.LBB0_1171:
	s_or_b64 exec, exec, s[82:83]
	v_mul_f32_e32 v119, v7, v7
	v_mul_f32_e32 v120, v9, v9
	v_mul_f32_e32 v114, v15, v15
	s_waitcnt lgkmcnt(0)
	v_mul_f32_e32 v115, v17, v17
	v_fmac_f32_e32 v119, v6, v6
	v_fmac_f32_e32 v120, v8, v8
	v_fmac_f32_e32 v114, v14, v14
	v_fmac_f32_e32 v115, v16, v16
	v_add_f32_e32 v119, v119, v120
	v_mul_f32_e32 v120, v3, v3
	v_add_f32_e32 v114, v114, v115
	v_mul_f32_e32 v115, v11, v11
	v_fmac_f32_e32 v120, v2, v2
	v_fmac_f32_e32 v115, v10, v10
	v_add_f32_e32 v119, v119, v120
	v_mul_f32_e32 v120, v5, v5
	v_add_f32_e32 v114, v114, v115
	v_mul_f32_e32 v115, v13, v13
	v_fmac_f32_e32 v120, v4, v4
	v_fmac_f32_e32 v115, v12, v12
	v_cvt_pk_bf16_f32 v116, v16, v17
	v_add_f32_e32 v119, v120, v119
	v_cvt_pk_bf16_f32 v120, v8, v9
	v_readlane_b32 s9, v249, 28
	v_add_f32_e32 v114, v115, v114
	v_cvt_pk_bf16_f32 v117, v10, v11
	v_cvt_pk_bf16_f32 v121, v2, v3
	s_add_u32 s9, s9, s42
	v_readlane_b32 s17, v253, 5
	v_cndmask_b32_e64 v123, v116, v120, s[52:53]
	v_mov_b32_e32 v128, v131
	v_cvt_pk_bf16_f32 v115, v14, v15
	v_cvt_pk_bf16_f32 v118, v12, v13
	v_add_f32_e32 v126, v114, v119
	v_cvt_pk_bf16_f32 v119, v6, v7
	v_cvt_pk_bf16_f32 v122, v4, v5
	s_addc_u32 s17, s17, s43
	v_cndmask_b32_e64 v124, v117, v121, s[52:53]
	v_mov_b32_dpp v128, v123 row_ror:8 row_mask:0xf bank_mask:0xf
	v_mov_b32_e32 v123, v131
	s_add_u32 s42, s9, s62
	v_cndmask_b32_e64 v114, v115, v119, s[52:53]
	v_cndmask_b32_e64 v125, v118, v122, s[52:53]
	v_mov_b32_e32 v127, v131
	v_mov_b32_dpp v123, v124 row_ror:8 row_mask:0xf bank_mask:0xf
	v_mov_b32_e32 v124, v131
	s_addc_u32 s43, s17, s63
	v_mov_b32_dpp v127, v114 row_ror:8 row_mask:0xf bank_mask:0xf
	v_mov_b32_dpp v124, v125 row_ror:8 row_mask:0xf bank_mask:0xf
	v_cndmask_b32_e64 v114, v127, v115, s[52:53]
	v_cndmask_b32_e64 v115, v128, v116, s[52:53]
	v_cndmask_b32_e64 v116, v123, v117, s[52:53]
	v_cndmask_b32_e64 v117, v124, v118, s[52:53]
	v_cndmask_b32_e64 v118, v119, v127, s[52:53]
	v_cndmask_b32_e64 v119, v120, v128, s[52:53]
	v_cndmask_b32_e64 v120, v121, v123, s[52:53]
	v_cndmask_b32_e64 v121, v122, v124, s[52:53]
	v_lshl_add_u64 v[122:123], s[42:43], 0, v[130:131]
	ds_bpermute_b32 v127, v165, v126
	v_lshl_add_u64 v[122:123], v[122:123], 0, v[152:153]
	v_lshl_add_u64 v[122:123], v[122:123], 0, v[150:151]
	s_mov_b32 s9, 0xb0000
	v_add_co_u32_e32 v124, vcc, s9, v122
	s_nop 1
	v_addc_co_u32_e32 v125, vcc, 0, v123, vcc
	global_store_dwordx4 v[124:125], v[114:117], off
	s_waitcnt lgkmcnt(0)
	s_nop 0
	v_add_f32_e32 v114, v126, v127
	ds_bpermute_b32 v115, v164, v114
	v_add_co_u32_e32 v116, vcc, 0xb8000, v122
	s_nop 1
	v_addc_co_u32_e32 v117, vcc, 0, v123, vcc
	global_store_dwordx4 v[116:117], v[118:121], off
	s_and_saveexec_b64 s[42:43], s[54:55]
	s_cbranch_execz .LBB0_1173
	v_readlane_b32 s44, v253, 6
	s_waitcnt lgkmcnt(0)
	v_add_f32_e32 v116, v114, v115
	v_lshlrev_b64 v[114:115], 7, v[154:155]
	s_lshl_b32 s38, s38, 2
	v_readlane_b32 s45, v253, 7
	s_ashr_i32 s39, s38, 31
	s_nop 0
	v_lshl_add_u64 v[114:115], s[44:45], 0, v[114:115]
	v_lshl_add_u64 v[114:115], s[38:39], 2, v[114:115]
	s_lshl_b32 s38, s25, 2
	s_mov_b32 s39, s81
	v_lshl_add_u64 v[114:115], v[114:115], 0, s[38:39]
	v_add_co_u32_e32 v114, vcc, 0x5000, v114
	s_nop 1
	v_addc_co_u32_e32 v115, vcc, 0, v115, vcc
	global_store_dword v[114:115], v116, off offset:2048

; __device__ __forceinline__ u32x4 pack8(f32x4 a, f32x4 b) { u32x4 w; w.x = cvtpk(a[0], a[1]); w.y = cvtpk(a[2], a[3]); w.z = cvtpk(b[0], b[1]); w.w = cvtpk(b[2], b[3]); return w; }
; __device__ __forceinline__ unsigned dpp_ror8(unsigned v) { return (unsigned)__builtin_amdgcn_update_dpp(0, (int)v, 0x128, 0xF, 0xF, false); }
; __device__ __forceinline__ void store_pair(bf16_t* grp  , size_t ld, int fr, int fq, u32x4 P0, u32x4 P1) {
;     const bool up = (fr & 8) != 0;
;     u32x4 snd, rcv;
;     snd.x = up ? P0.x : P1.x; snd.y = up ? P0.y : P1.y; snd.z = up ? P0.z : P1.z; snd.w = up ? P0.w : P1.w;
;     rcv.x = dpp_ror8(snd.x); rcv.y = dpp_ror8(snd.y); rcv.z = dpp_ror8(snd.z); rcv.w = dpp_ror8(snd.w);
;     u32x4 dA, dB;
;     dA.x = up ? rcv.x : P0.x; dA.y = up ? rcv.y : P0.y; dA.z = up ? rcv.z : P0.z; dA.w = up ? rcv.w : P0.w;
;     dB.x = up ? P1.x : rcv.x; dB.y = up ? P1.y : rcv.y; dB.z = up ? P1.z : rcv.z; dB.w = up ? P1.w : rcv.w;
;     bf16_t* p = grp + (size_t)(fr & 7) * ld + (up ? CBJ : 0) + 8 * fq;
;     __builtin_nontemporal_store(dA, (u32x4*)p); __builtin_nontemporal_store(dB, (u32x4*)(p + 8 * ld));
;     __device__ __forceinline__ void operator()(f32x4 (&acc)[2][2][4][2], const Unit& u, int wr, int wc, int fr, int fq) const {
;     ...
;         if (u.ks >= 0) {
;             bf16_t* base = (bf16_t*)yp + ((size_t)u.ks * MS + (rowg - MP)) * DM + colw;
; #pragma unroll
;             for (int ai = 0; ai < 2; ++ai)
; #pragma unroll
;                 for (int m = 0; m < 4; ++m)
;                     store_pair(base + (size_t)(ai * HALF + m * 16) * DM, DM, fr, fq, pack8(acc[ai][0][m][0], acc[ai][0][m][1]), pack8(acc[ai][1][m][0], acc[ai][1][m][1]));
;             return;
.LBB0_1175:
	s_and_b64 vcc, exec, s[42:43]
	s_cbranch_vccz .LBB0_1174
	s_ashr_i32 s59, s58, 31
	s_lshl_b64 s[38:39], s[58:59], 12
	s_lshl_b64 s[42:43], s[80:81], 22
	s_add_u32 s9, s33, s42
	s_addc_u32 s17, s15, s43
	s_add_u32 s9, s9, s38
	s_addc_u32 s17, s17, s39
	s_ashr_i32 s41, s40, 31
	s_lshl_b64 s[38:39], s[40:41], 1
	s_add_u32 s38, s9, s38
	s_addc_u32 s39, s17, s39
	s_waitcnt lgkmcnt(0)
	v_lshl_add_u64 v[114:115], s[38:39], 0, v[130:131]
	v_mov_b32_e32 v153, v131
	v_lshl_add_u64 v[114:115], v[114:115], 0, v[152:153]
	v_mov_b32_e32 v151, v131
	v_lshl_add_u64 v[114:115], v[114:115], 0, v[150:151]
	v_cndmask_b32_e64 v116, v160, v156, s[52:53]
	v_cndmask_b32_e64 v117, v161, v157, s[52:53]
	v_cndmask_b32_e64 v118, v162, v158, s[52:53]
	v_cndmask_b32_e64 v119, v163, v159, s[52:53]
	v_mov_b32_e32 v120, v131
	v_mov_b32_e32 v121, v131
	v_mov_b32_e32 v122, v131
	v_mov_b32_e32 v123, v131
	s_brev_b32 s9, 63
	v_mov_b32_dpp v120, v116 row_ror:8 row_mask:0xf bank_mask:0xf
	v_mov_b32_dpp v121, v117 row_ror:8 row_mask:0xf bank_mask:0xf
	v_mov_b32_dpp v122, v118 row_ror:8 row_mask:0xf bank_mask:0xf
	v_mov_b32_dpp v123, v119 row_ror:8 row_mask:0xf bank_mask:0xf
	v_add_co_u32_e32 v124, vcc, s9, v114
	v_cndmask_b32_e64 v116, v120, v160, s[52:53]
	v_cndmask_b32_e64 v117, v121, v161, s[52:53]
	v_cndmask_b32_e64 v118, v122, v162, s[52:53]
	v_cndmask_b32_e64 v119, v123, v163, s[52:53]
	v_addc_co_u32_e32 v125, vcc, -1, v115, vcc
	s_mov_b32 s9, 0xfc008000
	v_cvt_pk_bf16_f32 v106, v106, v107
	v_cvt_pk_bf16_f32 v102, v102, v103
	v_cvt_pk_bf16_f32 v103, v104, v105
	v_cvt_pk_bf16_f32 v104, v98, v99
	global_store_dwordx4 v[124:125], v[116:119], off
	v_cvt_pk_bf16_f32 v110, v110, v111
	v_cvt_pk_bf16_f32 v111, v112, v113
	v_add_co_u32_e32 v116, vcc, s9, v114
	v_cvt_pk_bf16_f32 v107, v108, v109
	v_cvt_pk_bf16_f32 v105, v100, v101
	v_cndmask_b32_e64 v100, v106, v104, s[52:53]
	v_mov_b32_e32 v112, v131
	v_addc_co_u32_e32 v117, vcc, -1, v115, vcc
	v_cndmask_b32_e64 v98, v110, v102, s[52:53]
	v_cndmask_b32_e64 v99, v111, v103, s[52:53]
	v_cndmask_b32_e64 v101, v107, v105, s[52:53]
	v_mov_b32_e32 v108, v131
	v_mov_b32_e32 v109, v131
	v_mov_b32_dpp v112, v100 row_ror:8 row_mask:0xf bank_mask:0xf
	v_mov_b32_e32 v113, v131
	s_mov_b32 s9, 0xfc010000
	v_mov_b32_dpp v108, v98 row_ror:8 row_mask:0xf bank_mask:0xf
	v_mov_b32_dpp v109, v99 row_ror:8 row_mask:0xf bank_mask:0xf
	v_mov_b32_dpp v113, v101 row_ror:8 row_mask:0xf bank_mask:0xf
	v_cndmask_b32_e64 v100, v112, v106, s[52:53]
	v_add_co_u32_e32 v106, vcc, s9, v114
	v_cndmask_b32_e64 v98, v108, v110, s[52:53]
	v_cndmask_b32_e64 v99, v109, v111, s[52:53]
	v_cndmask_b32_e64 v101, v113, v107, s[52:53]
	v_addc_co_u32_e32 v107, vcc, -1, v115, vcc
	s_mov_b32 s9, 0xfc018000
	v_cvt_pk_bf16_f32 v90, v90, v91
	v_cvt_pk_bf16_f32 v86, v86, v87
	v_cvt_pk_bf16_f32 v87, v88, v89
	v_cvt_pk_bf16_f32 v88, v82, v83
	global_store_dwordx4 v[106:107], v[98:101], off
	v_cvt_pk_bf16_f32 v94, v94, v95
	v_cvt_pk_bf16_f32 v95, v96, v97
	v_add_co_u32_e32 v98, vcc, s9, v114
	v_cvt_pk_bf16_f32 v91, v92, v93
	v_cvt_pk_bf16_f32 v89, v84, v85
	v_cndmask_b32_e64 v84, v90, v88, s[52:53]
	v_mov_b32_e32 v96, v131
	v_addc_co_u32_e32 v99, vcc, -1, v115, vcc
	v_cndmask_b32_e64 v82, v94, v86, s[52:53]
	v_cndmask_b32_e64 v83, v95, v87, s[52:53]
	v_cndmask_b32_e64 v85, v91, v89, s[52:53]
	v_mov_b32_e32 v92, v131
	v_mov_b32_e32 v93, v131
	v_mov_b32_dpp v96, v84 row_ror:8 row_mask:0xf bank_mask:0xf
	v_mov_b32_e32 v97, v131
	s_mov_b32 s9, 0xfc020000
	v_mov_b32_dpp v92, v82 row_ror:8 row_mask:0xf bank_mask:0xf
	v_mov_b32_dpp v93, v83 row_ror:8 row_mask:0xf bank_mask:0xf
	v_mov_b32_dpp v97, v85 row_ror:8 row_mask:0xf bank_mask:0xf
	v_cndmask_b32_e64 v84, v96, v90, s[52:53]
	v_add_co_u32_e32 v90, vcc, s9, v114
	v_cndmask_b32_e64 v82, v92, v94, s[52:53]
	v_cndmask_b32_e64 v83, v93, v95, s[52:53]
	v_cndmask_b32_e64 v85, v97, v91, s[52:53]
	v_addc_co_u32_e32 v91, vcc, -1, v115, vcc
	s_mov_b32 s9, 0xfc028000
	v_cvt_pk_bf16_f32 v74, v74, v75
	v_cvt_pk_bf16_f32 v70, v70, v71
	v_cvt_pk_bf16_f32 v71, v72, v73
	v_cvt_pk_bf16_f32 v72, v66, v67
	global_store_dwordx4 v[90:91], v[82:85], off
	v_cvt_pk_bf16_f32 v78, v78, v79
	v_cvt_pk_bf16_f32 v79, v80, v81
	v_add_co_u32_e32 v82, vcc, s9, v114
	v_cvt_pk_bf16_f32 v75, v76, v77
	v_cvt_pk_bf16_f32 v73, v68, v69
	v_cndmask_b32_e64 v68, v74, v72, s[52:53]
	v_mov_b32_e32 v80, v131
	v_addc_co_u32_e32 v83, vcc, -1, v115, vcc
	v_cndmask_b32_e64 v66, v78, v70, s[52:53]
	v_cndmask_b32_e64 v67, v79, v71, s[52:53]
	v_cndmask_b32_e64 v69, v75, v73, s[52:53]
	v_mov_b32_e32 v76, v131
	v_mov_b32_e32 v77, v131
	v_mov_b32_dpp v80, v68 row_ror:8 row_mask:0xf bank_mask:0xf
	v_mov_b32_e32 v81, v131
	s_mov_b32 s9, 0xfc030000
	v_mov_b32_dpp v76, v66 row_ror:8 row_mask:0xf bank_mask:0xf
	v_mov_b32_dpp v77, v67 row_ror:8 row_mask:0xf bank_mask:0xf
	v_mov_b32_dpp v81, v69 row_ror:8 row_mask:0xf bank_mask:0xf
	v_cndmask_b32_e64 v68, v80, v74, s[52:53]
	v_add_co_u32_e32 v74, vcc, s9, v114
	v_cndmask_b32_e64 v66, v76, v78, s[52:53]
	v_cndmask_b32_e64 v67, v77, v79, s[52:53]
	v_cndmask_b32_e64 v69, v81, v75, s[52:53]
	v_addc_co_u32_e32 v75, vcc, -1, v115, vcc
	s_mov_b32 s9, 0xfc038000
	v_cvt_pk_bf16_f32 v58, v58, v59
	v_cvt_pk_bf16_f32 v54, v54, v55
	v_cvt_pk_bf16_f32 v55, v56, v57
	v_cvt_pk_bf16_f32 v56, v50, v51
	global_store_dwordx4 v[74:75], v[66:69], off
	v_cvt_pk_bf16_f32 v62, v62, v63
	v_cvt_pk_bf16_f32 v63, v64, v65
	v_add_co_u32_e32 v66, vcc, s9, v114
	v_cvt_pk_bf16_f32 v59, v60, v61
	v_cvt_pk_bf16_f32 v57, v52, v53
	v_cndmask_b32_e64 v52, v58, v56, s[52:53]
	v_mov_b32_e32 v64, v131
	v_addc_co_u32_e32 v67, vcc, -1, v115, vcc
	v_cndmask_b32_e64 v50, v62, v54, s[52:53]
; __device__ __forceinline__ u32x4 pack8(f32x4 a, f32x4 b) { u32x4 w; w.x = cvtpk(a[0], a[1]); w.y = cvtpk(a[2], a[3]); w.z = cvtpk(b[0], b[1]); w.w = cvtpk(b[2], b[3]); return w; }
; __device__ __forceinline__ unsigned dpp_ror8(unsigned v) { return (unsigned)__builtin_amdgcn_update_dpp(0, (int)v, 0x128, 0xF, 0xF, false); }
; __device__ __forceinline__ void store_pair(bf16_t* grp  , size_t ld, int fr, int fq, u32x4 P0, u32x4 P1) {
;     const bool up = (fr & 8) != 0;
;     u32x4 snd, rcv;
;     snd.x = up ? P0.x : P1.x; snd.y = up ? P0.y : P1.y; snd.z = up ? P0.z : P1.z; snd.w = up ? P0.w : P1.w;
;     rcv.x = dpp_ror8(snd.x); rcv.y = dpp_ror8(snd.y); rcv.z = dpp_ror8(snd.z); rcv.w = dpp_ror8(snd.w);
;     u32x4 dA, dB;
;     dA.x = up ? rcv.x : P0.x; dA.y = up ? rcv.y : P0.y; dA.z = up ? rcv.z : P0.z; dA.w = up ? rcv.w : P0.w;
;     dB.x = up ? P1.x : rcv.x; dB.y = up ? P1.y : rcv.y; dB.z = up ? P1.z : rcv.z; dB.w = up ? P1.w : rcv.w;
;     bf16_t* p = grp + (size_t)(fr & 7) * ld + (up ? CBJ : 0) + 8 * fq;
;     __builtin_nontemporal_store(dA, (u32x4*)p); __builtin_nontemporal_store(dB, (u32x4*)(p + 8 * ld));
;     __device__ __forceinline__ void operator()(f32x4 (&acc)[2][2][4][2], const Unit& u, int wr, int wc, int fr, int fq) const {
;     ...
;         if (u.ks >= 0) {
;             bf16_t* base = (bf16_t*)yp + ((size_t)u.ks * MS + (rowg - MP)) * DM + colw;
; #pragma unroll
;             for (int ai = 0; ai < 2; ++ai)
; #pragma unroll
;                 for (int m = 0; m < 4; ++m)
;                     store_pair(base + (size_t)(ai * HALF + m * 16) * DM, DM, fr, fq, pack8(acc[ai][0][m][0], acc[ai][0][m][1]), pack8(acc[ai][1][m][0], acc[ai][1][m][1]));
;             return;
	v_cndmask_b32_e64 v51, v63, v55, s[52:53]
	v_cndmask_b32_e64 v53, v59, v57, s[52:53]
	v_mov_b32_e32 v60, v131
	v_mov_b32_e32 v61, v131
	v_mov_b32_dpp v64, v52 row_ror:8 row_mask:0xf bank_mask:0xf
	v_mov_b32_e32 v65, v131
	s_mov_b32 s9, 0xfc080000
	v_mov_b32_dpp v60, v50 row_ror:8 row_mask:0xf bank_mask:0xf
	v_mov_b32_dpp v61, v51 row_ror:8 row_mask:0xf bank_mask:0xf
	v_mov_b32_dpp v65, v53 row_ror:8 row_mask:0xf bank_mask:0xf
	v_cndmask_b32_e64 v52, v64, v58, s[52:53]
	v_add_co_u32_e32 v58, vcc, s9, v114
	v_cndmask_b32_e64 v50, v60, v62, s[52:53]
	v_cndmask_b32_e64 v51, v61, v63, s[52:53]
	v_cndmask_b32_e64 v53, v65, v59, s[52:53]
	v_addc_co_u32_e32 v59, vcc, -1, v115, vcc
	s_mov_b32 s9, 0xfc088000
	v_cvt_pk_bf16_f32 v42, v42, v43
	v_cvt_pk_bf16_f32 v38, v38, v39
	v_cvt_pk_bf16_f32 v39, v40, v41
	v_cvt_pk_bf16_f32 v40, v34, v35
	global_store_dwordx4 v[58:59], v[50:53], off
	v_cvt_pk_bf16_f32 v46, v46, v47
	v_cvt_pk_bf16_f32 v47, v48, v49
	v_add_co_u32_e32 v50, vcc, s9, v114
	v_cvt_pk_bf16_f32 v43, v44, v45
	v_cvt_pk_bf16_f32 v41, v36, v37
	v_cndmask_b32_e64 v36, v42, v40, s[52:53]
	v_mov_b32_e32 v48, v131
	v_addc_co_u32_e32 v51, vcc, -1, v115, vcc
	v_cndmask_b32_e64 v34, v46, v38, s[52:53]
	v_cndmask_b32_e64 v35, v47, v39, s[52:53]
	v_cndmask_b32_e64 v37, v43, v41, s[52:53]
	v_mov_b32_e32 v44, v131
	v_mov_b32_e32 v45, v131
	v_mov_b32_dpp v48, v36 row_ror:8 row_mask:0xf bank_mask:0xf
	v_mov_b32_e32 v49, v131
	s_mov_b32 s9, 0xfc090000
	v_mov_b32_dpp v44, v34 row_ror:8 row_mask:0xf bank_mask:0xf
	v_mov_b32_dpp v45, v35 row_ror:8 row_mask:0xf bank_mask:0xf
	v_mov_b32_dpp v49, v37 row_ror:8 row_mask:0xf bank_mask:0xf
	v_cndmask_b32_e64 v36, v48, v42, s[52:53]
	v_add_co_u32_e32 v42, vcc, s9, v114
	v_cndmask_b32_e64 v34, v44, v46, s[52:53]
	v_cndmask_b32_e64 v35, v45, v47, s[52:53]
	v_cndmask_b32_e64 v37, v49, v43, s[52:53]
	v_addc_co_u32_e32 v43, vcc, -1, v115, vcc
	s_mov_b32 s9, 0xfc098000
	v_cvt_pk_bf16_f32 v26, v26, v27
	v_cvt_pk_bf16_f32 v22, v22, v23
	v_cvt_pk_bf16_f32 v23, v24, v25
	v_cvt_pk_bf16_f32 v24, v18, v19
	global_store_dwordx4 v[42:43], v[34:37], off
	v_cvt_pk_bf16_f32 v30, v30, v31
	v_cvt_pk_bf16_f32 v31, v32, v33
	v_add_co_u32_e32 v34, vcc, s9, v114
	v_cvt_pk_bf16_f32 v27, v28, v29
	v_cvt_pk_bf16_f32 v25, v20, v21
	v_cndmask_b32_e64 v20, v26, v24, s[52:53]
	v_mov_b32_e32 v32, v131
	v_addc_co_u32_e32 v35, vcc, -1, v115, vcc
	v_cndmask_b32_e64 v18, v30, v22, s[52:53]
	v_cndmask_b32_e64 v19, v31, v23, s[52:53]
	v_cndmask_b32_e64 v21, v27, v25, s[52:53]
	v_mov_b32_e32 v28, v131
	v_mov_b32_e32 v29, v131
	v_mov_b32_dpp v32, v20 row_ror:8 row_mask:0xf bank_mask:0xf
	v_mov_b32_e32 v33, v131
	s_mov_b32 s9, 0xfc0a0000
	v_mov_b32_dpp v28, v18 row_ror:8 row_mask:0xf bank_mask:0xf
	v_mov_b32_dpp v29, v19 row_ror:8 row_mask:0xf bank_mask:0xf
	v_mov_b32_dpp v33, v21 row_ror:8 row_mask:0xf bank_mask:0xf
	v_cndmask_b32_e64 v20, v32, v26, s[52:53]
	v_add_co_u32_e32 v26, vcc, s9, v114
	v_cndmask_b32_e64 v18, v28, v30, s[52:53]
	v_cndmask_b32_e64 v19, v29, v31, s[52:53]
	v_cndmask_b32_e64 v21, v33, v27, s[52:53]
	v_addc_co_u32_e32 v27, vcc, -1, v115, vcc
	s_mov_b32 s9, 0xfc0a8000
	v_cvt_pk_bf16_f32 v10, v10, v11
	v_cvt_pk_bf16_f32 v6, v6, v7
	v_cvt_pk_bf16_f32 v7, v8, v9
	v_cvt_pk_bf16_f32 v8, v2, v3
	global_store_dwordx4 v[26:27], v[18:21], off
	v_cvt_pk_bf16_f32 v14, v14, v15
	v_cvt_pk_bf16_f32 v15, v16, v17
	v_add_co_u32_e32 v18, vcc, s9, v114
	v_cvt_pk_bf16_f32 v11, v12, v13
	v_cvt_pk_bf16_f32 v9, v4, v5
	v_cndmask_b32_e64 v4, v10, v8, s[52:53]
	v_mov_b32_e32 v16, v131
	v_addc_co_u32_e32 v19, vcc, -1, v115, vcc
	v_cndmask_b32_e64 v2, v14, v6, s[52:53]
	v_cndmask_b32_e64 v3, v15, v7, s[52:53]
	v_cndmask_b32_e64 v5, v11, v9, s[52:53]
	v_mov_b32_e32 v12, v131
	v_mov_b32_e32 v13, v131
	v_mov_b32_dpp v16, v4 row_ror:8 row_mask:0xf bank_mask:0xf
	v_mov_b32_e32 v17, v131
	v_mov_b32_dpp v12, v2 row_ror:8 row_mask:0xf bank_mask:0xf
	v_mov_b32_dpp v13, v3 row_ror:8 row_mask:0xf bank_mask:0xf
	v_mov_b32_dpp v17, v5 row_ror:8 row_mask:0xf bank_mask:0xf
	v_cndmask_b32_e64 v4, v16, v10, s[52:53]
	v_add_co_u32_e32 v10, vcc, 0xfc0b0000, v114
	v_cndmask_b32_e64 v2, v12, v14, s[52:53]
	v_cndmask_b32_e64 v3, v13, v15, s[52:53]
	v_cndmask_b32_e64 v5, v17, v11, s[52:53]
	v_addc_co_u32_e32 v11, vcc, -1, v115, vcc
	global_store_dwordx4 v[10:11], v[2:5], off
	v_cndmask_b32_e64 v120, v156, v120, s[52:53]
	v_cndmask_b32_e64 v121, v157, v121, s[52:53]
	v_add_co_u32_e32 v2, vcc, 0xfc0b8000, v114
	v_cndmask_b32_e64 v122, v158, v122, s[52:53]
	v_cndmask_b32_e64 v123, v159, v123, s[52:53]
	v_cndmask_b32_e64 v102, v102, v108, s[52:53]
	v_cndmask_b32_e64 v103, v103, v109, s[52:53]
	v_cndmask_b32_e64 v104, v104, v112, s[52:53]
	v_cndmask_b32_e64 v105, v105, v113, s[52:53]
	v_cndmask_b32_e64 v86, v86, v92, s[52:53]
	v_cndmask_b32_e64 v87, v87, v93, s[52:53]
	v_cndmask_b32_e64 v88, v88, v96, s[52:53]
	v_cndmask_b32_e64 v89, v89, v97, s[52:53]
	v_cndmask_b32_e64 v70, v70, v76, s[52:53]
	v_cndmask_b32_e64 v71, v71, v77, s[52:53]
	v_cndmask_b32_e64 v72, v72, v80, s[52:53]
	v_cndmask_b32_e64 v73, v73, v81, s[52:53]
	v_cndmask_b32_e64 v54, v54, v60, s[52:53]
	v_cndmask_b32_e64 v55, v55, v61, s[52:53]
	v_cndmask_b32_e64 v56, v56, v64, s[52:53]
	v_cndmask_b32_e64 v57, v57, v65, s[52:53]
	v_cndmask_b32_e64 v38, v38, v44, s[52:53]
	v_cndmask_b32_e64 v39, v39, v45, s[52:53]
	v_cndmask_b32_e64 v40, v40, v48, s[52:53]
	v_cndmask_b32_e64 v41, v41, v49, s[52:53]
	v_cndmask_b32_e64 v22, v22, v28, s[52:53]
	v_cndmask_b32_e64 v23, v23, v29, s[52:53]
	v_cndmask_b32_e64 v24, v24, v32, s[52:53]
	v_cndmask_b32_e64 v25, v25, v33, s[52:53]
	v_cndmask_b32_e64 v6, v6, v12, s[52:53]
	v_cndmask_b32_e64 v7, v7, v13, s[52:53]
	v_cndmask_b32_e64 v8, v8, v16, s[52:53]
	v_cndmask_b32_e64 v9, v9, v17, s[52:53]
	v_addc_co_u32_e32 v3, vcc, -1, v115, vcc
	global_store_dwordx4 v[116:117], v[120:123], off
	global_store_dwordx4 v[98:99], v[102:105], off
	global_store_dwordx4 v[82:83], v[86:89], off
	global_store_dwordx4 v[66:67], v[70:73], off
	global_store_dwordx4 v[50:51], v[54:57], off
	global_store_dwordx4 v[34:35], v[38:41], off
	global_store_dwordx4 v[18:19], v[22:25], off
	global_store_dwordx4 v[2:3], v[6:9], off
	s_andn2_b64 vcc, exec, s[56:57]
	s_mov_b64 s[40:41], -1
	s_cbranch_vccnz .LBB0_1147

; __device__ __forceinline__ u32x4 pack8(f32x4 a, f32x4 b) { u32x4 w; w.x = cvtpk(a[0], a[1]); w.y = cvtpk(a[2], a[3]); w.z = cvtpk(b[0], b[1]); w.w = cvtpk(b[2], b[3]); return w; }
;     __device__ __forceinline__ void operator()(f32x4 (&acc)[2][2][4][2], const Unit& u, int wr, int wc, int fr, int fq) const {
;         const int rowg = u.pm * BM + wr * 64, colw = u.pn * BM + wc * 64, row0 = rowg + fr, col0 = colw + 8 * fq;
;         u32x4 cv[4]; v4i_t ov[4];
; #pragma unroll
;         for (int k = 0; k < 4; ++k) { cv[k] = *(const u32x4*)(cmax + col0 + (k >> 1) * CBJ + (k & 1) * 4); ov[k] = *(const v4i_t*)(csum + (u.ks < 0 ? 0 : (1 + u.ks) * DM) + col0 + (k >> 1) * CBJ + (k & 1) * 4); }
;         float rv[8];
; #pragma unroll
;         for (int k = 0; k < 8; ++k) rv[k] = __uint_as_float(rmax[row0 + (k >> 2) * HALF + (k & 3) * 16]) * (1.0f / (255.0f * 127.0f));
; #pragma unroll
;         for (int ai = 0; ai < 2; ++ai)
; #pragma unroll
;             for (int m = 0; m < 4; ++m) {
;                 const int row = row0 + ai * HALF + m * 16;
;                 const float sr = rv[ai * 4 + m];
;                 float s = 0.f; u32x4 pk[2];
; #pragma unroll
;                 for (int bj = 0; bj < 2; ++bj) {
;                     const v4i_t i0 = __builtin_bit_cast(v4i_t, acc[ai][bj][m][0]) + ov[bj * 2], i1 = __builtin_bit_cast(v4i_t, acc[ai][bj][m][1]) + ov[bj * 2 + 1];
;                     const u32x4 c0_ = cv[bj * 2], c1_ = cv[bj * 2 + 1];
;                     f32x4 v0, v1;
; #pragma unroll
;                     for (int j = 0; j < 4; ++j) { v0[j] = (float)i0[j] * (sr * __uint_as_float(c0_[j])); v1[j] = (float)i1[j] * (sr * __uint_as_float(c1_[j])); }
;                     s += (v0[0] * v0[0] + v0[1] * v0[1]) + (v0[2] * v0[2] + v0[3] * v0[3]) + (v1[0] * v1[0] + v1[1] * v1[1]) + (v1[2] * v1[2] + v1[3] * v1[3]);
;                     pk[bj] = pack8(v0, v1);
.LBB0_1577:
	s_mov_b32 s0, s81
	s_lshl_b32 s0, s21, 8
	s_or_b32 s82, s0, s49
	s_lshl_b32 s0, s62, 11
	s_addk_i32 s0, 0x800
	s_cmp_lt_i32 s62, 0
	s_cselect_b64 s[42:43], -1, 0
	s_and_b64 vcc, s[42:43], exec
	s_cselect_b32 s80, 0, s0
	v_or_b32_e32 v50, s82, v172
	s_lshl_b64 s[0:1], s[80:81], 2
	v_ashrrev_i32_e32 v51, 31, v50
	s_add_u32 s0, s24, s0
	v_lshlrev_b64 v[50:51], 2, v[50:51]
	s_addc_u32 s1, s25, s1
	v_lshl_add_u64 v[74:75], s[0:1], 0, v[50:51]
	s_lshl_b32 s0, s14, 8
	s_add_i32 s0, s0, s39
	v_or_b32_e32 v182, s0, v173
	v_ashrrev_i32_e32 v183, 31, v182
	v_lshl_add_u64 v[54:55], s[16:17], 0, v[50:51]
	v_lshl_add_u64 v[184:185], v[182:183], 2, s[8:9]
	global_load_dwordx4 v[62:65], v[54:55], off offset:16
	global_load_dwordx4 v[66:69], v[54:55], off
	global_load_dwordx4 v[70:73], v[74:75], off offset:16
	global_load_dwordx4 v[78:81], v[74:75], off
	global_load_dwordx4 v[50:53], v[54:55], off offset:144
	s_nop 0
	global_load_dwordx4 v[54:57], v[54:55], off offset:128
	s_nop 0
	global_load_dwordx4 v[58:61], v[74:75], off offset:144
	s_nop 0
	global_load_dwordx4 v[74:77], v[74:75], off offset:128
	s_ashr_i32 s83, s82, 31
	global_load_dword v130, v[184:185], off
	global_load_dword v194, v[184:185], off offset:64
	global_load_dword v193, v[184:185], off offset:128
	global_load_dword v192, v[184:185], off offset:192
	global_load_dword v191, v[184:185], off offset:512
	global_load_dword v190, v[184:185], off offset:576
	global_load_dword v189, v[184:185], off offset:640
	global_load_dword v188, v[184:185], off offset:704
	s_mov_b64 s[56:57], -1
	v_readlane_b32 s97, v249, 8
	s_mov_b32 s46, 0x8000
	s_waitcnt vmcnt(0)
	v_add_u32_e32 v156, v70, v156
	v_add_u32_e32 v157, v71, v157
	v_cvt_f32_i32_e32 v157, v157
	v_cvt_f32_i32_e32 v156, v156
	v_add_u32_e32 v160, v78, v160
	v_add_u32_e32 v161, v79, v161
	v_add_u32_e32 v184, v80, v162
	v_mul_f32_e32 v130, 0x38018388, v130
	v_add_u32_e32 v185, v81, v163
	v_cvt_f32_i32_e32 v161, v161
	v_cvt_f32_i32_e32 v160, v160
	v_add_u32_e32 v186, v72, v158
	v_add_u32_e32 v187, v73, v159
	v_pk_mul_f32 v[158:159], v[62:63], v[130:131] op_sel_hi:[1,0]
	v_pk_mul_f32 v[162:163], v[66:67], v[130:131] op_sel_hi:[1,0]
	v_pk_mul_f32 v[156:157], v[158:159], v[156:157]
	v_cvt_f32_i32_e32 v159, v185
	v_cvt_f32_i32_e32 v158, v184
	v_pk_mul_f32 v[160:161], v[162:163], v[160:161]
	v_pk_mul_f32 v[162:163], v[68:69], v[130:131] op_sel_hi:[1,0]
	v_add_u32_e32 v152, v74, v152
	v_pk_mul_f32 v[158:159], v[162:163], v[158:159]
	v_cvt_f32_i32_e32 v163, v187
	v_cvt_f32_i32_e32 v162, v186
	v_add_u32_e32 v153, v75, v153
	v_add_u32_e32 v148, v58, v148
	v_add_u32_e32 v149, v59, v149
	v_cvt_f32_i32_e32 v153, v153
	v_cvt_f32_i32_e32 v152, v152
	v_cvt_f32_i32_e32 v149, v149
	v_cvt_f32_i32_e32 v148, v148
	v_pk_mul_f32 v[184:185], v[64:65], v[130:131] op_sel_hi:[1,0]
	v_add_u32_e32 v186, v60, v150
	v_pk_mul_f32 v[162:163], v[184:185], v[162:163]
	v_add_u32_e32 v184, v76, v154
	v_add_u32_e32 v185, v77, v155
	v_pk_mul_f32 v[154:155], v[54:55], v[130:131] op_sel_hi:[1,0]
	v_add_u32_e32 v187, v61, v151
	v_pk_mul_f32 v[150:151], v[50:51], v[130:131] op_sel_hi:[1,0]
	v_pk_mul_f32 v[152:153], v[154:155], v[152:153]
	v_pk_mul_f32 v[154:155], v[150:151], v[148:149]
	v_cvt_f32_i32_e32 v149, v185
	v_cvt_f32_i32_e32 v148, v184
	v_pk_mul_f32 v[150:151], v[56:57], v[130:131] op_sel_hi:[1,0]
	v_cvt_pk_bf16_f32 v195, v160, v161
	v_cvt_pk_bf16_f32 v196, v158, v159
	v_pk_mul_f32 v[184:185], v[150:151], v[148:149]
	v_cvt_f32_i32_e32 v149, v187
	v_cvt_f32_i32_e32 v148, v186
	v_pk_mul_f32 v[150:151], v[52:53], v[130:131] op_sel_hi:[1,0]
	v_cvt_pk_bf16_f32 v197, v156, v157
	v_cvt_pk_bf16_f32 v198, v162, v163
	v_pk_mul_f32 v[186:187], v[150:151], v[148:149]
	v_cvt_pk_bf16_f32 v199, v152, v153
	v_cvt_pk_bf16_f32 v200, v184, v185
	v_cvt_pk_bf16_f32 v201, v154, v155
	v_cvt_pk_bf16_f32 v202, v186, v187
	v_cndmask_b32_e64 v213, v195, v199, s[52:53]
	v_cndmask_b32_e64 v212, v196, v200, s[52:53]
	v_cndmask_b32_e64 v211, v197, v201, s[52:53]
	v_cndmask_b32_e64 v203, v198, v202, s[52:53]
	v_lshlrev_b32_e32 v130, 1, v174
	v_lshlrev_b32_e32 v150, 1, v176
	v_lshlrev_b32_e32 v148, 1, v172
	s_cbranch_vccz .LBB0_1581
; __device__ __forceinline__ unsigned dpp_ror8(unsigned v) { return (unsigned)__builtin_amdgcn_update_dpp(0, (int)v, 0x128, 0xF, 0xF, false); }
; __device__ __forceinline__ void store_pair(bf16_t* grp  , size_t ld, int fr, int fq, u32x4 P0, u32x4 P1) {
;     const bool up = (fr & 8) != 0;
;     u32x4 snd, rcv;
;     snd.x = up ? P0.x : P1.x; snd.y = up ? P0.y : P1.y; snd.z = up ? P0.z : P1.z; snd.w = up ? P0.w : P1.w;
;     rcv.x = dpp_ror8(snd.x); rcv.y = dpp_ror8(snd.y); rcv.z = dpp_ror8(snd.z); rcv.w = dpp_ror8(snd.w);
;     u32x4 dA, dB;
;     dA.x = up ? rcv.x : P0.x; dA.y = up ? rcv.y : P0.y; dA.z = up ? rcv.z : P0.z; dA.w = up ? rcv.w : P0.w;
;     dB.x = up ? P1.x : rcv.x; dB.y = up ? P1.y : rcv.y; dB.z = up ? P1.z : rcv.z; dB.w = up ? P1.w : rcv.w;
;     bf16_t* p = grp + (size_t)(fr & 7) * ld + (up ? CBJ : 0) + 8 * fq;
;     __builtin_nontemporal_store(dA, (u32x4*)p); __builtin_nontemporal_store(dB, (u32x4*)(p + 8 * ld));
;     __device__ __forceinline__ void operator()(f32x4 (&acc)[2][2][4][2], const Unit& u, int wr, int wc, int fr, int fq) const {
;     ...
;                 }
;                 if (u.ks >= 0) store_pair((bf16_t*)yp + ((size_t)u.ks * MS + (rowg - MP) + ai * HALF + m * 16) * DM + colw, DM, fr, fq, pk[0], pk[1]);
;                 else {
;                     store_pair(Y + (size_t)(rowg + ai * HALF + m * 16) * DM + colw, DM, fr, fq, pk[0], pk[1]);
;                     s += __shfl_xor(s, 16); s += __shfl_xor(s, 32);
;                     if (fq == 0) ssy[(size_t)row * 32 + u.pn * 4 + wc] = s;
;                 }
	v_pk_mul_f32 v[152:153], v[152:153], v[152:153]
	v_pk_mul_f32 v[184:185], v[184:185], v[184:185]
	v_pk_mul_f32 v[154:155], v[154:155], v[154:155]
	v_add_f32_e32 v149, v184, v185
	v_add_f32_e32 v151, v152, v153
	v_pk_mul_f32 v[186:187], v[186:187], v[186:187]
	v_add_f32_e32 v149, v151, v149
	v_add_f32_e32 v151, v154, v155
	v_pk_mul_f32 v[160:161], v[160:161], v[160:161]
	v_pk_mul_f32 v[158:159], v[158:159], v[158:159]
	v_add_f32_e32 v149, v151, v149
	v_add_f32_e32 v151, v186, v187
	v_pk_mul_f32 v[156:157], v[156:157], v[156:157]
	v_add_f32_e32 v149, v151, v149
	v_add_f32_e32 v151, v158, v159
	v_add_f32_e32 v152, v160, v161
	v_pk_mul_f32 v[162:163], v[162:163], v[162:163]
	v_add_f32_e32 v151, v152, v151
	v_add_f32_e32 v152, v156, v157
	v_add_f32_e32 v151, v152, v151
	v_add_f32_e32 v152, v162, v163
	v_add_f32_e32 v151, v152, v151
	v_add_f32_e32 v162, v151, v149
	v_mov_b32_e32 v149, v131
	s_ashr_i32 s1, s0, 31
	v_and_b32_e32 v163, 64, v204
	v_mov_b32_dpp v149, v213 row_ror:8 row_mask:0xf bank_mask:0xf
	s_lshl_b64 s[22:23], s[0:1], 12
	v_readlane_b32 s1, v249, 28
	v_cndmask_b32_e64 v152, v149, v195, s[52:53]
	v_cndmask_b32_e64 v156, v199, v149, s[52:53]
	v_xor_b32_e32 v149, 16, v204
	v_add_u32_e32 v163, 64, v163
	s_add_u32 s1, s1, s22
	v_readlane_b32 s14, v253, 5
	v_cmp_lt_i32_e32 vcc, v149, v163
	s_addc_u32 s14, s14, s23
	s_lshl_b64 s[22:23], s[82:83], 1
	v_cndmask_b32_e32 v149, v204, v149, vcc
	s_add_u32 s22, s1, s22
	v_mov_b32_e32 v151, v131
	v_lshlrev_b32_e32 v149, 2, v149
	s_addc_u32 s23, s14, s23
	v_mov_b32_dpp v151, v212 row_ror:8 row_mask:0xf bank_mask:0xf
	ds_bpermute_b32 v184, v149, v162
	v_cndmask_b32_e64 v153, v151, v196, s[52:53]
	v_cndmask_b32_e64 v157, v200, v151, s[52:53]
	v_lshl_add_u64 v[160:161], s[22:23], 0, v[130:131]
	v_mov_b32_e32 v151, v131
	v_lshl_add_u64 v[160:161], v[160:161], 0, v[150:151]
	v_xor_b32_e32 v151, 32, v204
	v_cmp_lt_i32_e32 vcc, v151, v163
	v_mov_b32_e32 v149, v131
	v_lshl_add_u64 v[160:161], v[160:161], 0, v[148:149]
	v_cndmask_b32_e32 v151, v204, v151, vcc
	s_waitcnt lgkmcnt(0)
	v_add_f32_e32 v149, v162, v184
	v_lshlrev_b32_e32 v151, 2, v151
	v_mov_b32_e32 v158, v131
	v_mov_b32_e32 v159, v131
	ds_bpermute_b32 v151, v151, v149
	v_mov_b32_dpp v158, v211 row_ror:8 row_mask:0xf bank_mask:0xf
	v_mov_b32_dpp v159, v203 row_ror:8 row_mask:0xf bank_mask:0xf
	v_cndmask_b32_e64 v154, v158, v197, s[52:53]
	v_cndmask_b32_e64 v155, v159, v198, s[52:53]
	global_store_dwordx4 v[160:161], v[152:155], off
	v_cndmask_b32_e64 v158, v201, v158, s[52:53]
	v_cndmask_b32_e64 v159, v202, v159, s[52:53]
	v_add_co_u32_e32 v152, vcc, s46, v160
	s_nop 1
	v_addc_co_u32_e32 v153, vcc, 0, v161, vcc
	global_store_dwordx4 v[152:153], v[156:159], off
	s_and_saveexec_b64 s[40:41], s[54:55]
	s_cbranch_execz .LBB0_1580
	v_readlane_b32 s44, v253, 6
	s_lshl_b32 s22, s21, 2
	v_lshlrev_b64 v[152:153], 7, v[182:183]
	v_readlane_b32 s45, v253, 7
	s_ashr_i32 s23, s22, 31
	s_lshl_b32 s80, s38, 2
	v_lshl_add_u64 v[152:153], s[44:45], 0, v[152:153]
	v_lshl_add_u64 v[152:153], s[22:23], 2, v[152:153]
	s_waitcnt lgkmcnt(0)
	v_add_f32_e32 v149, v149, v151
	v_lshl_add_u64 v[152:153], v[152:153], 0, s[80:81]
	global_store_dword v[152:153], v149, off

; __device__ __forceinline__ unsigned dpp_ror8(unsigned v) { return (unsigned)__builtin_amdgcn_update_dpp(0, (int)v, 0x128, 0xF, 0xF, false); }
; __device__ __forceinline__ void store_pair(bf16_t* grp  , size_t ld, int fr, int fq, u32x4 P0, u32x4 P1) {
;     const bool up = (fr & 8) != 0;
;     u32x4 snd, rcv;
;     snd.x = up ? P0.x : P1.x; snd.y = up ? P0.y : P1.y; snd.z = up ? P0.z : P1.z; snd.w = up ? P0.w : P1.w;
;     rcv.x = dpp_ror8(snd.x); rcv.y = dpp_ror8(snd.y); rcv.z = dpp_ror8(snd.z); rcv.w = dpp_ror8(snd.w);
;     u32x4 dA, dB;
;     dA.x = up ? rcv.x : P0.x; dA.y = up ? rcv.y : P0.y; dA.z = up ? rcv.z : P0.z; dA.w = up ? rcv.w : P0.w;
;     dB.x = up ? P1.x : rcv.x; dB.y = up ? P1.y : rcv.y; dB.z = up ? P1.z : rcv.z; dB.w = up ? P1.w : rcv.w;
;     bf16_t* p = grp + (size_t)(fr & 7) * ld + (up ? CBJ : 0) + 8 * fq;
;     __builtin_nontemporal_store(dA, (u32x4*)p); __builtin_nontemporal_store(dB, (u32x4*)(p + 8 * ld));
;     __device__ __forceinline__ void operator()(f32x4 (&acc)[2][2][4][2], const Unit& u, int wr, int wc, int fr, int fq) const {
;     ...
;                 if (u.ks >= 0) store_pair((bf16_t*)yp + ((size_t)u.ks * MS + (rowg - MP) + ai * HALF + m * 16) * DM + colw, DM, fr, fq, pk[0], pk[1]);
;                 else {
.LBB0_1581:
	s_add_i32 s40, s0, 0xffffc000
	s_andn2_b64 vcc, exec, s[56:57]
	s_ashr_i32 s41, s40, 31
	s_cbranch_vccnz .LBB0_1583
	s_mov_b32 s63, s81
	s_lshl_b64 s[22:23], s[62:63], 22
	s_lshl_b64 s[44:45], s[40:41], 12
	s_add_u32 s1, s88, s22
	s_addc_u32 s14, s89, s23
	s_add_u32 s1, s1, s44
	s_addc_u32 s14, s14, s45
	s_lshl_b64 s[22:23], s[82:83], 1
	s_add_u32 s22, s1, s22
	s_waitcnt lgkmcnt(0)
	v_mov_b32_e32 v151, v131
	s_addc_u32 s23, s14, s23
	v_mov_b32_e32 v149, v131
	v_mov_b32_dpp v151, v212 row_ror:8 row_mask:0xf bank_mask:0xf
	v_mov_b32_e32 v158, v131
	v_mov_b32_dpp v149, v213 row_ror:8 row_mask:0xf bank_mask:0xf
	v_mov_b32_e32 v159, v131
	v_cndmask_b32_e64 v153, v151, v196, s[52:53]
	v_cndmask_b32_e64 v157, v200, v151, s[52:53]
	v_lshl_add_u64 v[160:161], s[22:23], 0, v[130:131]
	v_mov_b32_e32 v151, v131
	v_mov_b32_dpp v158, v211 row_ror:8 row_mask:0xf bank_mask:0xf
	v_mov_b32_dpp v159, v203 row_ror:8 row_mask:0xf bank_mask:0xf
	v_cndmask_b32_e64 v152, v149, v195, s[52:53]
	v_cndmask_b32_e64 v156, v199, v149, s[52:53]
	v_lshl_add_u64 v[160:161], v[160:161], 0, v[150:151]
	v_mov_b32_e32 v149, v131
	v_cndmask_b32_e64 v154, v158, v197, s[52:53]
	v_cndmask_b32_e64 v155, v159, v198, s[52:53]
	v_lshl_add_u64 v[160:161], v[160:161], 0, v[148:149]
	global_store_dwordx4 v[160:161], v[152:155], off
	v_cndmask_b32_e64 v158, v201, v158, s[52:53]
	v_cndmask_b32_e64 v159, v202, v159, s[52:53]
	v_add_co_u32_e32 v152, vcc, 0x8000, v160
	s_nop 1
	v_addc_co_u32_e32 v153, vcc, 0, v161, vcc
	global_store_dwordx4 v[152:153], v[156:159], off
; __device__ __forceinline__ u32x4 pack8(f32x4 a, f32x4 b) { u32x4 w; w.x = cvtpk(a[0], a[1]); w.y = cvtpk(a[2], a[3]); w.z = cvtpk(b[0], b[1]); w.w = cvtpk(b[2], b[3]); return w; }
;     __device__ __forceinline__ void operator()(f32x4 (&acc)[2][2][4][2], const Unit& u, int wr, int wc, int fr, int fq) const {
;     ...
;                 const int row = row0 + ai * HALF + m * 16;
;                 const float sr = rv[ai * 4 + m];
;                 float s = 0.f; u32x4 pk[2];
; #pragma unroll
;                 for (int bj = 0; bj < 2; ++bj) {
;                     const v4i_t i0 = __builtin_bit_cast(v4i_t, acc[ai][bj][m][0]) + ov[bj * 2], i1 = __builtin_bit_cast(v4i_t, acc[ai][bj][m][1]) + ov[bj * 2 + 1];
;                     const u32x4 c0_ = cv[bj * 2], c1_ = cv[bj * 2 + 1];
;                     f32x4 v0, v1;
; #pragma unroll
;                     for (int j = 0; j < 4; ++j) { v0[j] = (float)i0[j] * (sr * __uint_as_float(c0_[j])); v1[j] = (float)i1[j] * (sr * __uint_as_float(c1_[j])); }
;                     s += (v0[0] * v0[0] + v0[1] * v0[1]) + (v0[2] * v0[2] + v0[3] * v0[3]) + (v1[0] * v1[0] + v1[1] * v1[1]) + (v1[2] * v1[2] + v1[3] * v1[3]);
;                     pk[bj] = pack8(v0, v1);
;                 }
;                 if (u.ks >= 0) store_pair((bf16_t*)yp + ((size_t)u.ks * MS + (rowg - MP) + ai * HALF + m * 16) * DM + colw, DM, fr, fq, pk[0], pk[1]);
;                 else {
;                     store_pair(Y + (size_t)(rowg + ai * HALF + m * 16) * DM + colw, DM, fr, fq, pk[0], pk[1]);
;                     s += __shfl_xor(s, 16); s += __shfl_xor(s, 32);
;                     if (fq == 0) ssy[(size_t)row * 32 + u.pn * 4 + wc] = s;
;                 }
.LBB0_1583:
	v_add_u32_e32 v144, v78, v144
	v_add_u32_e32 v145, v79, v145
	v_cvt_f32_i32_e32 v145, v145
	v_cvt_f32_i32_e32 v144, v144
	v_mul_f32_e32 v156, 0x38018388, v194
	v_pk_mul_f32 v[152:153], v[66:67], v[156:157] op_sel_hi:[1,0]
	v_add_u32_e32 v149, v80, v146
	s_waitcnt lgkmcnt(0)
	v_add_u32_e32 v151, v81, v147
	v_pk_mul_f32 v[144:145], v[152:153], v[144:145]
	v_cvt_f32_i32_e32 v153, v151
	v_cvt_f32_i32_e32 v152, v149
	v_add_u32_e32 v136, v74, v136
	v_add_u32_e32 v137, v75, v137
	v_cvt_f32_i32_e32 v137, v137
	v_cvt_f32_i32_e32 v136, v136
	v_pk_mul_f32 v[154:155], v[62:63], v[156:157] op_sel_hi:[1,0]
	v_add_u32_e32 v157, v72, v142
	v_add_u32_e32 v158, v73, v143
	v_pk_mul_f32 v[142:143], v[68:69], v[156:157] op_sel_hi:[1,0]
	v_add_u32_e32 v149, v76, v138
	v_pk_mul_f32 v[142:143], v[142:143], v[152:153]
	v_cvt_f32_i32_e32 v153, v158
	v_pk_mul_f32 v[158:159], v[54:55], v[156:157] op_sel_hi:[1,0]
	v_add_u32_e32 v151, v77, v139
	v_pk_mul_f32 v[146:147], v[64:65], v[156:157] op_sel_hi:[1,0]
	v_cvt_f32_i32_e32 v152, v157
	v_pk_mul_f32 v[160:161], v[50:51], v[156:157] op_sel_hi:[1,0]
	v_pk_mul_f32 v[136:137], v[158:159], v[136:137]
	v_add_u32_e32 v158, v60, v134
	v_add_u32_e32 v159, v61, v135
	v_pk_mul_f32 v[134:135], v[56:57], v[156:157] op_sel_hi:[1,0]
	v_pk_mul_f32 v[138:139], v[52:53], v[156:157] op_sel_hi:[1,0]
	v_cvt_f32_i32_e32 v157, v151
	v_cvt_f32_i32_e32 v156, v149
	v_add_u32_e32 v140, v70, v140
	v_add_u32_e32 v141, v71, v141
	v_add_u32_e32 v132, v58, v132
	v_add_u32_e32 v133, v59, v133
	v_cvt_f32_i32_e32 v141, v141
	v_cvt_f32_i32_e32 v140, v140
	v_cvt_f32_i32_e32 v133, v133
	v_cvt_f32_i32_e32 v132, v132
	v_pk_mul_f32 v[134:135], v[134:135], v[156:157]
	v_cvt_f32_i32_e32 v157, v159
	v_cvt_f32_i32_e32 v156, v158
	v_pk_mul_f32 v[140:141], v[154:155], v[140:141]
	v_pk_mul_f32 v[146:147], v[146:147], v[152:153]
	v_pk_mul_f32 v[132:133], v[160:161], v[132:133]
	v_pk_mul_f32 v[138:139], v[138:139], v[156:157]
	v_cvt_pk_bf16_f32 v152, v144, v145
	v_cvt_pk_bf16_f32 v153, v142, v143
	v_cvt_pk_bf16_f32 v154, v140, v141
	v_cvt_pk_bf16_f32 v155, v146, v147
	v_cvt_pk_bf16_f32 v156, v136, v137
	v_cvt_pk_bf16_f32 v157, v134, v135
	v_cvt_pk_bf16_f32 v158, v132, v133
	v_cvt_pk_bf16_f32 v159, v138, v139
	v_cndmask_b32_e64 v149, 0, 1, s[42:43]
	s_mov_b64 s[44:45], -1
	v_cmp_ne_u32_e64 s[56:57], 1, v149
	s_andn2_b64 vcc, exec, s[42:43]
	v_cndmask_b32_e64 v163, v152, v156, s[52:53]
	v_cndmask_b32_e64 v162, v153, v157, s[52:53]
	v_cndmask_b32_e64 v161, v154, v158, s[52:53]
	v_cndmask_b32_e64 v160, v155, v159, s[52:53]
	s_cbranch_vccnz .LBB0_1587
	v_pk_mul_f32 v[136:137], v[136:137], v[136:137]
	v_pk_mul_f32 v[134:135], v[134:135], v[134:135]
	v_pk_mul_f32 v[132:133], v[132:133], v[132:133]
	v_add_f32_e32 v134, v134, v135
	v_add_f32_e32 v135, v136, v137
	s_or_b32 s22, s0, 16
	v_pk_mul_f32 v[138:139], v[138:139], v[138:139]
	v_add_f32_e32 v134, v135, v134
	v_add_f32_e32 v132, v132, v133
	s_ashr_i32 s23, s22, 31
	v_pk_mul_f32 v[144:145], v[144:145], v[144:145]
	v_pk_mul_f32 v[142:143], v[142:143], v[142:143]
	v_add_f32_e32 v132, v132, v134
	v_add_f32_e32 v133, v138, v139
	s_lshl_b64 s[22:23], s[22:23], 12
	v_readlane_b32 s1, v249, 28
	v_pk_mul_f32 v[140:141], v[140:141], v[140:141]
	v_add_f32_e32 v132, v133, v132
	v_add_f32_e32 v133, v142, v143
	v_add_f32_e32 v134, v144, v145
	s_add_u32 s1, s1, s22
	v_readlane_b32 s14, v253, 5
	v_and_b32_e32 v144, 64, v204
	v_pk_mul_f32 v[146:147], v[146:147], v[146:147]
	v_add_f32_e32 v133, v134, v133
	v_add_f32_e32 v134, v140, v141
	s_addc_u32 s14, s14, s23
	s_lshl_b64 s[22:23], s[82:83], 1
	v_xor_b32_e32 v143, 16, v204
	v_add_u32_e32 v144, 64, v144
	v_add_f32_e32 v133, v134, v133
	v_add_f32_e32 v134, v146, v147
	s_add_u32 s22, s1, s22
	v_cmp_lt_i32_e32 vcc, v143, v144
	v_add_f32_e32 v133, v134, v133
	s_addc_u32 s23, s14, s23
	v_cndmask_b32_e32 v143, v204, v143, vcc
	v_add_f32_e32 v142, v133, v132
	v_mov_b32_e32 v136, v131
	v_mov_b32_e32 v137, v131
	v_mov_b32_e32 v138, v131
	v_mov_b32_e32 v139, v131
	v_lshl_add_u64 v[140:141], s[22:23], 0, v[130:131]
	v_mov_b32_e32 v151, v131
	v_lshlrev_b32_e32 v143, 2, v143
	v_mov_b32_dpp v136, v163 row_ror:8 row_mask:0xf bank_mask:0xf
	v_mov_b32_dpp v137, v162 row_ror:8 row_mask:0xf bank_mask:0xf
	v_mov_b32_dpp v138, v161 row_ror:8 row_mask:0xf bank_mask:0xf
	v_mov_b32_dpp v139, v160 row_ror:8 row_mask:0xf bank_mask:0xf
	ds_bpermute_b32 v143, v143, v142
	v_lshl_add_u64 v[140:141], v[140:141], 0, v[150:151]
	v_mov_b32_e32 v149, v131
	v_cndmask_b32_e64 v132, v136, v152, s[52:53]
	v_cndmask_b32_e64 v133, v137, v153, s[52:53]
	v_cndmask_b32_e64 v134, v138, v154, s[52:53]
	v_cndmask_b32_e64 v135, v139, v155, s[52:53]
	v_lshl_add_u64 v[140:141], v[140:141], 0, v[148:149]
	global_store_dwordx4 v[140:141], v[132:135], off
	v_cndmask_b32_e64 v136, v156, v136, s[52:53]
	v_cndmask_b32_e64 v137, v157, v137, s[52:53]
	v_xor_b32_e32 v133, 32, v204
	v_cmp_lt_i32_e32 vcc, v133, v144
	s_waitcnt lgkmcnt(0)
	v_add_f32_e32 v132, v142, v143
	v_cndmask_b32_e64 v138, v158, v138, s[52:53]
	v_cndmask_b32_e32 v133, v204, v133, vcc
	v_lshlrev_b32_e32 v133, 2, v133
	ds_bpermute_b32 v133, v133, v132
	v_add_co_u32_e32 v134, vcc, s46, v140
	v_cndmask_b32_e64 v139, v159, v139, s[52:53]
	s_nop 0
	v_addc_co_u32_e32 v135, vcc, 0, v141, vcc
	global_store_dwordx4 v[134:135], v[136:139], off
	s_and_saveexec_b64 s[42:43], s[54:55]
	s_cbranch_execz .LBB0_1586
	v_or_b32_e32 v134, 16, v182
	v_ashrrev_i32_e32 v135, 31, v134
	v_readlane_b32 s44, v253, 6
	s_waitcnt lgkmcnt(0)
	v_add_f32_e32 v136, v132, v133
	s_lshl_b32 s22, s21, 2
	v_lshlrev_b64 v[132:133], 7, v[134:135]
	v_readlane_b32 s45, v253, 7
	s_ashr_i32 s23, s22, 31
	s_lshl_b32 s80, s38, 2
	v_lshl_add_u64 v[132:133], s[44:45], 0, v[132:133]
	v_lshl_add_u64 v[132:133], s[22:23], 2, v[132:133]
	v_lshl_add_u64 v[132:133], v[132:133], 0, s[80:81]
	global_store_dword v[132:133], v136, off

; __device__ __forceinline__ unsigned dpp_ror8(unsigned v) { return (unsigned)__builtin_amdgcn_update_dpp(0, (int)v, 0x128, 0xF, 0xF, false); }
; __device__ __forceinline__ void store_pair(bf16_t* grp  , size_t ld, int fr, int fq, u32x4 P0, u32x4 P1) {
;     const bool up = (fr & 8) != 0;
;     u32x4 snd, rcv;
;     snd.x = up ? P0.x : P1.x; snd.y = up ? P0.y : P1.y; snd.z = up ? P0.z : P1.z; snd.w = up ? P0.w : P1.w;
;     rcv.x = dpp_ror8(snd.x); rcv.y = dpp_ror8(snd.y); rcv.z = dpp_ror8(snd.z); rcv.w = dpp_ror8(snd.w);
;     u32x4 dA, dB;
;     dA.x = up ? rcv.x : P0.x; dA.y = up ? rcv.y : P0.y; dA.z = up ? rcv.z : P0.z; dA.w = up ? rcv.w : P0.w;
;     dB.x = up ? P1.x : rcv.x; dB.y = up ? P1.y : rcv.y; dB.z = up ? P1.z : rcv.z; dB.w = up ? P1.w : rcv.w;
;     bf16_t* p = grp + (size_t)(fr & 7) * ld + (up ? CBJ : 0) + 8 * fq;
;     __builtin_nontemporal_store(dA, (u32x4*)p); __builtin_nontemporal_store(dB, (u32x4*)(p + 8 * ld));
;     __device__ __forceinline__ void operator()(f32x4 (&acc)[2][2][4][2], const Unit& u, int wr, int wc, int fr, int fq) const {
;     ...
;                 if (u.ks >= 0) store_pair((bf16_t*)yp + ((size_t)u.ks * MS + (rowg - MP) + ai * HALF + m * 16) * DM + colw, DM, fr, fq, pk[0], pk[1]);
;                 else {
.LBB0_1587:
	s_andn2_b64 vcc, exec, s[44:45]
	s_cbranch_vccnz .LBB0_1589
	s_mov_b32 s63, s81
	s_lshl_b64 s[22:23], s[62:63], 22
	s_lshl_b64 s[42:43], s[40:41], 12
	s_add_u32 s1, s88, s22
	s_addc_u32 s14, s89, s23
	s_add_u32 s1, s1, s42
	s_addc_u32 s14, s14, s43
	s_lshl_b64 s[22:23], s[82:83], 1
	s_add_u32 s22, s1, s22
	s_addc_u32 s23, s14, s23
	v_lshl_add_u64 v[140:141], s[22:23], 0, v[130:131]
	v_mov_b32_e32 v151, v131
	v_lshl_add_u64 v[140:141], v[140:141], 0, v[150:151]
	v_mov_b32_e32 v149, v131
	v_mov_b32_e32 v136, v131
	v_mov_b32_e32 v137, v131
	v_mov_b32_e32 v138, v131
	v_mov_b32_e32 v139, v131
	v_lshl_add_u64 v[140:141], v[140:141], 0, v[148:149]
	v_mov_b32_dpp v136, v163 row_ror:8 row_mask:0xf bank_mask:0xf
	v_mov_b32_dpp v137, v162 row_ror:8 row_mask:0xf bank_mask:0xf
	v_mov_b32_dpp v138, v161 row_ror:8 row_mask:0xf bank_mask:0xf
	v_mov_b32_dpp v139, v160 row_ror:8 row_mask:0xf bank_mask:0xf
	v_add_co_u32_e32 v142, vcc, 0x10000, v140
	v_cndmask_b32_e64 v132, v136, v152, s[52:53]
	s_waitcnt lgkmcnt(0)
	v_cndmask_b32_e64 v133, v137, v153, s[52:53]
	v_cndmask_b32_e64 v134, v138, v154, s[52:53]
	v_cndmask_b32_e64 v135, v139, v155, s[52:53]
	v_addc_co_u32_e32 v143, vcc, 0, v141, vcc
	global_store_dwordx4 v[142:143], v[132:135], off
	v_cndmask_b32_e64 v136, v156, v136, s[52:53]
	v_cndmask_b32_e64 v137, v157, v137, s[52:53]
	v_add_co_u32_e32 v132, vcc, 0x18000, v140
	v_cndmask_b32_e64 v138, v158, v138, s[52:53]
	v_cndmask_b32_e64 v139, v159, v139, s[52:53]
	v_addc_co_u32_e32 v133, vcc, 0, v141, vcc
	global_store_dwordx4 v[132:133], v[136:139], off
; __device__ __forceinline__ u32x4 pack8(f32x4 a, f32x4 b) { u32x4 w; w.x = cvtpk(a[0], a[1]); w.y = cvtpk(a[2], a[3]); w.z = cvtpk(b[0], b[1]); w.w = cvtpk(b[2], b[3]); return w; }
;     __device__ __forceinline__ void operator()(f32x4 (&acc)[2][2][4][2], const Unit& u, int wr, int wc, int fr, int fq) const {
;     ...
;                 const int row = row0 + ai * HALF + m * 16;
;                 const float sr = rv[ai * 4 + m];
;                 float s = 0.f; u32x4 pk[2];
; #pragma unroll
;                 for (int bj = 0; bj < 2; ++bj) {
;                     const v4i_t i0 = __builtin_bit_cast(v4i_t, acc[ai][bj][m][0]) + ov[bj * 2], i1 = __builtin_bit_cast(v4i_t, acc[ai][bj][m][1]) + ov[bj * 2 + 1];
;                     const u32x4 c0_ = cv[bj * 2], c1_ = cv[bj * 2 + 1];
;                     f32x4 v0, v1;
; #pragma unroll
;                     for (int j = 0; j < 4; ++j) { v0[j] = (float)i0[j] * (sr * __uint_as_float(c0_[j])); v1[j] = (float)i1[j] * (sr * __uint_as_float(c1_[j])); }
;                     s += (v0[0] * v0[0] + v0[1] * v0[1]) + (v0[2] * v0[2] + v0[3] * v0[3]) + (v1[0] * v1[0] + v1[1] * v1[1]) + (v1[2] * v1[2] + v1[3] * v1[3]);
;                     pk[bj] = pack8(v0, v1);
;                 }
;                 if (u.ks >= 0) store_pair((bf16_t*)yp + ((size_t)u.ks * MS + (rowg - MP) + ai * HALF + m * 16) * DM + colw, DM, fr, fq, pk[0], pk[1]);
;                 else {
;                     store_pair(Y + (size_t)(rowg + ai * HALF + m * 16) * DM + colw, DM, fr, fq, pk[0], pk[1]);
;                     s += __shfl_xor(s, 16); s += __shfl_xor(s, 32);
;                     if (fq == 0) ssy[(size_t)row * 32 + u.pn * 4 + wc] = s;
;                 }
.LBB0_1589:
	v_add_u32_e32 v126, v78, v126
	v_add_u32_e32 v127, v79, v127
	v_cvt_f32_i32_e32 v127, v127
	v_cvt_f32_i32_e32 v126, v126
	v_mul_f32_e32 v136, 0x38018388, v193
	s_waitcnt lgkmcnt(0)
	v_pk_mul_f32 v[132:133], v[66:67], v[136:137] op_sel_hi:[1,0]
	v_pk_mul_f32 v[134:135], v[62:63], v[136:137] op_sel_hi:[1,0]
	v_add_u32_e32 v137, v80, v128
	v_add_u32_e32 v138, v81, v129
	v_pk_mul_f32 v[126:127], v[132:133], v[126:127]
	v_cvt_f32_i32_e32 v133, v138
	v_cvt_f32_i32_e32 v132, v137
	v_add_u32_e32 v118, v74, v118
	v_add_u32_e32 v119, v75, v119
	v_cvt_f32_i32_e32 v119, v119
	v_cvt_f32_i32_e32 v118, v118
	v_add_u32_e32 v139, v72, v124
	v_add_u32_e32 v140, v73, v125
	v_pk_mul_f32 v[124:125], v[68:69], v[136:137] op_sel_hi:[1,0]
	v_pk_mul_f32 v[128:129], v[64:65], v[136:137] op_sel_hi:[1,0]
	v_pk_mul_f32 v[124:125], v[124:125], v[132:133]
	v_cvt_f32_i32_e32 v133, v140
	v_cvt_f32_i32_e32 v132, v139
	v_pk_mul_f32 v[138:139], v[54:55], v[136:137] op_sel_hi:[1,0]
	v_pk_mul_f32 v[140:141], v[50:51], v[136:137] op_sel_hi:[1,0]
	v_add_u32_e32 v142, v76, v120
	v_add_u32_e32 v137, v77, v121
	v_pk_mul_f32 v[118:119], v[138:139], v[118:119]
	v_add_u32_e32 v138, v60, v116
	v_add_u32_e32 v139, v61, v117
	v_pk_mul_f32 v[116:117], v[56:57], v[136:137] op_sel_hi:[1,0]
	v_pk_mul_f32 v[120:121], v[52:53], v[136:137] op_sel_hi:[1,0]
	v_cvt_f32_i32_e32 v137, v137
	v_cvt_f32_i32_e32 v136, v142
	v_add_u32_e32 v122, v70, v122
	v_add_u32_e32 v123, v71, v123
	v_add_u32_e32 v114, v58, v114
	v_add_u32_e32 v115, v59, v115
	v_cvt_f32_i32_e32 v123, v123
	v_cvt_f32_i32_e32 v122, v122
	v_cvt_f32_i32_e32 v115, v115
	v_cvt_f32_i32_e32 v114, v114
	v_pk_mul_f32 v[116:117], v[116:117], v[136:137]
	v_cvt_f32_i32_e32 v137, v139
	v_cvt_f32_i32_e32 v136, v138
	v_pk_mul_f32 v[122:123], v[134:135], v[122:123]
	v_pk_mul_f32 v[128:129], v[128:129], v[132:133]
	v_pk_mul_f32 v[114:115], v[140:141], v[114:115]
	v_pk_mul_f32 v[120:121], v[120:121], v[136:137]
	v_cvt_pk_bf16_f32 v132, v126, v127
	v_cvt_pk_bf16_f32 v133, v124, v125
	v_cvt_pk_bf16_f32 v134, v122, v123
	v_cvt_pk_bf16_f32 v135, v128, v129
	v_cvt_pk_bf16_f32 v136, v118, v119
	v_cvt_pk_bf16_f32 v137, v116, v117
	v_cvt_pk_bf16_f32 v138, v114, v115
	v_cvt_pk_bf16_f32 v139, v120, v121
	s_mov_b64 s[42:43], -1
	s_and_b64 vcc, exec, s[56:57]
	v_cndmask_b32_e64 v143, v132, v136, s[52:53]
	v_cndmask_b32_e64 v142, v133, v137, s[52:53]
	v_cndmask_b32_e64 v141, v134, v138, s[52:53]
	v_cndmask_b32_e64 v140, v135, v139, s[52:53]
	s_cbranch_vccnz .LBB0_1593
	v_pk_mul_f32 v[118:119], v[118:119], v[118:119]
	v_pk_mul_f32 v[116:117], v[116:117], v[116:117]
	v_pk_mul_f32 v[114:115], v[114:115], v[114:115]
	v_add_f32_e32 v116, v116, v117
	v_add_f32_e32 v117, v118, v119
	s_or_b32 s22, s0, 32
	v_pk_mul_f32 v[120:121], v[120:121], v[120:121]
	v_add_f32_e32 v116, v117, v116
	v_add_f32_e32 v114, v114, v115
	s_ashr_i32 s23, s22, 31
	v_pk_mul_f32 v[126:127], v[126:127], v[126:127]
	v_pk_mul_f32 v[124:125], v[124:125], v[124:125]
	v_add_f32_e32 v114, v114, v116
	v_add_f32_e32 v115, v120, v121
	s_lshl_b64 s[22:23], s[22:23], 12
	v_readlane_b32 s1, v249, 28
	v_pk_mul_f32 v[122:123], v[122:123], v[122:123]
	v_add_f32_e32 v114, v115, v114
	v_add_f32_e32 v115, v124, v125
	v_add_f32_e32 v116, v126, v127
	s_add_u32 s1, s1, s22
	v_readlane_b32 s14, v253, 5
	v_and_b32_e32 v126, 64, v204
	v_pk_mul_f32 v[128:129], v[128:129], v[128:129]
	v_add_f32_e32 v115, v116, v115
	v_add_f32_e32 v116, v122, v123
	s_addc_u32 s14, s14, s23
	s_lshl_b64 s[22:23], s[82:83], 1
	v_xor_b32_e32 v125, 16, v204
	v_add_u32_e32 v126, 64, v126
	v_add_f32_e32 v115, v116, v115
	v_add_f32_e32 v116, v128, v129
	s_add_u32 s22, s1, s22
	v_cmp_lt_i32_e32 vcc, v125, v126
	v_add_f32_e32 v115, v116, v115
	s_addc_u32 s23, s14, s23
	v_cndmask_b32_e32 v125, v204, v125, vcc
	v_add_f32_e32 v124, v115, v114
	v_mov_b32_e32 v118, v131
	v_mov_b32_e32 v119, v131
	v_mov_b32_e32 v120, v131
	v_mov_b32_e32 v121, v131
	v_lshl_add_u64 v[122:123], s[22:23], 0, v[130:131]
	v_mov_b32_e32 v151, v131
	v_lshlrev_b32_e32 v125, 2, v125
	v_mov_b32_dpp v118, v143 row_ror:8 row_mask:0xf bank_mask:0xf
	v_mov_b32_dpp v119, v142 row_ror:8 row_mask:0xf bank_mask:0xf
	v_mov_b32_dpp v120, v141 row_ror:8 row_mask:0xf bank_mask:0xf
	v_mov_b32_dpp v121, v140 row_ror:8 row_mask:0xf bank_mask:0xf
	ds_bpermute_b32 v125, v125, v124
	v_lshl_add_u64 v[122:123], v[122:123], 0, v[150:151]
	v_mov_b32_e32 v149, v131
	v_cndmask_b32_e64 v114, v118, v132, s[52:53]
	v_cndmask_b32_e64 v115, v119, v133, s[52:53]
	v_cndmask_b32_e64 v116, v120, v134, s[52:53]
	v_cndmask_b32_e64 v117, v121, v135, s[52:53]
	v_lshl_add_u64 v[122:123], v[122:123], 0, v[148:149]
	global_store_dwordx4 v[122:123], v[114:117], off
	v_cndmask_b32_e64 v118, v136, v118, s[52:53]
	v_cndmask_b32_e64 v119, v137, v119, s[52:53]
	v_xor_b32_e32 v115, 32, v204
	v_cmp_lt_i32_e32 vcc, v115, v126
	s_waitcnt lgkmcnt(0)
	v_add_f32_e32 v114, v124, v125
	v_cndmask_b32_e64 v120, v138, v120, s[52:53]
	v_cndmask_b32_e32 v115, v204, v115, vcc
	v_lshlrev_b32_e32 v115, 2, v115
	ds_bpermute_b32 v115, v115, v114
	v_add_co_u32_e32 v116, vcc, s46, v122
	v_cndmask_b32_e64 v121, v139, v121, s[52:53]
	s_nop 0
	v_addc_co_u32_e32 v117, vcc, 0, v123, vcc
	global_store_dwordx4 v[116:117], v[118:121], off
	s_and_saveexec_b64 s[42:43], s[54:55]
	s_cbranch_execz .LBB0_1592
	v_or_b32_e32 v116, 32, v182
	v_ashrrev_i32_e32 v117, 31, v116
	v_readlane_b32 s44, v253, 6
	s_waitcnt lgkmcnt(0)
	v_add_f32_e32 v118, v114, v115
	s_lshl_b32 s22, s21, 2
	v_lshlrev_b64 v[114:115], 7, v[116:117]
	v_readlane_b32 s45, v253, 7
	s_ashr_i32 s23, s22, 31
	s_lshl_b32 s80, s38, 2
	v_lshl_add_u64 v[114:115], s[44:45], 0, v[114:115]
	v_lshl_add_u64 v[114:115], s[22:23], 2, v[114:115]
	v_lshl_add_u64 v[114:115], v[114:115], 0, s[80:81]
	global_store_dword v[114:115], v118, off

; __device__ __forceinline__ unsigned dpp_ror8(unsigned v) { return (unsigned)__builtin_amdgcn_update_dpp(0, (int)v, 0x128, 0xF, 0xF, false); }
; __device__ __forceinline__ void store_pair(bf16_t* grp  , size_t ld, int fr, int fq, u32x4 P0, u32x4 P1) {
;     const bool up = (fr & 8) != 0;
;     u32x4 snd, rcv;
;     snd.x = up ? P0.x : P1.x; snd.y = up ? P0.y : P1.y; snd.z = up ? P0.z : P1.z; snd.w = up ? P0.w : P1.w;
;     rcv.x = dpp_ror8(snd.x); rcv.y = dpp_ror8(snd.y); rcv.z = dpp_ror8(snd.z); rcv.w = dpp_ror8(snd.w);
;     u32x4 dA, dB;
;     dA.x = up ? rcv.x : P0.x; dA.y = up ? rcv.y : P0.y; dA.z = up ? rcv.z : P0.z; dA.w = up ? rcv.w : P0.w;
;     dB.x = up ? P1.x : rcv.x; dB.y = up ? P1.y : rcv.y; dB.z = up ? P1.z : rcv.z; dB.w = up ? P1.w : rcv.w;
;     bf16_t* p = grp + (size_t)(fr & 7) * ld + (up ? CBJ : 0) + 8 * fq;
;     __builtin_nontemporal_store(dA, (u32x4*)p); __builtin_nontemporal_store(dB, (u32x4*)(p + 8 * ld));
;     __device__ __forceinline__ void operator()(f32x4 (&acc)[2][2][4][2], const Unit& u, int wr, int wc, int fr, int fq) const {
;     ...
;                 if (u.ks >= 0) store_pair((bf16_t*)yp + ((size_t)u.ks * MS + (rowg - MP) + ai * HALF + m * 16) * DM + colw, DM, fr, fq, pk[0], pk[1]);
;                 else {
.LBB0_1593:
	s_andn2_b64 vcc, exec, s[42:43]
	s_cbranch_vccnz .LBB0_1595
	s_mov_b32 s63, s81
	s_lshl_b64 s[22:23], s[62:63], 22
	s_lshl_b64 s[42:43], s[40:41], 12
	s_add_u32 s1, s88, s22
	s_addc_u32 s14, s89, s23
	s_add_u32 s1, s1, s42
	s_addc_u32 s14, s14, s43
	s_lshl_b64 s[22:23], s[82:83], 1
	s_add_u32 s22, s1, s22
	s_addc_u32 s23, s14, s23
	v_lshl_add_u64 v[122:123], s[22:23], 0, v[130:131]
	v_mov_b32_e32 v151, v131
	v_lshl_add_u64 v[122:123], v[122:123], 0, v[150:151]
	v_mov_b32_e32 v149, v131
	v_mov_b32_e32 v118, v131
	v_mov_b32_e32 v119, v131
	v_mov_b32_e32 v120, v131
	v_mov_b32_e32 v121, v131
	v_lshl_add_u64 v[122:123], v[122:123], 0, v[148:149]
	v_mov_b32_dpp v118, v143 row_ror:8 row_mask:0xf bank_mask:0xf
	v_mov_b32_dpp v119, v142 row_ror:8 row_mask:0xf bank_mask:0xf
	v_mov_b32_dpp v120, v141 row_ror:8 row_mask:0xf bank_mask:0xf
	v_mov_b32_dpp v121, v140 row_ror:8 row_mask:0xf bank_mask:0xf
	v_add_co_u32_e32 v124, vcc, 0x20000, v122
	v_cndmask_b32_e64 v114, v118, v132, s[52:53]
	s_waitcnt lgkmcnt(0)
	v_cndmask_b32_e64 v115, v119, v133, s[52:53]
	v_cndmask_b32_e64 v116, v120, v134, s[52:53]
	v_cndmask_b32_e64 v117, v121, v135, s[52:53]
	v_addc_co_u32_e32 v125, vcc, 0, v123, vcc
	global_store_dwordx4 v[124:125], v[114:117], off
	v_cndmask_b32_e64 v118, v136, v118, s[52:53]
	v_cndmask_b32_e64 v119, v137, v119, s[52:53]
	v_add_co_u32_e32 v114, vcc, 0x28000, v122
	v_cndmask_b32_e64 v120, v138, v120, s[52:53]
	v_cndmask_b32_e64 v121, v139, v121, s[52:53]
	v_addc_co_u32_e32 v115, vcc, 0, v123, vcc
	global_store_dwordx4 v[114:115], v[118:121], off
; __device__ __forceinline__ u32x4 pack8(f32x4 a, f32x4 b) { u32x4 w; w.x = cvtpk(a[0], a[1]); w.y = cvtpk(a[2], a[3]); w.z = cvtpk(b[0], b[1]); w.w = cvtpk(b[2], b[3]); return w; }
;     __device__ __forceinline__ void operator()(f32x4 (&acc)[2][2][4][2], const Unit& u, int wr, int wc, int fr, int fq) const {
;     ...
;                 const int row = row0 + ai * HALF + m * 16;
;                 const float sr = rv[ai * 4 + m];
;                 float s = 0.f; u32x4 pk[2];
; #pragma unroll
;                 for (int bj = 0; bj < 2; ++bj) {
;                     const v4i_t i0 = __builtin_bit_cast(v4i_t, acc[ai][bj][m][0]) + ov[bj * 2], i1 = __builtin_bit_cast(v4i_t, acc[ai][bj][m][1]) + ov[bj * 2 + 1];
;                     const u32x4 c0_ = cv[bj * 2], c1_ = cv[bj * 2 + 1];
;                     f32x4 v0, v1;
; #pragma unroll
;                     for (int j = 0; j < 4; ++j) { v0[j] = (float)i0[j] * (sr * __uint_as_float(c0_[j])); v1[j] = (float)i1[j] * (sr * __uint_as_float(c1_[j])); }
;                     s += (v0[0] * v0[0] + v0[1] * v0[1]) + (v0[2] * v0[2] + v0[3] * v0[3]) + (v1[0] * v1[0] + v1[1] * v1[1]) + (v1[2] * v1[2] + v1[3] * v1[3]);
;                     pk[bj] = pack8(v0, v1);
;                 }
;                 if (u.ks >= 0) store_pair((bf16_t*)yp + ((size_t)u.ks * MS + (rowg - MP) + ai * HALF + m * 16) * DM + colw, DM, fr, fq, pk[0], pk[1]);
;                 else {
;                     store_pair(Y + (size_t)(rowg + ai * HALF + m * 16) * DM + colw, DM, fr, fq, pk[0], pk[1]);
;                     s += __shfl_xor(s, 16); s += __shfl_xor(s, 32);
;                     if (fq == 0) ssy[(size_t)row * 32 + u.pn * 4 + wc] = s;
;                 }
.LBB0_1595:
	v_add_u32_e32 v110, v78, v110
	v_add_u32_e32 v111, v79, v111
	v_cvt_f32_i32_e32 v111, v111
	v_cvt_f32_i32_e32 v110, v110
	v_mul_f32_e32 v118, 0x38018388, v192
	s_waitcnt lgkmcnt(0)
	v_pk_mul_f32 v[114:115], v[66:67], v[118:119] op_sel_hi:[1,0]
	v_pk_mul_f32 v[116:117], v[62:63], v[118:119] op_sel_hi:[1,0]
	v_add_u32_e32 v119, v80, v112
	v_add_u32_e32 v120, v81, v113
	v_pk_mul_f32 v[110:111], v[114:115], v[110:111]
	v_cvt_f32_i32_e32 v115, v120
	v_cvt_f32_i32_e32 v114, v119
	v_add_u32_e32 v102, v74, v102
	v_add_u32_e32 v103, v75, v103
	v_cvt_f32_i32_e32 v103, v103
	v_cvt_f32_i32_e32 v102, v102
	v_add_u32_e32 v121, v72, v108
	v_add_u32_e32 v122, v73, v109
	v_pk_mul_f32 v[108:109], v[68:69], v[118:119] op_sel_hi:[1,0]
	v_pk_mul_f32 v[112:113], v[64:65], v[118:119] op_sel_hi:[1,0]
	v_pk_mul_f32 v[108:109], v[108:109], v[114:115]
	v_cvt_f32_i32_e32 v115, v122
	v_cvt_f32_i32_e32 v114, v121
	v_pk_mul_f32 v[120:121], v[54:55], v[118:119] op_sel_hi:[1,0]
	v_pk_mul_f32 v[122:123], v[50:51], v[118:119] op_sel_hi:[1,0]
	v_add_u32_e32 v124, v76, v104
	v_add_u32_e32 v119, v77, v105
	v_pk_mul_f32 v[102:103], v[120:121], v[102:103]
	v_add_u32_e32 v120, v60, v100
	v_add_u32_e32 v121, v61, v101
	v_pk_mul_f32 v[100:101], v[56:57], v[118:119] op_sel_hi:[1,0]
	v_pk_mul_f32 v[104:105], v[52:53], v[118:119] op_sel_hi:[1,0]
	v_cvt_f32_i32_e32 v119, v119
	v_cvt_f32_i32_e32 v118, v124
	v_add_u32_e32 v106, v70, v106
	v_add_u32_e32 v107, v71, v107
	v_add_u32_e32 v98, v58, v98
	v_add_u32_e32 v99, v59, v99
	v_cvt_f32_i32_e32 v107, v107
	v_cvt_f32_i32_e32 v106, v106
	v_cvt_f32_i32_e32 v99, v99
	v_cvt_f32_i32_e32 v98, v98
	v_pk_mul_f32 v[100:101], v[100:101], v[118:119]
	v_cvt_f32_i32_e32 v119, v121
	v_cvt_f32_i32_e32 v118, v120
	v_pk_mul_f32 v[106:107], v[116:117], v[106:107]
	v_pk_mul_f32 v[112:113], v[112:113], v[114:115]
	v_pk_mul_f32 v[98:99], v[122:123], v[98:99]
	v_pk_mul_f32 v[104:105], v[104:105], v[118:119]
	v_cvt_pk_bf16_f32 v114, v110, v111
	v_cvt_pk_bf16_f32 v115, v108, v109
	v_cvt_pk_bf16_f32 v116, v106, v107
	v_cvt_pk_bf16_f32 v117, v112, v113
	v_cvt_pk_bf16_f32 v118, v102, v103
	v_cvt_pk_bf16_f32 v119, v100, v101
	v_cvt_pk_bf16_f32 v120, v98, v99
	v_cvt_pk_bf16_f32 v121, v104, v105
	s_mov_b64 s[42:43], -1
	s_and_b64 vcc, exec, s[56:57]
	v_cndmask_b32_e64 v125, v114, v118, s[52:53]
	v_cndmask_b32_e64 v124, v115, v119, s[52:53]
	v_cndmask_b32_e64 v123, v116, v120, s[52:53]
	v_cndmask_b32_e64 v122, v117, v121, s[52:53]
	s_cbranch_vccnz .LBB0_1599
	v_pk_mul_f32 v[102:103], v[102:103], v[102:103]
	v_pk_mul_f32 v[100:101], v[100:101], v[100:101]
	v_pk_mul_f32 v[98:99], v[98:99], v[98:99]
	v_add_f32_e32 v100, v100, v101
	v_add_f32_e32 v101, v102, v103
	s_or_b32 s22, s0, 48
	v_pk_mul_f32 v[104:105], v[104:105], v[104:105]
	v_add_f32_e32 v100, v101, v100
	v_add_f32_e32 v98, v98, v99
	s_ashr_i32 s23, s22, 31
	v_pk_mul_f32 v[110:111], v[110:111], v[110:111]
	v_pk_mul_f32 v[108:109], v[108:109], v[108:109]
	v_add_f32_e32 v98, v98, v100
	v_add_f32_e32 v99, v104, v105
	s_lshl_b64 s[22:23], s[22:23], 12
	v_readlane_b32 s1, v249, 28
	v_pk_mul_f32 v[106:107], v[106:107], v[106:107]
	v_add_f32_e32 v98, v99, v98
	v_add_f32_e32 v99, v108, v109
	v_add_f32_e32 v100, v110, v111
	s_add_u32 s1, s1, s22
	v_readlane_b32 s14, v253, 5
	v_and_b32_e32 v110, 64, v204
	v_pk_mul_f32 v[112:113], v[112:113], v[112:113]
	v_add_f32_e32 v99, v100, v99
	v_add_f32_e32 v100, v106, v107
	s_addc_u32 s14, s14, s23
	s_lshl_b64 s[22:23], s[82:83], 1
	v_xor_b32_e32 v109, 16, v204
	v_add_u32_e32 v110, 64, v110
	v_add_f32_e32 v99, v100, v99
	v_add_f32_e32 v100, v112, v113
	s_add_u32 s22, s1, s22
	v_cmp_lt_i32_e32 vcc, v109, v110
	v_add_f32_e32 v99, v100, v99
	s_addc_u32 s23, s14, s23
	v_cndmask_b32_e32 v109, v204, v109, vcc
	v_add_f32_e32 v108, v99, v98
	v_mov_b32_e32 v102, v131
	v_mov_b32_e32 v103, v131
	v_mov_b32_e32 v104, v131
	v_mov_b32_e32 v105, v131
	v_lshl_add_u64 v[106:107], s[22:23], 0, v[130:131]
	v_mov_b32_e32 v151, v131
	v_lshlrev_b32_e32 v109, 2, v109
	v_mov_b32_dpp v102, v125 row_ror:8 row_mask:0xf bank_mask:0xf
	v_mov_b32_dpp v103, v124 row_ror:8 row_mask:0xf bank_mask:0xf
	v_mov_b32_dpp v104, v123 row_ror:8 row_mask:0xf bank_mask:0xf
	v_mov_b32_dpp v105, v122 row_ror:8 row_mask:0xf bank_mask:0xf
	ds_bpermute_b32 v109, v109, v108
	v_lshl_add_u64 v[106:107], v[106:107], 0, v[150:151]
	v_mov_b32_e32 v149, v131
	v_cndmask_b32_e64 v98, v102, v114, s[52:53]
	v_cndmask_b32_e64 v99, v103, v115, s[52:53]
	v_cndmask_b32_e64 v100, v104, v116, s[52:53]
	v_cndmask_b32_e64 v101, v105, v117, s[52:53]
	v_lshl_add_u64 v[106:107], v[106:107], 0, v[148:149]
	global_store_dwordx4 v[106:107], v[98:101], off
	v_cndmask_b32_e64 v102, v118, v102, s[52:53]
	v_cndmask_b32_e64 v103, v119, v103, s[52:53]
	v_xor_b32_e32 v99, 32, v204
	v_cmp_lt_i32_e32 vcc, v99, v110
	s_waitcnt lgkmcnt(0)
	v_add_f32_e32 v98, v108, v109
	v_cndmask_b32_e64 v104, v120, v104, s[52:53]
	v_cndmask_b32_e32 v99, v204, v99, vcc
	v_lshlrev_b32_e32 v99, 2, v99
	ds_bpermute_b32 v99, v99, v98
	v_add_co_u32_e32 v100, vcc, s46, v106
	v_cndmask_b32_e64 v105, v121, v105, s[52:53]
	s_nop 0
	v_addc_co_u32_e32 v101, vcc, 0, v107, vcc
	global_store_dwordx4 v[100:101], v[102:105], off
	s_and_saveexec_b64 s[42:43], s[54:55]
	s_cbranch_execz .LBB0_1598
	v_or_b32_e32 v100, 48, v182
	v_ashrrev_i32_e32 v101, 31, v100
	v_readlane_b32 s44, v253, 6
	s_waitcnt lgkmcnt(0)
	v_add_f32_e32 v102, v98, v99
	s_lshl_b32 s22, s21, 2
	v_lshlrev_b64 v[98:99], 7, v[100:101]
	v_readlane_b32 s45, v253, 7
	s_ashr_i32 s23, s22, 31
	s_lshl_b32 s80, s38, 2
	v_lshl_add_u64 v[98:99], s[44:45], 0, v[98:99]
	v_lshl_add_u64 v[98:99], s[22:23], 2, v[98:99]
	v_lshl_add_u64 v[98:99], v[98:99], 0, s[80:81]
	global_store_dword v[98:99], v102, off

; __device__ __forceinline__ unsigned dpp_ror8(unsigned v) { return (unsigned)__builtin_amdgcn_update_dpp(0, (int)v, 0x128, 0xF, 0xF, false); }
; __device__ __forceinline__ void store_pair(bf16_t* grp  , size_t ld, int fr, int fq, u32x4 P0, u32x4 P1) {
;     const bool up = (fr & 8) != 0;
;     u32x4 snd, rcv;
;     snd.x = up ? P0.x : P1.x; snd.y = up ? P0.y : P1.y; snd.z = up ? P0.z : P1.z; snd.w = up ? P0.w : P1.w;
;     rcv.x = dpp_ror8(snd.x); rcv.y = dpp_ror8(snd.y); rcv.z = dpp_ror8(snd.z); rcv.w = dpp_ror8(snd.w);
;     u32x4 dA, dB;
;     dA.x = up ? rcv.x : P0.x; dA.y = up ? rcv.y : P0.y; dA.z = up ? rcv.z : P0.z; dA.w = up ? rcv.w : P0.w;
;     dB.x = up ? P1.x : rcv.x; dB.y = up ? P1.y : rcv.y; dB.z = up ? P1.z : rcv.z; dB.w = up ? P1.w : rcv.w;
;     bf16_t* p = grp + (size_t)(fr & 7) * ld + (up ? CBJ : 0) + 8 * fq;
;     __builtin_nontemporal_store(dA, (u32x4*)p); __builtin_nontemporal_store(dB, (u32x4*)(p + 8 * ld));
;     __device__ __forceinline__ void operator()(f32x4 (&acc)[2][2][4][2], const Unit& u, int wr, int wc, int fr, int fq) const {
;     ...
;                 if (u.ks >= 0) store_pair((bf16_t*)yp + ((size_t)u.ks * MS + (rowg - MP) + ai * HALF + m * 16) * DM + colw, DM, fr, fq, pk[0], pk[1]);
;                 else {
.LBB0_1599:
	s_andn2_b64 vcc, exec, s[42:43]
	s_cbranch_vccnz .LBB0_1601
	s_mov_b32 s63, s81
	s_lshl_b64 s[22:23], s[62:63], 22
	s_lshl_b64 s[42:43], s[40:41], 12
	s_add_u32 s1, s88, s22
	s_addc_u32 s14, s89, s23
	s_add_u32 s1, s1, s42
	s_addc_u32 s14, s14, s43
	s_lshl_b64 s[22:23], s[82:83], 1
	s_add_u32 s22, s1, s22
	s_addc_u32 s23, s14, s23
	v_lshl_add_u64 v[106:107], s[22:23], 0, v[130:131]
	v_mov_b32_e32 v151, v131
	v_lshl_add_u64 v[106:107], v[106:107], 0, v[150:151]
	v_mov_b32_e32 v149, v131
	v_mov_b32_e32 v102, v131
	v_mov_b32_e32 v103, v131
	v_mov_b32_e32 v104, v131
	v_mov_b32_e32 v105, v131
	v_lshl_add_u64 v[106:107], v[106:107], 0, v[148:149]
	v_mov_b32_dpp v102, v125 row_ror:8 row_mask:0xf bank_mask:0xf
	v_mov_b32_dpp v103, v124 row_ror:8 row_mask:0xf bank_mask:0xf
	v_mov_b32_dpp v104, v123 row_ror:8 row_mask:0xf bank_mask:0xf
	v_mov_b32_dpp v105, v122 row_ror:8 row_mask:0xf bank_mask:0xf
	v_add_co_u32_e32 v108, vcc, 0x30000, v106
	v_cndmask_b32_e64 v98, v102, v114, s[52:53]
	s_waitcnt lgkmcnt(0)
	v_cndmask_b32_e64 v99, v103, v115, s[52:53]
	v_cndmask_b32_e64 v100, v104, v116, s[52:53]
	v_cndmask_b32_e64 v101, v105, v117, s[52:53]
	v_addc_co_u32_e32 v109, vcc, 0, v107, vcc
	global_store_dwordx4 v[108:109], v[98:101], off
	v_cndmask_b32_e64 v102, v118, v102, s[52:53]
	v_cndmask_b32_e64 v103, v119, v103, s[52:53]
	v_add_co_u32_e32 v98, vcc, 0x38000, v106
	v_cndmask_b32_e64 v104, v120, v104, s[52:53]
	v_cndmask_b32_e64 v105, v121, v105, s[52:53]
	v_addc_co_u32_e32 v99, vcc, 0, v107, vcc
	global_store_dwordx4 v[98:99], v[102:105], off
; __device__ __forceinline__ u32x4 pack8(f32x4 a, f32x4 b) { u32x4 w; w.x = cvtpk(a[0], a[1]); w.y = cvtpk(a[2], a[3]); w.z = cvtpk(b[0], b[1]); w.w = cvtpk(b[2], b[3]); return w; }
;     __device__ __forceinline__ void operator()(f32x4 (&acc)[2][2][4][2], const Unit& u, int wr, int wc, int fr, int fq) const {
;     ...
;                 const int row = row0 + ai * HALF + m * 16;
;                 const float sr = rv[ai * 4 + m];
;                 float s = 0.f; u32x4 pk[2];
; #pragma unroll
;                 for (int bj = 0; bj < 2; ++bj) {
;                     const v4i_t i0 = __builtin_bit_cast(v4i_t, acc[ai][bj][m][0]) + ov[bj * 2], i1 = __builtin_bit_cast(v4i_t, acc[ai][bj][m][1]) + ov[bj * 2 + 1];
;                     const u32x4 c0_ = cv[bj * 2], c1_ = cv[bj * 2 + 1];
;                     f32x4 v0, v1;
; #pragma unroll
;                     for (int j = 0; j < 4; ++j) { v0[j] = (float)i0[j] * (sr * __uint_as_float(c0_[j])); v1[j] = (float)i1[j] * (sr * __uint_as_float(c1_[j])); }
;                     s += (v0[0] * v0[0] + v0[1] * v0[1]) + (v0[2] * v0[2] + v0[3] * v0[3]) + (v1[0] * v1[0] + v1[1] * v1[1]) + (v1[2] * v1[2] + v1[3] * v1[3]);
;                     pk[bj] = pack8(v0, v1);
;                 }
;                 if (u.ks >= 0) store_pair((bf16_t*)yp + ((size_t)u.ks * MS + (rowg - MP) + ai * HALF + m * 16) * DM + colw, DM, fr, fq, pk[0], pk[1]);
;                 else {
;                     store_pair(Y + (size_t)(rowg + ai * HALF + m * 16) * DM + colw, DM, fr, fq, pk[0], pk[1]);
;                     s += __shfl_xor(s, 16); s += __shfl_xor(s, 32);
;                     if (fq == 0) ssy[(size_t)row * 32 + u.pn * 4 + wc] = s;
;                 }
.LBB0_1601:
	v_add_u32_e32 v94, v78, v94
	v_add_u32_e32 v95, v79, v95
	v_cvt_f32_i32_e32 v95, v95
	v_cvt_f32_i32_e32 v94, v94
	v_mul_f32_e32 v102, 0x38018388, v191
	s_waitcnt lgkmcnt(0)
	v_pk_mul_f32 v[98:99], v[66:67], v[102:103] op_sel_hi:[1,0]
	v_pk_mul_f32 v[100:101], v[62:63], v[102:103] op_sel_hi:[1,0]
	v_add_u32_e32 v103, v80, v96
	v_add_u32_e32 v104, v81, v97
	v_pk_mul_f32 v[94:95], v[98:99], v[94:95]
	v_cvt_f32_i32_e32 v99, v104
	v_cvt_f32_i32_e32 v98, v103
	v_add_u32_e32 v86, v74, v86
	v_add_u32_e32 v87, v75, v87
	v_cvt_f32_i32_e32 v87, v87
	v_cvt_f32_i32_e32 v86, v86
	v_add_u32_e32 v105, v72, v92
	v_add_u32_e32 v106, v73, v93
	v_pk_mul_f32 v[92:93], v[68:69], v[102:103] op_sel_hi:[1,0]
	v_pk_mul_f32 v[96:97], v[64:65], v[102:103] op_sel_hi:[1,0]
	v_pk_mul_f32 v[92:93], v[92:93], v[98:99]
	v_cvt_f32_i32_e32 v99, v106
	v_cvt_f32_i32_e32 v98, v105
	v_pk_mul_f32 v[104:105], v[54:55], v[102:103] op_sel_hi:[1,0]
	v_pk_mul_f32 v[106:107], v[50:51], v[102:103] op_sel_hi:[1,0]
	v_add_u32_e32 v108, v76, v88
	v_add_u32_e32 v103, v77, v89
	v_pk_mul_f32 v[86:87], v[104:105], v[86:87]
	v_add_u32_e32 v104, v60, v84
	v_add_u32_e32 v105, v61, v85
	v_pk_mul_f32 v[84:85], v[56:57], v[102:103] op_sel_hi:[1,0]
	v_pk_mul_f32 v[88:89], v[52:53], v[102:103] op_sel_hi:[1,0]
	v_cvt_f32_i32_e32 v103, v103
	v_cvt_f32_i32_e32 v102, v108
	v_add_u32_e32 v90, v70, v90
	v_add_u32_e32 v91, v71, v91
	v_add_u32_e32 v82, v58, v82
	v_add_u32_e32 v83, v59, v83
	v_cvt_f32_i32_e32 v91, v91
	v_cvt_f32_i32_e32 v90, v90
	v_cvt_f32_i32_e32 v83, v83
	v_cvt_f32_i32_e32 v82, v82
	v_pk_mul_f32 v[84:85], v[84:85], v[102:103]
	v_cvt_f32_i32_e32 v103, v105
	v_cvt_f32_i32_e32 v102, v104
	v_pk_mul_f32 v[90:91], v[100:101], v[90:91]
	v_pk_mul_f32 v[96:97], v[96:97], v[98:99]
	v_pk_mul_f32 v[82:83], v[106:107], v[82:83]
	v_pk_mul_f32 v[88:89], v[88:89], v[102:103]
	v_cvt_pk_bf16_f32 v98, v94, v95
	v_cvt_pk_bf16_f32 v99, v92, v93
	v_cvt_pk_bf16_f32 v100, v90, v91
	v_cvt_pk_bf16_f32 v101, v96, v97
	v_cvt_pk_bf16_f32 v102, v86, v87
	v_cvt_pk_bf16_f32 v103, v84, v85
	v_cvt_pk_bf16_f32 v104, v82, v83
	v_cvt_pk_bf16_f32 v105, v88, v89
	s_mov_b64 s[42:43], -1
	s_and_b64 vcc, exec, s[56:57]
	v_cndmask_b32_e64 v109, v98, v102, s[52:53]
	v_cndmask_b32_e64 v108, v99, v103, s[52:53]
	v_cndmask_b32_e64 v107, v100, v104, s[52:53]
	v_cndmask_b32_e64 v106, v101, v105, s[52:53]
	s_cbranch_vccnz .LBB0_1605
	v_pk_mul_f32 v[86:87], v[86:87], v[86:87]
	v_pk_mul_f32 v[84:85], v[84:85], v[84:85]
	s_ashr_i32 s1, s0, 31
	v_pk_mul_f32 v[82:83], v[82:83], v[82:83]
	v_add_f32_e32 v84, v84, v85
	v_add_f32_e32 v85, v86, v87
	s_lshl_b64 s[22:23], s[0:1], 12
	v_readlane_b32 s1, v249, 28
	v_pk_mul_f32 v[88:89], v[88:89], v[88:89]
	v_add_f32_e32 v84, v85, v84
	v_add_f32_e32 v82, v82, v83
	s_add_u32 s1, s1, s22
	v_readlane_b32 s14, v253, 5
	v_pk_mul_f32 v[94:95], v[94:95], v[94:95]
	v_pk_mul_f32 v[92:93], v[92:93], v[92:93]
	v_add_f32_e32 v82, v82, v84
	v_add_f32_e32 v83, v88, v89
	s_addc_u32 s14, s14, s23
	s_lshl_b64 s[22:23], s[82:83], 1
	v_pk_mul_f32 v[90:91], v[90:91], v[90:91]
	v_add_f32_e32 v82, v83, v82
	v_add_f32_e32 v83, v92, v93
	v_add_f32_e32 v84, v94, v95
	s_add_u32 s22, s1, s22
	v_and_b32_e32 v93, 64, v204
	v_pk_mul_f32 v[96:97], v[96:97], v[96:97]
	v_add_f32_e32 v83, v84, v83
	v_add_f32_e32 v84, v90, v91
	s_addc_u32 s23, s14, s23
	v_xor_b32_e32 v92, 16, v204
	v_add_u32_e32 v95, 64, v93
	v_add_f32_e32 v83, v84, v83
	v_add_f32_e32 v84, v96, v97
	v_lshl_add_u64 v[90:91], s[22:23], 0, v[130:131]
	v_mov_b32_e32 v151, v131
	v_cmp_lt_i32_e32 vcc, v92, v95
	v_add_f32_e32 v83, v84, v83
	v_lshl_add_u64 v[90:91], v[90:91], 0, v[150:151]
	v_mov_b32_e32 v149, v131
	v_cndmask_b32_e32 v92, v204, v92, vcc
	v_add_f32_e32 v94, v83, v82
	v_mov_b32_e32 v86, v131
	v_mov_b32_e32 v87, v131
	v_mov_b32_e32 v88, v131
	v_mov_b32_e32 v89, v131
	v_lshl_add_u64 v[90:91], v[90:91], 0, v[148:149]
	v_lshlrev_b32_e32 v92, 2, v92
	s_mov_b32 s1, 0x80000
	v_mov_b32_dpp v86, v109 row_ror:8 row_mask:0xf bank_mask:0xf
	v_mov_b32_dpp v87, v108 row_ror:8 row_mask:0xf bank_mask:0xf
	v_mov_b32_dpp v88, v107 row_ror:8 row_mask:0xf bank_mask:0xf
	v_mov_b32_dpp v89, v106 row_ror:8 row_mask:0xf bank_mask:0xf
	ds_bpermute_b32 v96, v92, v94
	v_add_co_u32_e32 v92, vcc, s1, v90
	v_cndmask_b32_e64 v82, v86, v98, s[52:53]
	v_cndmask_b32_e64 v83, v87, v99, s[52:53]
	v_cndmask_b32_e64 v84, v88, v100, s[52:53]
	v_cndmask_b32_e64 v85, v89, v101, s[52:53]
	v_addc_co_u32_e32 v93, vcc, 0, v91, vcc
	global_store_dwordx4 v[92:93], v[82:85], off
	s_mov_b32 s1, 0x88000
	v_cndmask_b32_e64 v86, v102, v86, s[52:53]
	v_xor_b32_e32 v83, 32, v204
	v_cmp_lt_i32_e32 vcc, v83, v95
	s_waitcnt lgkmcnt(0)
	v_add_f32_e32 v82, v94, v96
	v_cndmask_b32_e64 v87, v103, v87, s[52:53]
	v_cndmask_b32_e32 v83, v204, v83, vcc
	v_lshlrev_b32_e32 v83, 2, v83
	ds_bpermute_b32 v83, v83, v82
	v_add_co_u32_e32 v84, vcc, s1, v90
	v_cndmask_b32_e64 v88, v104, v88, s[52:53]
	v_cndmask_b32_e64 v89, v105, v89, s[52:53]
	v_addc_co_u32_e32 v85, vcc, 0, v91, vcc
	global_store_dwordx4 v[84:85], v[86:89], off
	s_and_saveexec_b64 s[42:43], s[54:55]
	s_cbranch_execz .LBB0_1604
	v_readlane_b32 s44, v253, 6
	v_lshlrev_b64 v[84:85], 7, v[182:183]
	s_lshl_b32 s22, s21, 2
	v_readlane_b32 s45, v253, 7
	s_waitcnt lgkmcnt(0)
	v_add_f32_e32 v86, v82, v83
	s_ashr_i32 s23, s22, 31
	v_lshl_add_u64 v[82:83], s[44:45], 0, v[84:85]
	v_lshl_add_u64 v[82:83], s[22:23], 2, v[82:83]
	s_lshl_b32 s80, s38, 2
	v_lshl_add_u64 v[82:83], v[82:83], 0, s[80:81]
	v_add_co_u32_e32 v82, vcc, 0x4000, v82
	s_nop 1
	v_addc_co_u32_e32 v83, vcc, 0, v83, vcc
	global_store_dword v[82:83], v86, off

; __device__ __forceinline__ unsigned dpp_ror8(unsigned v) { return (unsigned)__builtin_amdgcn_update_dpp(0, (int)v, 0x128, 0xF, 0xF, false); }
; __device__ __forceinline__ void store_pair(bf16_t* grp  , size_t ld, int fr, int fq, u32x4 P0, u32x4 P1) {
;     const bool up = (fr & 8) != 0;
;     u32x4 snd, rcv;
;     snd.x = up ? P0.x : P1.x; snd.y = up ? P0.y : P1.y; snd.z = up ? P0.z : P1.z; snd.w = up ? P0.w : P1.w;
;     rcv.x = dpp_ror8(snd.x); rcv.y = dpp_ror8(snd.y); rcv.z = dpp_ror8(snd.z); rcv.w = dpp_ror8(snd.w);
;     u32x4 dA, dB;
;     dA.x = up ? rcv.x : P0.x; dA.y = up ? rcv.y : P0.y; dA.z = up ? rcv.z : P0.z; dA.w = up ? rcv.w : P0.w;
;     dB.x = up ? P1.x : rcv.x; dB.y = up ? P1.y : rcv.y; dB.z = up ? P1.z : rcv.z; dB.w = up ? P1.w : rcv.w;
;     bf16_t* p = grp + (size_t)(fr & 7) * ld + (up ? CBJ : 0) + 8 * fq;
;     __builtin_nontemporal_store(dA, (u32x4*)p); __builtin_nontemporal_store(dB, (u32x4*)(p + 8 * ld));
;     __device__ __forceinline__ void operator()(f32x4 (&acc)[2][2][4][2], const Unit& u, int wr, int wc, int fr, int fq) const {
;     ...
;                 if (u.ks >= 0) store_pair((bf16_t*)yp + ((size_t)u.ks * MS + (rowg - MP) + ai * HALF + m * 16) * DM + colw, DM, fr, fq, pk[0], pk[1]);
;                 else {
.LBB0_1605:
	s_andn2_b64 vcc, exec, s[42:43]
	s_cbranch_vccnz .LBB0_1607
	s_mov_b32 s63, s81
	s_lshl_b64 s[22:23], s[62:63], 22
	s_lshl_b64 s[42:43], s[40:41], 12
	s_add_u32 s1, s88, s22
	s_addc_u32 s14, s89, s23
	s_add_u32 s1, s1, s42
	s_addc_u32 s14, s14, s43
	s_lshl_b64 s[22:23], s[82:83], 1
	s_add_u32 s22, s1, s22
	s_addc_u32 s23, s14, s23
	v_lshl_add_u64 v[90:91], s[22:23], 0, v[130:131]
	v_mov_b32_e32 v151, v131
	v_lshl_add_u64 v[90:91], v[90:91], 0, v[150:151]
	v_mov_b32_e32 v149, v131
	v_mov_b32_e32 v86, v131
	v_mov_b32_e32 v87, v131
	v_mov_b32_e32 v88, v131
	v_mov_b32_e32 v89, v131
	v_lshl_add_u64 v[90:91], v[90:91], 0, v[148:149]
	v_mov_b32_dpp v86, v109 row_ror:8 row_mask:0xf bank_mask:0xf
	v_mov_b32_dpp v87, v108 row_ror:8 row_mask:0xf bank_mask:0xf
	v_mov_b32_dpp v88, v107 row_ror:8 row_mask:0xf bank_mask:0xf
	v_mov_b32_dpp v89, v106 row_ror:8 row_mask:0xf bank_mask:0xf
	v_add_co_u32_e32 v92, vcc, 0x80000, v90
	v_cndmask_b32_e64 v82, v86, v98, s[52:53]
	s_waitcnt lgkmcnt(0)
	v_cndmask_b32_e64 v83, v87, v99, s[52:53]
	v_cndmask_b32_e64 v84, v88, v100, s[52:53]
	v_cndmask_b32_e64 v85, v89, v101, s[52:53]
	v_addc_co_u32_e32 v93, vcc, 0, v91, vcc
	global_store_dwordx4 v[92:93], v[82:85], off
	v_cndmask_b32_e64 v86, v102, v86, s[52:53]
	v_cndmask_b32_e64 v87, v103, v87, s[52:53]
	v_add_co_u32_e32 v82, vcc, 0x88000, v90
	v_cndmask_b32_e64 v88, v104, v88, s[52:53]
	v_cndmask_b32_e64 v89, v105, v89, s[52:53]
	v_addc_co_u32_e32 v83, vcc, 0, v91, vcc
	global_store_dwordx4 v[82:83], v[86:89], off
; __device__ __forceinline__ void store_pair(bf16_t* grp  , size_t ld, int fr, int fq, u32x4 P0, u32x4 P1) {
;     const bool up = (fr & 8) != 0;
;     u32x4 snd, rcv;
;     snd.x = up ? P0.x : P1.x; snd.y = up ? P0.y : P1.y; snd.z = up ? P0.z : P1.z; snd.w = up ? P0.w : P1.w;
;     rcv.x = dpp_ror8(snd.x); rcv.y = dpp_ror8(snd.y); rcv.z = dpp_ror8(snd.z); rcv.w = dpp_ror8(snd.w);
;     u32x4 dA, dB;
;     dA.x = up ? rcv.x : P0.x; dA.y = up ? rcv.y : P0.y; dA.z = up ? rcv.z : P0.z; dA.w = up ? rcv.w : P0.w;
;     dB.x = up ? P1.x : rcv.x; dB.y = up ? P1.y : rcv.y; dB.z = up ? P1.z : rcv.z; dB.w = up ? P1.w : rcv.w;
;     bf16_t* p = grp + (size_t)(fr & 7) * ld + (up ? CBJ : 0) + 8 * fq;
;     __builtin_nontemporal_store(dA, (u32x4*)p); __builtin_nontemporal_store(dB, (u32x4*)(p + 8 * ld));
;     __device__ __forceinline__ void operator()(f32x4 (&acc)[2][2][4][2], const Unit& u, int wr, int wc, int fr, int fq) const {
;     ...
;                 const int row = row0 + ai * HALF + m * 16;
;                 const float sr = rv[ai * 4 + m];
;                 float s = 0.f; u32x4 pk[2];
; #pragma unroll
;                 for (int bj = 0; bj < 2; ++bj) {
;                     const v4i_t i0 = __builtin_bit_cast(v4i_t, acc[ai][bj][m][0]) + ov[bj * 2], i1 = __builtin_bit_cast(v4i_t, acc[ai][bj][m][1]) + ov[bj * 2 + 1];
;                     const u32x4 c0_ = cv[bj * 2], c1_ = cv[bj * 2 + 1];
;                     f32x4 v0, v1;
; #pragma unroll
;                     for (int j = 0; j < 4; ++j) { v0[j] = (float)i0[j] * (sr * __uint_as_float(c0_[j])); v1[j] = (float)i1[j] * (sr * __uint_as_float(c1_[j])); }
;                     s += (v0[0] * v0[0] + v0[1] * v0[1]) + (v0[2] * v0[2] + v0[3] * v0[3]) + (v1[0] * v1[0] + v1[1] * v1[1]) + (v1[2] * v1[2] + v1[3] * v1[3]);
;                     pk[bj] = pack8(v0, v1);
;                 }
;                 if (u.ks >= 0) store_pair((bf16_t*)yp + ((size_t)u.ks * MS + (rowg - MP) + ai * HALF + m * 16) * DM + colw, DM, fr, fq, pk[0], pk[1]);
;                 else {
;                     store_pair(Y + (size_t)(rowg + ai * HALF + m * 16) * DM + colw, DM, fr, fq, pk[0], pk[1]);
;                     s += __shfl_xor(s, 16); s += __shfl_xor(s, 32);
;                     if (fq == 0) ssy[(size_t)row * 32 + u.pn * 4 + wc] = s;
;                 }
.LBB0_1607:
	v_add_u32_e32 v46, v78, v46
	v_add_u32_e32 v47, v79, v47
	v_cvt_f32_i32_e32 v47, v47
	v_cvt_f32_i32_e32 v46, v46
	v_mul_f32_e32 v86, 0x38018388, v190
	s_waitcnt lgkmcnt(0)
	v_pk_mul_f32 v[82:83], v[66:67], v[86:87] op_sel_hi:[1,0]
	v_pk_mul_f32 v[84:85], v[62:63], v[86:87] op_sel_hi:[1,0]
	v_add_u32_e32 v87, v80, v48
	v_add_u32_e32 v88, v81, v49
	v_pk_mul_f32 v[46:47], v[82:83], v[46:47]
	v_cvt_f32_i32_e32 v83, v88
	v_cvt_f32_i32_e32 v82, v87
	v_add_u32_e32 v38, v74, v38
	v_add_u32_e32 v39, v75, v39
	v_cvt_f32_i32_e32 v39, v39
	v_cvt_f32_i32_e32 v38, v38
	v_add_u32_e32 v89, v72, v44
	v_add_u32_e32 v90, v73, v45
	v_pk_mul_f32 v[44:45], v[68:69], v[86:87] op_sel_hi:[1,0]
	v_pk_mul_f32 v[48:49], v[64:65], v[86:87] op_sel_hi:[1,0]
	v_pk_mul_f32 v[44:45], v[44:45], v[82:83]
	v_cvt_f32_i32_e32 v83, v90
	v_cvt_f32_i32_e32 v82, v89
	v_pk_mul_f32 v[88:89], v[54:55], v[86:87] op_sel_hi:[1,0]
	v_pk_mul_f32 v[90:91], v[50:51], v[86:87] op_sel_hi:[1,0]
	v_add_u32_e32 v92, v76, v40
	v_add_u32_e32 v87, v77, v41
	v_pk_mul_f32 v[38:39], v[88:89], v[38:39]
	v_add_u32_e32 v88, v60, v36
	v_add_u32_e32 v89, v61, v37
	v_pk_mul_f32 v[36:37], v[56:57], v[86:87] op_sel_hi:[1,0]
	v_pk_mul_f32 v[40:41], v[52:53], v[86:87] op_sel_hi:[1,0]
	v_cvt_f32_i32_e32 v87, v87
	v_cvt_f32_i32_e32 v86, v92
	v_add_u32_e32 v42, v70, v42
	v_add_u32_e32 v43, v71, v43
	v_add_u32_e32 v34, v58, v34
	v_add_u32_e32 v35, v59, v35
	v_cvt_f32_i32_e32 v43, v43
	v_cvt_f32_i32_e32 v42, v42
	v_cvt_f32_i32_e32 v35, v35
	v_cvt_f32_i32_e32 v34, v34
	v_pk_mul_f32 v[36:37], v[36:37], v[86:87]
	v_cvt_f32_i32_e32 v87, v89
	v_cvt_f32_i32_e32 v86, v88
	v_pk_mul_f32 v[42:43], v[84:85], v[42:43]
	v_pk_mul_f32 v[48:49], v[48:49], v[82:83]
	v_pk_mul_f32 v[34:35], v[90:91], v[34:35]
	v_pk_mul_f32 v[40:41], v[40:41], v[86:87]
	v_cvt_pk_bf16_f32 v82, v46, v47
	v_cvt_pk_bf16_f32 v83, v44, v45
	v_cvt_pk_bf16_f32 v84, v42, v43
	v_cvt_pk_bf16_f32 v85, v48, v49
	v_cvt_pk_bf16_f32 v86, v38, v39
	v_cvt_pk_bf16_f32 v87, v36, v37
	v_cvt_pk_bf16_f32 v88, v34, v35
	v_cvt_pk_bf16_f32 v89, v40, v41
	s_mov_b64 s[42:43], -1
	s_and_b64 vcc, exec, s[56:57]
	v_cndmask_b32_e64 v93, v82, v86, s[52:53]
	v_cndmask_b32_e64 v92, v83, v87, s[52:53]
	v_cndmask_b32_e64 v91, v84, v88, s[52:53]
	v_cndmask_b32_e64 v90, v85, v89, s[52:53]
	s_cbranch_vccnz .LBB0_1611
	v_pk_mul_f32 v[38:39], v[38:39], v[38:39]
	v_pk_mul_f32 v[36:37], v[36:37], v[36:37]
	s_ashr_i32 s1, s0, 31
	v_pk_mul_f32 v[34:35], v[34:35], v[34:35]
	v_add_f32_e32 v36, v36, v37
	v_add_f32_e32 v37, v38, v39
	s_lshl_b64 s[22:23], s[0:1], 12
	v_readlane_b32 s1, v249, 28
	v_pk_mul_f32 v[40:41], v[40:41], v[40:41]
	v_add_f32_e32 v36, v37, v36
	v_add_f32_e32 v34, v34, v35
	s_add_u32 s1, s1, s22
	v_readlane_b32 s14, v253, 5
	v_pk_mul_f32 v[46:47], v[46:47], v[46:47]
	v_pk_mul_f32 v[44:45], v[44:45], v[44:45]
	v_add_f32_e32 v34, v34, v36
	v_add_f32_e32 v35, v40, v41
	s_addc_u32 s14, s14, s23
	s_lshl_b64 s[22:23], s[82:83], 1
	v_pk_mul_f32 v[42:43], v[42:43], v[42:43]
	v_add_f32_e32 v34, v35, v34
	v_add_f32_e32 v35, v44, v45
	v_add_f32_e32 v36, v46, v47
	s_add_u32 s22, s1, s22
	v_and_b32_e32 v45, 64, v204
	v_pk_mul_f32 v[48:49], v[48:49], v[48:49]
	v_add_f32_e32 v35, v36, v35
	v_add_f32_e32 v36, v42, v43
	s_addc_u32 s23, s14, s23
	v_xor_b32_e32 v44, 16, v204
	v_add_u32_e32 v47, 64, v45
	v_add_f32_e32 v35, v36, v35
	v_add_f32_e32 v36, v48, v49
	v_lshl_add_u64 v[42:43], s[22:23], 0, v[130:131]
	v_mov_b32_e32 v151, v131
	v_cmp_lt_i32_e32 vcc, v44, v47
	v_add_f32_e32 v35, v36, v35
	v_lshl_add_u64 v[42:43], v[42:43], 0, v[150:151]
	v_mov_b32_e32 v149, v131
	v_cndmask_b32_e32 v44, v204, v44, vcc
	v_add_f32_e32 v46, v35, v34
	v_mov_b32_e32 v38, v131
	v_mov_b32_e32 v39, v131
	v_mov_b32_e32 v40, v131
	v_mov_b32_e32 v41, v131
	v_lshl_add_u64 v[42:43], v[42:43], 0, v[148:149]
	v_lshlrev_b32_e32 v44, 2, v44
	s_mov_b32 s1, 0x90000
	v_mov_b32_dpp v38, v93 row_ror:8 row_mask:0xf bank_mask:0xf
	v_mov_b32_dpp v39, v92 row_ror:8 row_mask:0xf bank_mask:0xf
	v_mov_b32_dpp v40, v91 row_ror:8 row_mask:0xf bank_mask:0xf
	v_mov_b32_dpp v41, v90 row_ror:8 row_mask:0xf bank_mask:0xf
	ds_bpermute_b32 v48, v44, v46
	v_add_co_u32_e32 v44, vcc, s1, v42
	v_cndmask_b32_e64 v34, v38, v82, s[52:53]
	v_cndmask_b32_e64 v35, v39, v83, s[52:53]
	v_cndmask_b32_e64 v36, v40, v84, s[52:53]
	v_cndmask_b32_e64 v37, v41, v85, s[52:53]
	v_addc_co_u32_e32 v45, vcc, 0, v43, vcc
	global_store_dwordx4 v[44:45], v[34:37], off
	s_mov_b32 s1, 0x98000
	v_cndmask_b32_e64 v38, v86, v38, s[52:53]
	v_xor_b32_e32 v35, 32, v204
	v_cmp_lt_i32_e32 vcc, v35, v47
	s_waitcnt lgkmcnt(0)
	v_add_f32_e32 v34, v46, v48
	v_cndmask_b32_e64 v39, v87, v39, s[52:53]
	v_cndmask_b32_e32 v35, v204, v35, vcc
	v_lshlrev_b32_e32 v35, 2, v35
	ds_bpermute_b32 v35, v35, v34
	v_add_co_u32_e32 v36, vcc, s1, v42
	v_cndmask_b32_e64 v40, v88, v40, s[52:53]
	v_cndmask_b32_e64 v41, v89, v41, s[52:53]
	v_addc_co_u32_e32 v37, vcc, 0, v43, vcc
	global_store_dwordx4 v[36:37], v[38:41], off
	s_and_saveexec_b64 s[42:43], s[54:55]
	s_cbranch_execz .LBB0_1610
	v_readlane_b32 s44, v253, 6
	s_waitcnt lgkmcnt(0)
	v_add_f32_e32 v36, v34, v35
	v_lshlrev_b64 v[34:35], 7, v[182:183]
	s_lshl_b32 s22, s21, 2
	v_readlane_b32 s45, v253, 7
	s_ashr_i32 s23, s22, 31
	s_lshl_b32 s80, s38, 2
	v_lshl_add_u64 v[34:35], s[44:45], 0, v[34:35]
	v_lshl_add_u64 v[34:35], s[22:23], 2, v[34:35]
	v_lshl_add_u64 v[34:35], v[34:35], 0, s[80:81]
	v_add_co_u32_e32 v34, vcc, 0x4000, v34
	s_nop 1
	v_addc_co_u32_e32 v35, vcc, 0, v35, vcc
	global_store_dword v[34:35], v36, off offset:2048

; __device__ __forceinline__ unsigned dpp_ror8(unsigned v) { return (unsigned)__builtin_amdgcn_update_dpp(0, (int)v, 0x128, 0xF, 0xF, false); }
; __device__ __forceinline__ void store_pair(bf16_t* grp  , size_t ld, int fr, int fq, u32x4 P0, u32x4 P1) {
;     const bool up = (fr & 8) != 0;
;     u32x4 snd, rcv;
;     snd.x = up ? P0.x : P1.x; snd.y = up ? P0.y : P1.y; snd.z = up ? P0.z : P1.z; snd.w = up ? P0.w : P1.w;
;     rcv.x = dpp_ror8(snd.x); rcv.y = dpp_ror8(snd.y); rcv.z = dpp_ror8(snd.z); rcv.w = dpp_ror8(snd.w);
;     u32x4 dA, dB;
;     dA.x = up ? rcv.x : P0.x; dA.y = up ? rcv.y : P0.y; dA.z = up ? rcv.z : P0.z; dA.w = up ? rcv.w : P0.w;
;     dB.x = up ? P1.x : rcv.x; dB.y = up ? P1.y : rcv.y; dB.z = up ? P1.z : rcv.z; dB.w = up ? P1.w : rcv.w;
;     bf16_t* p = grp + (size_t)(fr & 7) * ld + (up ? CBJ : 0) + 8 * fq;
;     __builtin_nontemporal_store(dA, (u32x4*)p); __builtin_nontemporal_store(dB, (u32x4*)(p + 8 * ld));
;     __device__ __forceinline__ void operator()(f32x4 (&acc)[2][2][4][2], const Unit& u, int wr, int wc, int fr, int fq) const {
;     ...
;                 if (u.ks >= 0) store_pair((bf16_t*)yp + ((size_t)u.ks * MS + (rowg - MP) + ai * HALF + m * 16) * DM + colw, DM, fr, fq, pk[0], pk[1]);
;                 else {
;                     store_pair(Y + (size_t)(rowg + ai * HALF + m * 16) * DM + colw, DM, fr, fq, pk[0], pk[1]);
;                     s += __shfl_xor(s, 16); s += __shfl_xor(s, 32);
;                     if (fq == 0) ssy[(size_t)row * 32 + u.pn * 4 + wc] = s;
;                 }
.LBB0_1611:
	s_andn2_b64 vcc, exec, s[42:43]
	s_cbranch_vccnz .LBB0_1613
	s_mov_b32 s63, s81
	s_lshl_b64 s[22:23], s[62:63], 22
	s_lshl_b64 s[42:43], s[40:41], 12
	s_add_u32 s1, s88, s22
	s_addc_u32 s14, s89, s23
	s_add_u32 s1, s1, s42
	s_addc_u32 s14, s14, s43
	s_lshl_b64 s[22:23], s[82:83], 1
	s_add_u32 s22, s1, s22
	s_addc_u32 s23, s14, s23
	v_lshl_add_u64 v[42:43], s[22:23], 0, v[130:131]
	v_mov_b32_e32 v151, v131
	v_lshl_add_u64 v[42:43], v[42:43], 0, v[150:151]
	v_mov_b32_e32 v149, v131
	v_mov_b32_e32 v38, v131
	v_mov_b32_e32 v39, v131
	v_mov_b32_e32 v40, v131
	v_mov_b32_e32 v41, v131
	v_lshl_add_u64 v[42:43], v[42:43], 0, v[148:149]
	v_mov_b32_dpp v38, v93 row_ror:8 row_mask:0xf bank_mask:0xf
	v_mov_b32_dpp v39, v92 row_ror:8 row_mask:0xf bank_mask:0xf
	v_mov_b32_dpp v40, v91 row_ror:8 row_mask:0xf bank_mask:0xf
	v_mov_b32_dpp v41, v90 row_ror:8 row_mask:0xf bank_mask:0xf
	v_add_co_u32_e32 v44, vcc, 0x90000, v42
	v_cndmask_b32_e64 v34, v38, v82, s[52:53]
	s_waitcnt lgkmcnt(0)
	v_cndmask_b32_e64 v35, v39, v83, s[52:53]
	v_cndmask_b32_e64 v36, v40, v84, s[52:53]
	v_cndmask_b32_e64 v37, v41, v85, s[52:53]
	v_addc_co_u32_e32 v45, vcc, 0, v43, vcc
	global_store_dwordx4 v[44:45], v[34:37], off
	v_cndmask_b32_e64 v38, v86, v38, s[52:53]
	v_cndmask_b32_e64 v39, v87, v39, s[52:53]
	v_add_co_u32_e32 v34, vcc, 0x98000, v42
	v_cndmask_b32_e64 v40, v88, v40, s[52:53]
	v_cndmask_b32_e64 v41, v89, v41, s[52:53]
	v_addc_co_u32_e32 v35, vcc, 0, v43, vcc
	global_store_dwordx4 v[34:35], v[38:41], off
.LBB0_1613:
	v_add_u32_e32 v30, v78, v30
	v_add_u32_e32 v31, v79, v31
	v_cvt_f32_i32_e32 v31, v31
	v_cvt_f32_i32_e32 v30, v30
	v_mul_f32_e32 v38, 0x38018388, v189
	s_waitcnt lgkmcnt(0)
	v_pk_mul_f32 v[34:35], v[66:67], v[38:39] op_sel_hi:[1,0]
	v_pk_mul_f32 v[36:37], v[62:63], v[38:39] op_sel_hi:[1,0]
	v_add_u32_e32 v39, v80, v32
	v_add_u32_e32 v40, v81, v33
	v_pk_mul_f32 v[30:31], v[34:35], v[30:31]
	v_cvt_f32_i32_e32 v35, v40
	v_cvt_f32_i32_e32 v34, v39
	v_add_u32_e32 v22, v74, v22
	v_add_u32_e32 v23, v75, v23
	v_cvt_f32_i32_e32 v23, v23
	v_cvt_f32_i32_e32 v22, v22
	v_add_u32_e32 v41, v72, v28
	v_add_u32_e32 v42, v73, v29
	v_pk_mul_f32 v[28:29], v[68:69], v[38:39] op_sel_hi:[1,0]
	v_pk_mul_f32 v[32:33], v[64:65], v[38:39] op_sel_hi:[1,0]
	v_pk_mul_f32 v[28:29], v[28:29], v[34:35]
	v_cvt_f32_i32_e32 v35, v42
	v_cvt_f32_i32_e32 v34, v41
	v_pk_mul_f32 v[40:41], v[54:55], v[38:39] op_sel_hi:[1,0]
	v_pk_mul_f32 v[42:43], v[50:51], v[38:39] op_sel_hi:[1,0]
	v_add_u32_e32 v44, v76, v24
	v_add_u32_e32 v39, v77, v25
	v_pk_mul_f32 v[22:23], v[40:41], v[22:23]
	v_add_u32_e32 v40, v60, v20
	v_add_u32_e32 v41, v61, v21
	v_pk_mul_f32 v[20:21], v[56:57], v[38:39] op_sel_hi:[1,0]
	v_pk_mul_f32 v[24:25], v[52:53], v[38:39] op_sel_hi:[1,0]
	v_cvt_f32_i32_e32 v39, v39
	v_cvt_f32_i32_e32 v38, v44
	v_add_u32_e32 v26, v70, v26
	v_add_u32_e32 v27, v71, v27
	v_add_u32_e32 v18, v58, v18
	v_add_u32_e32 v19, v59, v19
	v_cvt_f32_i32_e32 v27, v27
	v_cvt_f32_i32_e32 v26, v26
	v_cvt_f32_i32_e32 v19, v19
	v_cvt_f32_i32_e32 v18, v18
	v_pk_mul_f32 v[20:21], v[20:21], v[38:39]
	v_cvt_f32_i32_e32 v39, v41
	v_cvt_f32_i32_e32 v38, v40
	v_pk_mul_f32 v[26:27], v[36:37], v[26:27]
	v_pk_mul_f32 v[32:33], v[32:33], v[34:35]
	v_pk_mul_f32 v[18:19], v[42:43], v[18:19]
	v_pk_mul_f32 v[24:25], v[24:25], v[38:39]
	v_cvt_pk_bf16_f32 v34, v30, v31
	v_cvt_pk_bf16_f32 v35, v28, v29
	v_cvt_pk_bf16_f32 v36, v26, v27
	v_cvt_pk_bf16_f32 v37, v32, v33
	v_cvt_pk_bf16_f32 v38, v22, v23
	v_cvt_pk_bf16_f32 v39, v20, v21
	v_cvt_pk_bf16_f32 v40, v18, v19
	v_cvt_pk_bf16_f32 v41, v24, v25
	s_mov_b64 s[42:43], -1
	s_and_b64 vcc, exec, s[56:57]
	v_cndmask_b32_e64 v45, v34, v38, s[52:53]
	v_cndmask_b32_e64 v44, v35, v39, s[52:53]
	v_cndmask_b32_e64 v43, v36, v40, s[52:53]
	v_cndmask_b32_e64 v42, v37, v41, s[52:53]
	s_cbranch_vccnz .LBB0_1617
	v_pk_mul_f32 v[22:23], v[22:23], v[22:23]
	v_pk_mul_f32 v[20:21], v[20:21], v[20:21]
	s_ashr_i32 s1, s0, 31
	v_pk_mul_f32 v[18:19], v[18:19], v[18:19]
	v_add_f32_e32 v20, v20, v21
	v_add_f32_e32 v21, v22, v23
	s_lshl_b64 s[22:23], s[0:1], 12
	v_readlane_b32 s1, v249, 28
	v_pk_mul_f32 v[24:25], v[24:25], v[24:25]
	v_add_f32_e32 v20, v21, v20
	v_add_f32_e32 v18, v18, v19
	s_add_u32 s1, s1, s22
	v_readlane_b32 s14, v253, 5
	v_pk_mul_f32 v[30:31], v[30:31], v[30:31]
	v_pk_mul_f32 v[28:29], v[28:29], v[28:29]
	v_add_f32_e32 v18, v18, v20
	v_add_f32_e32 v19, v24, v25
	s_addc_u32 s14, s14, s23
	s_lshl_b64 s[22:23], s[82:83], 1
	v_pk_mul_f32 v[26:27], v[26:27], v[26:27]
	v_add_f32_e32 v18, v19, v18
	v_add_f32_e32 v19, v28, v29
	v_add_f32_e32 v20, v30, v31
	s_add_u32 s22, s1, s22
	v_and_b32_e32 v29, 64, v204
	v_pk_mul_f32 v[32:33], v[32:33], v[32:33]
	v_add_f32_e32 v19, v20, v19
	v_add_f32_e32 v20, v26, v27
	s_addc_u32 s23, s14, s23
	v_xor_b32_e32 v28, 16, v204
	v_add_u32_e32 v31, 64, v29
	v_add_f32_e32 v19, v20, v19
	v_add_f32_e32 v20, v32, v33
	v_lshl_add_u64 v[26:27], s[22:23], 0, v[130:131]
	v_mov_b32_e32 v151, v131
	v_cmp_lt_i32_e32 vcc, v28, v31
	v_add_f32_e32 v19, v20, v19
	v_lshl_add_u64 v[26:27], v[26:27], 0, v[150:151]
	v_mov_b32_e32 v149, v131
	v_cndmask_b32_e32 v28, v204, v28, vcc
	v_add_f32_e32 v30, v19, v18
	v_mov_b32_e32 v22, v131
	v_mov_b32_e32 v23, v131
	v_mov_b32_e32 v24, v131
	v_mov_b32_e32 v25, v131
	v_lshl_add_u64 v[26:27], v[26:27], 0, v[148:149]
	v_lshlrev_b32_e32 v28, 2, v28
	s_mov_b32 s1, 0xa0000
	v_mov_b32_dpp v22, v45 row_ror:8 row_mask:0xf bank_mask:0xf
	v_mov_b32_dpp v23, v44 row_ror:8 row_mask:0xf bank_mask:0xf
	v_mov_b32_dpp v24, v43 row_ror:8 row_mask:0xf bank_mask:0xf
	v_mov_b32_dpp v25, v42 row_ror:8 row_mask:0xf bank_mask:0xf
	ds_bpermute_b32 v32, v28, v30
	v_add_co_u32_e32 v28, vcc, s1, v26
	v_cndmask_b32_e64 v18, v22, v34, s[52:53]
	v_cndmask_b32_e64 v19, v23, v35, s[52:53]
	v_cndmask_b32_e64 v20, v24, v36, s[52:53]
	v_cndmask_b32_e64 v21, v25, v37, s[52:53]
	v_addc_co_u32_e32 v29, vcc, 0, v27, vcc
	global_store_dwordx4 v[28:29], v[18:21], off
	s_mov_b32 s1, 0xa8000
	v_cndmask_b32_e64 v22, v38, v22, s[52:53]
	v_xor_b32_e32 v19, 32, v204
	v_cmp_lt_i32_e32 vcc, v19, v31
	s_waitcnt lgkmcnt(0)
	v_add_f32_e32 v18, v30, v32
	v_cndmask_b32_e64 v23, v39, v23, s[52:53]
	v_cndmask_b32_e32 v19, v204, v19, vcc
	v_lshlrev_b32_e32 v19, 2, v19
	ds_bpermute_b32 v19, v19, v18
	v_add_co_u32_e32 v20, vcc, s1, v26
	v_cndmask_b32_e64 v24, v40, v24, s[52:53]
	v_cndmask_b32_e64 v25, v41, v25, s[52:53]
	v_addc_co_u32_e32 v21, vcc, 0, v27, vcc
	global_store_dwordx4 v[20:21], v[22:25], off
	s_and_saveexec_b64 s[42:43], s[54:55]
	s_cbranch_execz .LBB0_1616
	v_readlane_b32 s44, v253, 6
	s_waitcnt lgkmcnt(0)
	v_add_f32_e32 v20, v18, v19
	v_lshlrev_b64 v[18:19], 7, v[182:183]
	s_lshl_b32 s22, s21, 2
	v_readlane_b32 s45, v253, 7
	s_ashr_i32 s23, s22, 31
	s_lshl_b32 s80, s38, 2
	v_lshl_add_u64 v[18:19], s[44:45], 0, v[18:19]
	v_lshl_add_u64 v[18:19], s[22:23], 2, v[18:19]
	v_lshl_add_u64 v[18:19], v[18:19], 0, s[80:81]
	v_add_co_u32_e32 v18, vcc, 0x5000, v18
	s_nop 1
	v_addc_co_u32_e32 v19, vcc, 0, v19, vcc
	global_store_dword v[18:19], v20, off

; __device__ __forceinline__ unsigned dpp_ror8(unsigned v) { return (unsigned)__builtin_amdgcn_update_dpp(0, (int)v, 0x128, 0xF, 0xF, false); }
; __device__ __forceinline__ void store_pair(bf16_t* grp  , size_t ld, int fr, int fq, u32x4 P0, u32x4 P1) {
;     const bool up = (fr & 8) != 0;
;     u32x4 snd, rcv;
;     snd.x = up ? P0.x : P1.x; snd.y = up ? P0.y : P1.y; snd.z = up ? P0.z : P1.z; snd.w = up ? P0.w : P1.w;
;     rcv.x = dpp_ror8(snd.x); rcv.y = dpp_ror8(snd.y); rcv.z = dpp_ror8(snd.z); rcv.w = dpp_ror8(snd.w);
;     u32x4 dA, dB;
;     dA.x = up ? rcv.x : P0.x; dA.y = up ? rcv.y : P0.y; dA.z = up ? rcv.z : P0.z; dA.w = up ? rcv.w : P0.w;
;     dB.x = up ? P1.x : rcv.x; dB.y = up ? P1.y : rcv.y; dB.z = up ? P1.z : rcv.z; dB.w = up ? P1.w : rcv.w;
;     bf16_t* p = grp + (size_t)(fr & 7) * ld + (up ? CBJ : 0) + 8 * fq;
;     __builtin_nontemporal_store(dA, (u32x4*)p); __builtin_nontemporal_store(dB, (u32x4*)(p + 8 * ld));
;     __device__ __forceinline__ void operator()(f32x4 (&acc)[2][2][4][2], const Unit& u, int wr, int wc, int fr, int fq) const {
;     ...
;                 if (u.ks >= 0) store_pair((bf16_t*)yp + ((size_t)u.ks * MS + (rowg - MP) + ai * HALF + m * 16) * DM + colw, DM, fr, fq, pk[0], pk[1]);
;                 else {
;                     store_pair(Y + (size_t)(rowg + ai * HALF + m * 16) * DM + colw, DM, fr, fq, pk[0], pk[1]);
;                     s += __shfl_xor(s, 16); s += __shfl_xor(s, 32);
;                     if (fq == 0) ssy[(size_t)row * 32 + u.pn * 4 + wc] = s;
;                 }
.LBB0_1617:
	s_andn2_b64 vcc, exec, s[42:43]
	s_cbranch_vccnz .LBB0_1619
	s_mov_b32 s63, s81
	s_lshl_b64 s[22:23], s[62:63], 22
	s_lshl_b64 s[42:43], s[40:41], 12
	s_add_u32 s1, s88, s22
	s_addc_u32 s14, s89, s23
	s_add_u32 s1, s1, s42
	s_addc_u32 s14, s14, s43
	s_lshl_b64 s[22:23], s[82:83], 1
	s_add_u32 s22, s1, s22
	s_addc_u32 s23, s14, s23
	v_lshl_add_u64 v[26:27], s[22:23], 0, v[130:131]
	v_mov_b32_e32 v151, v131
	v_lshl_add_u64 v[26:27], v[26:27], 0, v[150:151]
	v_mov_b32_e32 v149, v131
	v_mov_b32_e32 v22, v131
	v_mov_b32_e32 v23, v131
	v_mov_b32_e32 v24, v131
	v_mov_b32_e32 v25, v131
	v_lshl_add_u64 v[26:27], v[26:27], 0, v[148:149]
	v_mov_b32_dpp v22, v45 row_ror:8 row_mask:0xf bank_mask:0xf
	v_mov_b32_dpp v23, v44 row_ror:8 row_mask:0xf bank_mask:0xf
	v_mov_b32_dpp v24, v43 row_ror:8 row_mask:0xf bank_mask:0xf
	v_mov_b32_dpp v25, v42 row_ror:8 row_mask:0xf bank_mask:0xf
	v_add_co_u32_e32 v28, vcc, 0xa0000, v26
	v_cndmask_b32_e64 v18, v22, v34, s[52:53]
	s_waitcnt lgkmcnt(0)
	v_cndmask_b32_e64 v19, v23, v35, s[52:53]
	v_cndmask_b32_e64 v20, v24, v36, s[52:53]
	v_cndmask_b32_e64 v21, v25, v37, s[52:53]
	v_addc_co_u32_e32 v29, vcc, 0, v27, vcc
	global_store_dwordx4 v[28:29], v[18:21], off
	v_cndmask_b32_e64 v22, v38, v22, s[52:53]
	v_cndmask_b32_e64 v23, v39, v23, s[52:53]
	v_add_co_u32_e32 v18, vcc, 0xa8000, v26
	v_cndmask_b32_e64 v24, v40, v24, s[52:53]
	v_cndmask_b32_e64 v25, v41, v25, s[52:53]
	v_addc_co_u32_e32 v19, vcc, 0, v27, vcc
	global_store_dwordx4 v[18:19], v[22:25], off
.LBB0_1619:
	v_add_u32_e32 v14, v78, v14
	v_add_u32_e32 v15, v79, v15
	v_mul_f32_e32 v22, 0x38018388, v188
	v_cvt_f32_i32_e32 v15, v15
	v_cvt_f32_i32_e32 v14, v14
	v_add_u32_e32 v10, v70, v10
	v_add_u32_e32 v11, v71, v11
	s_waitcnt lgkmcnt(0)
	v_pk_mul_f32 v[18:19], v[66:67], v[22:23] op_sel_hi:[1,0]
	v_pk_mul_f32 v[20:21], v[62:63], v[22:23] op_sel_hi:[1,0]
	v_add_u32_e32 v23, v80, v16
	v_add_u32_e32 v24, v81, v17
	v_cvt_f32_i32_e32 v17, v11
	v_cvt_f32_i32_e32 v16, v10
	v_add_u32_e32 v6, v74, v6
	v_add_u32_e32 v7, v75, v7
	v_pk_mul_f32 v[10:11], v[18:19], v[14:15]
	v_add_u32_e32 v18, v72, v12
	v_add_u32_e32 v19, v73, v13
	v_cvt_f32_i32_e32 v7, v7
	v_cvt_f32_i32_e32 v6, v6
	v_add_u32_e32 v2, v58, v2
	v_add_u32_e32 v3, v59, v3
	v_pk_mul_f32 v[12:13], v[20:21], v[16:17]
	v_cvt_f32_i32_e32 v15, v24
	v_cvt_f32_i32_e32 v14, v23
	v_cvt_f32_i32_e32 v17, v19
	v_cvt_f32_i32_e32 v16, v18
	v_pk_mul_f32 v[18:19], v[68:69], v[22:23] op_sel_hi:[1,0]
	v_pk_mul_f32 v[20:21], v[64:65], v[22:23] op_sel_hi:[1,0]
	v_pk_mul_f32 v[24:25], v[54:55], v[22:23] op_sel_hi:[1,0]
	v_pk_mul_f32 v[26:27], v[50:51], v[22:23] op_sel_hi:[1,0]
	v_add_u32_e32 v23, v76, v8
	v_add_u32_e32 v28, v77, v9
	v_cvt_f32_i32_e32 v9, v3
	v_cvt_f32_i32_e32 v8, v2
	v_pk_mul_f32 v[2:3], v[24:25], v[6:7]
	v_add_u32_e32 v24, v60, v4
	v_add_u32_e32 v25, v61, v5
	v_pk_mul_f32 v[4:5], v[26:27], v[8:9]
	v_cvt_f32_i32_e32 v7, v28
	v_cvt_f32_i32_e32 v6, v23
	v_cvt_f32_i32_e32 v9, v25
	v_cvt_f32_i32_e32 v8, v24
	v_pk_mul_f32 v[24:25], v[56:57], v[22:23] op_sel_hi:[1,0]
	v_pk_mul_f32 v[22:23], v[52:53], v[22:23] op_sel_hi:[1,0]
	v_pk_mul_f32 v[14:15], v[18:19], v[14:15]
	v_pk_mul_f32 v[16:17], v[20:21], v[16:17]
	v_pk_mul_f32 v[6:7], v[24:25], v[6:7]
	v_pk_mul_f32 v[8:9], v[22:23], v[8:9]
	v_cvt_pk_bf16_f32 v18, v10, v11
	v_cvt_pk_bf16_f32 v19, v14, v15
	v_cvt_pk_bf16_f32 v20, v12, v13
	v_cvt_pk_bf16_f32 v21, v16, v17
	v_cvt_pk_bf16_f32 v22, v2, v3
	v_cvt_pk_bf16_f32 v23, v6, v7
	v_cvt_pk_bf16_f32 v24, v4, v5
	v_cvt_pk_bf16_f32 v25, v8, v9
	s_mov_b64 s[42:43], -1
	s_and_b64 vcc, exec, s[56:57]
	v_cndmask_b32_e64 v29, v18, v22, s[52:53]
	v_cndmask_b32_e64 v28, v19, v23, s[52:53]
	v_cndmask_b32_e64 v27, v20, v24, s[52:53]
	v_cndmask_b32_e64 v26, v21, v25, s[52:53]
	s_cbranch_vccnz .LBB0_1623
	v_pk_mul_f32 v[2:3], v[2:3], v[2:3]
	v_pk_mul_f32 v[6:7], v[6:7], v[6:7]
	v_pk_mul_f32 v[4:5], v[4:5], v[4:5]
	v_add_f32_e32 v6, v6, v7
	v_add_f32_e32 v2, v2, v3
	s_ashr_i32 s1, s0, 31
	v_pk_mul_f32 v[8:9], v[8:9], v[8:9]
	v_add_f32_e32 v2, v2, v6
	v_add_f32_e32 v3, v4, v5
	s_lshl_b64 s[0:1], s[0:1], 12
	v_readlane_b32 s14, v249, 28
	v_pk_mul_f32 v[10:11], v[10:11], v[10:11]
	v_pk_mul_f32 v[14:15], v[14:15], v[14:15]
	v_add_f32_e32 v2, v3, v2
	v_add_f32_e32 v3, v8, v9
	s_add_u32 s14, s14, s0
	v_readlane_b32 s0, v253, 5
	v_pk_mul_f32 v[12:13], v[12:13], v[12:13]
	v_add_f32_e32 v2, v3, v2
	v_add_f32_e32 v3, v14, v15
	v_add_f32_e32 v4, v10, v11
	s_addc_u32 s22, s0, s1
	s_lshl_b64 s[0:1], s[82:83], 1
	v_add_f32_e32 v3, v4, v3
	v_add_f32_e32 v4, v12, v13
	s_add_u32 s0, s14, s0
	v_and_b32_e32 v13, 64, v204
	v_pk_mul_f32 v[16:17], v[16:17], v[16:17]
	s_addc_u32 s1, s22, s1
	v_xor_b32_e32 v12, 16, v204
	v_add_u32_e32 v15, 64, v13
	v_add_f32_e32 v3, v4, v3
	v_add_f32_e32 v4, v16, v17
	v_lshl_add_u64 v[10:11], s[0:1], 0, v[130:131]
	v_mov_b32_e32 v151, v131
	v_cmp_lt_i32_e32 vcc, v12, v15
	v_add_f32_e32 v3, v4, v3
	v_lshl_add_u64 v[10:11], v[10:11], 0, v[150:151]
	v_mov_b32_e32 v149, v131
	v_cndmask_b32_e32 v12, v204, v12, vcc
	v_add_f32_e32 v14, v3, v2
	v_mov_b32_e32 v6, v131
	v_mov_b32_e32 v7, v131
	v_mov_b32_e32 v8, v131
	v_mov_b32_e32 v9, v131
	v_lshl_add_u64 v[10:11], v[10:11], 0, v[148:149]
	v_lshlrev_b32_e32 v12, 2, v12
	s_mov_b32 s0, 0xb0000
	v_mov_b32_dpp v6, v29 row_ror:8 row_mask:0xf bank_mask:0xf
	v_mov_b32_dpp v7, v28 row_ror:8 row_mask:0xf bank_mask:0xf
	v_mov_b32_dpp v8, v27 row_ror:8 row_mask:0xf bank_mask:0xf
	v_mov_b32_dpp v9, v26 row_ror:8 row_mask:0xf bank_mask:0xf
	ds_bpermute_b32 v16, v12, v14
	v_add_co_u32_e32 v12, vcc, s0, v10
	v_cndmask_b32_e64 v2, v6, v18, s[52:53]
	v_cndmask_b32_e64 v3, v7, v19, s[52:53]
	v_cndmask_b32_e64 v4, v8, v20, s[52:53]
	v_cndmask_b32_e64 v5, v9, v21, s[52:53]
	v_addc_co_u32_e32 v13, vcc, 0, v11, vcc
	global_store_dwordx4 v[12:13], v[2:5], off
	s_mov_b32 s0, 0xb8000
	v_cndmask_b32_e64 v6, v22, v6, s[52:53]
	v_xor_b32_e32 v3, 32, v204
	v_cmp_lt_i32_e32 vcc, v3, v15
	s_waitcnt lgkmcnt(0)
	v_add_f32_e32 v2, v14, v16
	v_cndmask_b32_e64 v7, v23, v7, s[52:53]
	v_cndmask_b32_e32 v3, v204, v3, vcc
	v_lshlrev_b32_e32 v3, 2, v3
	ds_bpermute_b32 v3, v3, v2
	v_add_co_u32_e32 v4, vcc, s0, v10
	v_cndmask_b32_e64 v8, v24, v8, s[52:53]
	v_cndmask_b32_e64 v9, v25, v9, s[52:53]
	v_addc_co_u32_e32 v5, vcc, 0, v11, vcc
	global_store_dwordx4 v[4:5], v[6:9], off
	s_and_saveexec_b64 s[0:1], s[54:55]
	s_cbranch_execz .LBB0_1622
	v_readlane_b32 s42, v253, 6
	s_waitcnt lgkmcnt(0)
	v_add_f32_e32 v4, v2, v3
	v_lshlrev_b64 v[2:3], 7, v[182:183]
	s_lshl_b32 s22, s21, 2
	v_readlane_b32 s43, v253, 7
	s_ashr_i32 s23, s22, 31
	s_lshl_b32 s80, s38, 2
	v_lshl_add_u64 v[2:3], s[42:43], 0, v[2:3]
	v_lshl_add_u64 v[2:3], s[22:23], 2, v[2:3]
	v_lshl_add_u64 v[2:3], v[2:3], 0, s[80:81]
	v_add_co_u32_e32 v2, vcc, 0x5000, v2
	s_nop 1
	v_addc_co_u32_e32 v3, vcc, 0, v3, vcc
	global_store_dword v[2:3], v4, off offset:2048

; __device__ __forceinline__ unsigned dpp_ror8(unsigned v) { return (unsigned)__builtin_amdgcn_update_dpp(0, (int)v, 0x128, 0xF, 0xF, false); }
; __device__ __forceinline__ void store_pair(bf16_t* grp  , size_t ld, int fr, int fq, u32x4 P0, u32x4 P1) {
;     const bool up = (fr & 8) != 0;
;     u32x4 snd, rcv;
;     snd.x = up ? P0.x : P1.x; snd.y = up ? P0.y : P1.y; snd.z = up ? P0.z : P1.z; snd.w = up ? P0.w : P1.w;
;     rcv.x = dpp_ror8(snd.x); rcv.y = dpp_ror8(snd.y); rcv.z = dpp_ror8(snd.z); rcv.w = dpp_ror8(snd.w);
;     u32x4 dA, dB;
;     dA.x = up ? rcv.x : P0.x; dA.y = up ? rcv.y : P0.y; dA.z = up ? rcv.z : P0.z; dA.w = up ? rcv.w : P0.w;
;     dB.x = up ? P1.x : rcv.x; dB.y = up ? P1.y : rcv.y; dB.z = up ? P1.z : rcv.z; dB.w = up ? P1.w : rcv.w;
;     bf16_t* p = grp + (size_t)(fr & 7) * ld + (up ? CBJ : 0) + 8 * fq;
;     __builtin_nontemporal_store(dA, (u32x4*)p); __builtin_nontemporal_store(dB, (u32x4*)(p + 8 * ld));
;     __device__ __forceinline__ void operator()(f32x4 (&acc)[2][2][4][2], const Unit& u, int wr, int wc, int fr, int fq) const {
;     ...
;                 if (u.ks >= 0) store_pair((bf16_t*)yp + ((size_t)u.ks * MS + (rowg - MP) + ai * HALF + m * 16) * DM + colw, DM, fr, fq, pk[0], pk[1]);
;                 else {
;                     store_pair(Y + (size_t)(rowg + ai * HALF + m * 16) * DM + colw, DM, fr, fq, pk[0], pk[1]);
.LBB0_1624:
	s_mov_b32 s63, s81
	s_lshl_b64 s[0:1], s[62:63], 22
	s_lshl_b64 s[22:23], s[40:41], 12
	s_add_u32 s0, s88, s0
	s_addc_u32 s1, s89, s1
	s_add_u32 s14, s0, s22
	s_addc_u32 s21, s1, s23
	s_lshl_b64 s[0:1], s[82:83], 1
	s_add_u32 s0, s14, s0
	s_addc_u32 s1, s21, s1
	v_lshl_add_u64 v[10:11], s[0:1], 0, v[130:131]
	v_mov_b32_e32 v151, v131
	v_lshl_add_u64 v[10:11], v[10:11], 0, v[150:151]
	v_mov_b32_e32 v149, v131
	v_mov_b32_e32 v6, v131
	v_mov_b32_e32 v7, v131
	v_mov_b32_e32 v8, v131
	v_mov_b32_e32 v9, v131
	v_lshl_add_u64 v[10:11], v[10:11], 0, v[148:149]
	v_mov_b32_dpp v6, v29 row_ror:8 row_mask:0xf bank_mask:0xf
	v_mov_b32_dpp v7, v28 row_ror:8 row_mask:0xf bank_mask:0xf
	v_mov_b32_dpp v8, v27 row_ror:8 row_mask:0xf bank_mask:0xf
	v_mov_b32_dpp v9, v26 row_ror:8 row_mask:0xf bank_mask:0xf
	v_add_co_u32_e32 v12, vcc, 0xb0000, v10
	v_cndmask_b32_e64 v2, v6, v18, s[52:53]
	s_waitcnt lgkmcnt(0)
	v_cndmask_b32_e64 v3, v7, v19, s[52:53]
	v_cndmask_b32_e64 v4, v8, v20, s[52:53]
	v_cndmask_b32_e64 v5, v9, v21, s[52:53]
	v_addc_co_u32_e32 v13, vcc, 0, v11, vcc
	global_store_dwordx4 v[12:13], v[2:5], off
	v_cndmask_b32_e64 v6, v22, v6, s[52:53]
	v_cndmask_b32_e64 v7, v23, v7, s[52:53]
	v_add_co_u32_e32 v2, vcc, 0xb8000, v10
	v_cndmask_b32_e64 v8, v24, v8, s[52:53]
	v_cndmask_b32_e64 v9, v25, v9, s[52:53]
	v_addc_co_u32_e32 v3, vcc, 0, v11, vcc
	global_store_dwordx4 v[2:3], v[6:9], off
